# GEMM MFMA order: accumulator pairs adjacent + Gray walk over fragment pairs (consecutive MFMAs share accumulator or one operand); k-step order alternates per accumulator
# speedup vs baseline: 1.0194x; 1.0104x over previous
; #define PG8_STAGE(bufoff, gbase, voff) do { if constexpr (!pg8_noload<Epi>::value) { _Pragma("unroll") for (int _i = 0; _i < 2; ++_i) \
;         __builtin_amdgcn_global_load_lds((const unsigned*)((const char*)(gbase) + (size_t)_i * pstep + (voff)[0]), (PG8_LAS unsigned*)(lds + (bufoff) + ldsw + _i * 8192), 16, 0, 0); } } while (0)
; #define PG8_LDA(dst, b, h) do { _Pragma("unroll") for (int m = 0; m < 4; ++m) _Pragma("unroll") for (int k = 0; k < 2; ++k) dst[m][k] = *(const PG8_LAS bf16x8*)(lds + PG8_SA(b, h) + aoff + m * 2048 + k * 1024); } while (0)
; #define PG8_LDB(dst, b, h) do { _Pragma("unroll") for (int n = 0; n < 2; ++n) _Pragma("unroll") for (int k = 0; k < 2; ++k) dst[n][k] = *(const PG8_LAS bf16x8*)(lds + PG8_SB(b, h) + boff + n * 2048 + k * 1024); } while (0)
; #define PG8_MMA(ai, bj, At, Bt) do { __builtin_amdgcn_s_setprio(1); _Pragma("unroll") for (int m = 0; m < 4; ++m) _Pragma("unroll") for (int n = 0; n < 2; ++n) _Pragma("unroll") for (int k = 0; k < 2; ++k) \
;         acc[ai][bj][m][n] = __builtin_amdgcn_mfma_f32_16x16x32_bf16(Bt[n][k], At[m][k], acc[ai][bj][m][n], 0, 0, 0); __builtin_amdgcn_s_setprio(0); } while (0)
; #define PG8_BAR __builtin_amdgcn_s_barrier()
; template <class Epi, class Sched, bool ALIGN_EPI = false, bool SP2 = false, bool ABLK = false>
; __device__ __forceinline__ void gemm_phase(PG8_LAS unsigned char* lds, const Gemm g, const Sched& S, const Epi& E) {
;     ...
;         for (int t = 0; t < nt; t += 2) {
;             const bool last = (t == nt - 2);
;             const char* a1 = cA + (size_t)(t + 1) * kstep;
;             const char* a2 = last ? nA : cA + (size_t)(t + 2) * kstep; const char* b2 = last ? nB : cB + (size_t)(t + 2) * kstepB;
;             const char* a3 = a2 + kstep; const char* b3 = b2 + kstepB;
;             if (last && has_next) S.a_ready(nxt);
;             if constexpr (SP2) {
;             PG8_LDB(B0, 0, 0); PG8_LDB(B1, 0, 1); PG8_SCHED; PG8_LDA(At, 0, 0); PG8_STAGE(PG8_SA(1, 1), a1 + hstep, voffA);
;             PG8_WAIT_V(8); PG8_WAIT_L(0); PG8_BAR; PG8_MMA(0, 0, At, B0); PG8_MMA(0, 1, At, B1); PG8_BAR; PG8_SCHED;
;             PG8_LDA(At, 0, 1); PG8_STAGE(PG8_SB(0, 0), b2, voffB); PG8_STAGE(PG8_SB(0, 1), b2 + hstep, voffB); PG8_STAGE(PG8_SA(0, 0), a2, voffA);
;             PG8_WAIT_V(8); PG8_WAIT_L(0); PG8_BAR; PG8_MMA(1, 0, At, B0); PG8_MMA(1, 1, At, B1); PG8_BAR; PG8_SCHED;
.LBB0_114:
	ds_read_b128 v[144:147], v168
	ds_read_b128 v[184:187], v168 offset:1024
	ds_read_b128 v[188:191], v168 offset:2048
	ds_read_b128 v[192:195], v168 offset:3072
	ds_read_b128 v[196:199], v169
	ds_read_b128 v[200:203], v169 offset:1024
	ds_read_b128 v[204:207], v169 offset:2048
	ds_read_b128 v[208:211], v169 offset:3072
	s_add_u32 s71, vcc_lo, 0xfff80800
	s_addc_u32 s73, vcc_hi, -1
	s_cmp_eq_u32 s70, 28
	s_cselect_b32 s75, s3, s73
	s_cselect_b32 s74, s7, s71
	s_cselect_b32 s77, s21, s17
	s_cselect_b32 s76, s72, s16
	v_lshl_add_u64 v[244:245], vcc, 0, v[136:137]
	s_add_i32 m0, s53, 0xc000
	ds_read_b128 v[212:215], v170
	ds_read_b128 v[216:219], v170 offset:1024
	ds_read_b128 v[220:223], v170 offset:2048
	ds_read_b128 v[224:227], v170 offset:3072
	ds_read_b128 v[228:231], v170 offset:4096
	ds_read_b128 v[232:235], v170 offset:5120
	ds_read_b128 v[236:239], v170 offset:6144
	ds_read_b128 v[240:243], v170 offset:7168
	global_load_lds_dwordx4 v[244:245], off
	v_lshl_add_u64 v[244:245], v[244:245], 0, s[0:1]
	s_add_i32 m0, s53, 0xe000
	s_nop 0
	global_load_lds_dwordx4 v[244:245], off
	s_waitcnt vmcnt(8)
	s_waitcnt lgkmcnt(0)
	s_barrier
	s_setprio 1
	s_waitcnt lgkmcnt(0)
	v_mfma_f32_16x16x32_bf16 v[126:129], v[144:147], v[212:215], v[126:129]
	v_mfma_f32_16x16x32_bf16 v[126:129], v[184:187], v[216:219], v[126:129]
	v_mfma_f32_16x16x32_bf16 v[122:125], v[192:195], v[216:219], v[122:125]
	v_mfma_f32_16x16x32_bf16 v[122:125], v[188:191], v[212:215], v[122:125]
	v_mfma_f32_16x16x32_bf16 v[106:109], v[188:191], v[220:223], v[106:109]
	v_mfma_f32_16x16x32_bf16 v[106:109], v[192:195], v[224:227], v[106:109]
	v_mfma_f32_16x16x32_bf16 v[110:113], v[184:187], v[224:227], v[110:113]
	v_mfma_f32_16x16x32_bf16 v[110:113], v[144:147], v[220:223], v[110:113]
	v_mfma_f32_16x16x32_bf16 v[94:97], v[144:147], v[228:231], v[94:97]
	v_mfma_f32_16x16x32_bf16 v[94:97], v[184:187], v[232:235], v[94:97]
	v_mfma_f32_16x16x32_bf16 v[90:93], v[192:195], v[232:235], v[90:93]
	v_mfma_f32_16x16x32_bf16 v[90:93], v[188:191], v[228:231], v[90:93]
	v_mfma_f32_16x16x32_bf16 v[74:77], v[188:191], v[236:239], v[74:77]
	v_mfma_f32_16x16x32_bf16 v[74:77], v[192:195], v[240:243], v[74:77]
	v_mfma_f32_16x16x32_bf16 v[78:81], v[184:187], v[240:243], v[78:81]
	v_mfma_f32_16x16x32_bf16 v[78:81], v[144:147], v[236:239], v[78:81]
	v_mfma_f32_16x16x32_bf16 v[118:121], v[196:199], v[212:215], v[118:121]
	v_mfma_f32_16x16x32_bf16 v[118:121], v[200:203], v[216:219], v[118:121]
	v_mfma_f32_16x16x32_bf16 v[114:117], v[208:211], v[216:219], v[114:117]
	v_mfma_f32_16x16x32_bf16 v[114:117], v[204:207], v[212:215], v[114:117]
	v_mfma_f32_16x16x32_bf16 v[98:101], v[204:207], v[220:223], v[98:101]
	v_mfma_f32_16x16x32_bf16 v[98:101], v[208:211], v[224:227], v[98:101]
	v_mfma_f32_16x16x32_bf16 v[102:105], v[200:203], v[224:227], v[102:105]
	v_mfma_f32_16x16x32_bf16 v[102:105], v[196:199], v[220:223], v[102:105]
	v_mfma_f32_16x16x32_bf16 v[86:89], v[196:199], v[228:231], v[86:89]
	v_mfma_f32_16x16x32_bf16 v[86:89], v[200:203], v[232:235], v[86:89]
	v_mfma_f32_16x16x32_bf16 v[82:85], v[208:211], v[232:235], v[82:85]
	v_mfma_f32_16x16x32_bf16 v[82:85], v[204:207], v[228:231], v[82:85]
	s_barrier
	s_setprio 2
	v_mfma_f32_16x16x32_bf16 v[66:69], v[204:207], v[236:239], v[66:69]
	v_mfma_f32_16x16x32_bf16 v[66:69], v[208:211], v[240:243], v[66:69]
	v_mfma_f32_16x16x32_bf16 v[70:73], v[200:203], v[240:243], v[70:73]
	v_mfma_f32_16x16x32_bf16 v[70:73], v[196:199], v[236:239], v[70:73]
	s_setprio 0
	s_add_i32 s71, s64, s52
	v_lshl_add_u64 v[244:245], s[76:77], 0, v[130:131]
	s_mov_b32 m0, s71
	ds_read_b128 v[212:215], v170 offset:16384
	ds_read_b128 v[216:219], v170 offset:17408
	ds_read_b128 v[220:223], v170 offset:18432
	ds_read_b128 v[224:227], v170 offset:19456
	ds_read_b128 v[228:231], v170 offset:20480
	ds_read_b128 v[232:235], v170 offset:21504
	ds_read_b128 v[236:239], v170 offset:22528
	ds_read_b128 v[240:243], v170 offset:23552
	global_load_lds_dwordx4 v[244:245], off
	v_lshl_add_u64 v[246:247], v[244:245], 0, s[0:1]
	s_add_i32 m0, s71, 0x2000
	s_add_i32 s71, s65, s52
	global_load_lds_dwordx4 v[246:247], off
	v_lshl_add_u64 v[246:247], v[244:245], 0, s[14:15]
	s_mov_b32 m0, s71
	s_nop 0
	global_load_lds_dwordx4 v[246:247], off
	v_lshl_add_u64 v[246:247], v[244:245], 0, s[18:19]
	s_add_i32 m0, s71, 0x2000
	s_nop 0
	global_load_lds_dwordx4 v[246:247], off
	v_lshl_add_u64 v[246:247], s[74:75], 0, v[130:131]
	s_mov_b32 m0, s53
	v_lshl_add_u64 v[248:249], v[246:247], 0, s[0:1]
	global_load_lds_dwordx4 v[246:247], off
	s_mov_b32 m0, s54
	s_nop 0
	global_load_lds_dwordx4 v[248:249], off
	s_waitcnt vmcnt(8)
	s_waitcnt lgkmcnt(0)
	s_barrier
; #define PG8_STAGE(bufoff, gbase, voff) do { if constexpr (!pg8_noload<Epi>::value) { _Pragma("unroll") for (int _i = 0; _i < 2; ++_i) \
;         __builtin_amdgcn_global_load_lds((const unsigned*)((const char*)(gbase) + (size_t)_i * pstep + (voff)[0]), (PG8_LAS unsigned*)(lds + (bufoff) + ldsw + _i * 8192), 16, 0, 0); } } while (0)
; #define PG8_LDA(dst, b, h) do { _Pragma("unroll") for (int m = 0; m < 4; ++m) _Pragma("unroll") for (int k = 0; k < 2; ++k) dst[m][k] = *(const PG8_LAS bf16x8*)(lds + PG8_SA(b, h) + aoff + m * 2048 + k * 1024); } while (0)
; #define PG8_LDB(dst, b, h) do { _Pragma("unroll") for (int n = 0; n < 2; ++n) _Pragma("unroll") for (int k = 0; k < 2; ++k) dst[n][k] = *(const PG8_LAS bf16x8*)(lds + PG8_SB(b, h) + boff + n * 2048 + k * 1024); } while (0)
; #define PG8_MMA(ai, bj, At, Bt) do { __builtin_amdgcn_s_setprio(1); _Pragma("unroll") for (int m = 0; m < 4; ++m) _Pragma("unroll") for (int n = 0; n < 2; ++n) _Pragma("unroll") for (int k = 0; k < 2; ++k) \
;         acc[ai][bj][m][n] = __builtin_amdgcn_mfma_f32_16x16x32_bf16(Bt[n][k], At[m][k], acc[ai][bj][m][n], 0, 0, 0); __builtin_amdgcn_s_setprio(0); } while (0)
; #define PG8_WAIT_V(n) asm volatile("s_waitcnt vmcnt(" #n ")" ::: "memory")
; #define PG8_WAIT_L(n) asm volatile("s_waitcnt lgkmcnt(" #n ")" ::: "memory")
; #define PG8_BAR __builtin_amdgcn_s_barrier()
; #define PG8_SCHED __builtin_amdgcn_sched_barrier(0)
; template <class Epi, class Sched, bool ALIGN_EPI = false, bool SP2 = false, bool ABLK = false>
; __device__ __forceinline__ void gemm_phase(PG8_LAS unsigned char* lds, const Gemm g, const Sched& S, const Epi& E) {
;     ...
;             PG8_WAIT_V(8); PG8_WAIT_L(0); PG8_BAR; PG8_MMA(1, 0, At, B0); PG8_MMA(1, 1, At, B1); PG8_BAR; PG8_SCHED;
;             PG8_LDB(B0, 1, 0); PG8_LDB(B1, 1, 1); PG8_SCHED; PG8_LDA(At, 1, 0); PG8_STAGE(PG8_SA(0, 1), a2 + hstep, voffA);
;             PG8_WAIT_V(8); PG8_WAIT_L(0); PG8_BAR; PG8_MMA(0, 0, At, B0); PG8_MMA(0, 1, At, B1); PG8_BAR; PG8_SCHED;
	s_setprio 1
	s_waitcnt lgkmcnt(0)
	v_mfma_f32_16x16x32_bf16 v[62:65], v[144:147], v[212:215], v[62:65]
	v_mfma_f32_16x16x32_bf16 v[62:65], v[184:187], v[216:219], v[62:65]
	v_mfma_f32_16x16x32_bf16 v[58:61], v[192:195], v[216:219], v[58:61]
	v_mfma_f32_16x16x32_bf16 v[58:61], v[188:191], v[212:215], v[58:61]
	v_mfma_f32_16x16x32_bf16 v[42:45], v[188:191], v[220:223], v[42:45]
	v_mfma_f32_16x16x32_bf16 v[42:45], v[192:195], v[224:227], v[42:45]
	v_mfma_f32_16x16x32_bf16 v[46:49], v[184:187], v[224:227], v[46:49]
	v_mfma_f32_16x16x32_bf16 v[46:49], v[144:147], v[220:223], v[46:49]
	v_mfma_f32_16x16x32_bf16 v[30:33], v[144:147], v[228:231], v[30:33]
	v_mfma_f32_16x16x32_bf16 v[30:33], v[184:187], v[232:235], v[30:33]
	v_mfma_f32_16x16x32_bf16 v[26:29], v[192:195], v[232:235], v[26:29]
	v_mfma_f32_16x16x32_bf16 v[26:29], v[188:191], v[228:231], v[26:29]
	v_mfma_f32_16x16x32_bf16 v[10:13], v[188:191], v[236:239], v[10:13]
	v_mfma_f32_16x16x32_bf16 v[10:13], v[192:195], v[240:243], v[10:13]
	v_mfma_f32_16x16x32_bf16 v[14:17], v[184:187], v[240:243], v[14:17]
	v_mfma_f32_16x16x32_bf16 v[14:17], v[144:147], v[236:239], v[14:17]
	v_mfma_f32_16x16x32_bf16 v[54:57], v[196:199], v[212:215], v[54:57]
	v_mfma_f32_16x16x32_bf16 v[54:57], v[200:203], v[216:219], v[54:57]
	v_mfma_f32_16x16x32_bf16 v[50:53], v[208:211], v[216:219], v[50:53]
	v_mfma_f32_16x16x32_bf16 v[50:53], v[204:207], v[212:215], v[50:53]
	v_mfma_f32_16x16x32_bf16 v[34:37], v[204:207], v[220:223], v[34:37]
	v_mfma_f32_16x16x32_bf16 v[34:37], v[208:211], v[224:227], v[34:37]
	v_mfma_f32_16x16x32_bf16 v[38:41], v[200:203], v[224:227], v[38:41]
	v_mfma_f32_16x16x32_bf16 v[38:41], v[196:199], v[220:223], v[38:41]
	v_mfma_f32_16x16x32_bf16 v[22:25], v[196:199], v[228:231], v[22:25]
	v_mfma_f32_16x16x32_bf16 v[22:25], v[200:203], v[232:235], v[22:25]
	v_mfma_f32_16x16x32_bf16 v[18:21], v[208:211], v[232:235], v[18:21]
	v_mfma_f32_16x16x32_bf16 v[18:21], v[204:207], v[228:231], v[18:21]
	s_barrier
	s_setprio 2
	v_mfma_f32_16x16x32_bf16 v[2:5], v[204:207], v[236:239], v[2:5]
	v_mfma_f32_16x16x32_bf16 v[2:5], v[208:211], v[240:243], v[2:5]
	v_mfma_f32_16x16x32_bf16 v[6:9], v[200:203], v[240:243], v[6:9]
	v_mfma_f32_16x16x32_bf16 v[6:9], v[196:199], v[236:239], v[6:9]
	s_setprio 0
	s_add_i32 s71, 0, 0x18000
	v_add_u32_e32 v133, s71, v149
	s_add_i32 s73, 0, 0x1c000
	ds_read_b128 v[144:147], v133
	ds_read_b128 v[184:187], v133 offset:1024
	ds_read_b128 v[188:191], v133 offset:2048
	ds_read_b128 v[192:195], v133 offset:3072
	v_add_u32_e32 v133, s73, v149
	ds_read_b128 v[196:199], v133
	ds_read_b128 v[200:203], v133 offset:1024
	ds_read_b128 v[204:207], v133 offset:2048
	ds_read_b128 v[208:211], v133 offset:3072
	s_mov_b32 m0, s55
	v_lshl_add_u64 v[248:249], v[246:247], 0, s[14:15]
	ds_read_b128 v[212:215], v170 offset:32768
	ds_read_b128 v[216:219], v170 offset:33792
	ds_read_b128 v[220:223], v170 offset:34816
	ds_read_b128 v[224:227], v170 offset:35840
	ds_read_b128 v[228:231], v170 offset:36864
	ds_read_b128 v[232:235], v170 offset:37888
	ds_read_b128 v[236:239], v170 offset:38912
	ds_read_b128 v[240:243], v170 offset:39936
	global_load_lds_dwordx4 v[248:249], off
	v_lshl_add_u64 v[248:249], v[246:247], 0, s[18:19]
	s_mov_b32 m0, s56
	s_nop 0
	global_load_lds_dwordx4 v[248:249], off
	s_waitcnt vmcnt(8)
	s_waitcnt lgkmcnt(0)
	s_barrier
	s_setprio 1
	s_waitcnt lgkmcnt(0)
	v_mfma_f32_16x16x32_bf16 v[126:129], v[144:147], v[212:215], v[126:129]
	v_mfma_f32_16x16x32_bf16 v[126:129], v[184:187], v[216:219], v[126:129]
	v_mfma_f32_16x16x32_bf16 v[122:125], v[192:195], v[216:219], v[122:125]
	v_mfma_f32_16x16x32_bf16 v[122:125], v[188:191], v[212:215], v[122:125]
	v_mfma_f32_16x16x32_bf16 v[106:109], v[188:191], v[220:223], v[106:109]
	v_mfma_f32_16x16x32_bf16 v[106:109], v[192:195], v[224:227], v[106:109]
	v_mfma_f32_16x16x32_bf16 v[110:113], v[184:187], v[224:227], v[110:113]
	v_mfma_f32_16x16x32_bf16 v[110:113], v[144:147], v[220:223], v[110:113]
	v_mfma_f32_16x16x32_bf16 v[94:97], v[144:147], v[228:231], v[94:97]
	v_mfma_f32_16x16x32_bf16 v[94:97], v[184:187], v[232:235], v[94:97]
	v_mfma_f32_16x16x32_bf16 v[90:93], v[192:195], v[232:235], v[90:93]
	v_mfma_f32_16x16x32_bf16 v[90:93], v[188:191], v[228:231], v[90:93]
	v_mfma_f32_16x16x32_bf16 v[74:77], v[188:191], v[236:239], v[74:77]
	v_mfma_f32_16x16x32_bf16 v[74:77], v[192:195], v[240:243], v[74:77]
	v_mfma_f32_16x16x32_bf16 v[78:81], v[184:187], v[240:243], v[78:81]
	v_mfma_f32_16x16x32_bf16 v[78:81], v[144:147], v[236:239], v[78:81]
	v_mfma_f32_16x16x32_bf16 v[118:121], v[196:199], v[212:215], v[118:121]
	v_mfma_f32_16x16x32_bf16 v[118:121], v[200:203], v[216:219], v[118:121]
	v_mfma_f32_16x16x32_bf16 v[114:117], v[208:211], v[216:219], v[114:117]
	v_mfma_f32_16x16x32_bf16 v[114:117], v[204:207], v[212:215], v[114:117]
	v_mfma_f32_16x16x32_bf16 v[98:101], v[204:207], v[220:223], v[98:101]
	v_mfma_f32_16x16x32_bf16 v[98:101], v[208:211], v[224:227], v[98:101]
	v_mfma_f32_16x16x32_bf16 v[102:105], v[200:203], v[224:227], v[102:105]
	v_mfma_f32_16x16x32_bf16 v[102:105], v[196:199], v[220:223], v[102:105]
	v_mfma_f32_16x16x32_bf16 v[86:89], v[196:199], v[228:231], v[86:89]
	v_mfma_f32_16x16x32_bf16 v[86:89], v[200:203], v[232:235], v[86:89]
	v_mfma_f32_16x16x32_bf16 v[82:85], v[208:211], v[232:235], v[82:85]
	v_mfma_f32_16x16x32_bf16 v[82:85], v[204:207], v[228:231], v[82:85]
	s_barrier
; #define PG8_STAGE(bufoff, gbase, voff) do { if constexpr (!pg8_noload<Epi>::value) { _Pragma("unroll") for (int _i = 0; _i < 2; ++_i) \
;         __builtin_amdgcn_global_load_lds((const unsigned*)((const char*)(gbase) + (size_t)_i * pstep + (voff)[0]), (PG8_LAS unsigned*)(lds + (bufoff) + ldsw + _i * 8192), 16, 0, 0); } } while (0)
; #define PG8_LDA(dst, b, h) do { _Pragma("unroll") for (int m = 0; m < 4; ++m) _Pragma("unroll") for (int k = 0; k < 2; ++k) dst[m][k] = *(const PG8_LAS bf16x8*)(lds + PG8_SA(b, h) + aoff + m * 2048 + k * 1024); } while (0)
; #define PG8_MMA(ai, bj, At, Bt) do { __builtin_amdgcn_s_setprio(1); _Pragma("unroll") for (int m = 0; m < 4; ++m) _Pragma("unroll") for (int n = 0; n < 2; ++n) _Pragma("unroll") for (int k = 0; k < 2; ++k) \
;         acc[ai][bj][m][n] = __builtin_amdgcn_mfma_f32_16x16x32_bf16(Bt[n][k], At[m][k], acc[ai][bj][m][n], 0, 0, 0); __builtin_amdgcn_s_setprio(0); } while (0)
; #define PG8_WAIT_V(n) asm volatile("s_waitcnt vmcnt(" #n ")" ::: "memory")
; #define PG8_WAIT_L(n) asm volatile("s_waitcnt lgkmcnt(" #n ")" ::: "memory")
; #define PG8_BAR __builtin_amdgcn_s_barrier()
; #define PG8_SCHED __builtin_amdgcn_sched_barrier(0)
; template <class Epi, class Sched, bool ALIGN_EPI = false, bool SP2 = false, bool ABLK = false>
; __device__ __forceinline__ void gemm_phase(PG8_LAS unsigned char* lds, const Gemm g, const Sched& S, const Epi& E) {
;     ...
;             PG8_LDA(At, 1, 1); PG8_STAGE(PG8_SB(1, 0), b3, voffB); PG8_STAGE(PG8_SB(1, 1), b3 + hstep, voffB); PG8_STAGE(PG8_SA(1, 0), a3, voffA);
;             PG8_WAIT_V(8); PG8_WAIT_L(0); PG8_BAR; PG8_MMA(1, 0, At, B0); PG8_MMA(1, 1, At, B1); PG8_BAR; PG8_SCHED;
;     ...
;         if constexpr (ALIGN_EPI) { if (wr == 0) PG8_BAR; }
	s_setprio 2
	v_mfma_f32_16x16x32_bf16 v[66:69], v[204:207], v[236:239], v[66:69]
	v_mfma_f32_16x16x32_bf16 v[66:69], v[208:211], v[240:243], v[66:69]
	v_mfma_f32_16x16x32_bf16 v[70:73], v[200:203], v[240:243], v[70:73]
	v_mfma_f32_16x16x32_bf16 v[70:73], v[196:199], v[236:239], v[70:73]
	s_setprio 0
	s_add_i32 s71, s71, s52
	v_lshl_add_u64 v[248:249], v[244:245], 0, s[28:29]
	s_mov_b32 m0, s71
	ds_read_b128 v[212:215], v170 offset:49152
	ds_read_b128 v[216:219], v170 offset:50176
	ds_read_b128 v[220:223], v170 offset:51200
	ds_read_b128 v[224:227], v170 offset:52224
	ds_read_b128 v[228:231], v170 offset:53248
	ds_read_b128 v[232:235], v170 offset:54272
	ds_read_b128 v[236:239], v170 offset:55296
	ds_read_b128 v[240:243], v170 offset:56320
	global_load_lds_dwordx4 v[248:249], off
	v_lshl_add_u64 v[248:249], v[244:245], 0, s[30:31]
	s_add_i32 m0, s71, 0x2000
	s_add_i32 s71, s73, s52
	global_load_lds_dwordx4 v[248:249], off
	v_lshl_add_u64 v[248:249], v[244:245], 0, s[34:35]
	s_mov_b32 m0, s71
	v_lshl_add_u64 v[244:245], v[244:245], 0, s[36:37]
	global_load_lds_dwordx4 v[248:249], off
	s_add_i32 m0, s71, 0x2000
	s_nop 0
	global_load_lds_dwordx4 v[244:245], off
	v_lshl_add_u64 v[244:245], v[246:247], 0, s[28:29]
	s_mov_b32 m0, s59
	s_nop 0
	global_load_lds_dwordx4 v[244:245], off
	v_lshl_add_u64 v[244:245], v[246:247], 0, s[30:31]
	s_mov_b32 m0, s60
	s_nop 0
	global_load_lds_dwordx4 v[244:245], off
	s_waitcnt vmcnt(8)
	s_waitcnt lgkmcnt(0)
	s_barrier
	s_setprio 1
	s_waitcnt lgkmcnt(0)
	v_mfma_f32_16x16x32_bf16 v[62:65], v[144:147], v[212:215], v[62:65]
	v_mfma_f32_16x16x32_bf16 v[62:65], v[184:187], v[216:219], v[62:65]
	v_mfma_f32_16x16x32_bf16 v[58:61], v[192:195], v[216:219], v[58:61]
	v_mfma_f32_16x16x32_bf16 v[58:61], v[188:191], v[212:215], v[58:61]
	v_mfma_f32_16x16x32_bf16 v[42:45], v[188:191], v[220:223], v[42:45]
	v_mfma_f32_16x16x32_bf16 v[42:45], v[192:195], v[224:227], v[42:45]
	v_mfma_f32_16x16x32_bf16 v[46:49], v[184:187], v[224:227], v[46:49]
	v_mfma_f32_16x16x32_bf16 v[46:49], v[144:147], v[220:223], v[46:49]
	v_mfma_f32_16x16x32_bf16 v[30:33], v[144:147], v[228:231], v[30:33]
	v_mfma_f32_16x16x32_bf16 v[30:33], v[184:187], v[232:235], v[30:33]
	v_mfma_f32_16x16x32_bf16 v[26:29], v[192:195], v[232:235], v[26:29]
	v_mfma_f32_16x16x32_bf16 v[26:29], v[188:191], v[228:231], v[26:29]
	v_mfma_f32_16x16x32_bf16 v[10:13], v[188:191], v[236:239], v[10:13]
	v_mfma_f32_16x16x32_bf16 v[10:13], v[192:195], v[240:243], v[10:13]
	v_mfma_f32_16x16x32_bf16 v[14:17], v[184:187], v[240:243], v[14:17]
	v_mfma_f32_16x16x32_bf16 v[14:17], v[144:147], v[236:239], v[14:17]
	v_mfma_f32_16x16x32_bf16 v[54:57], v[196:199], v[212:215], v[54:57]
	v_mfma_f32_16x16x32_bf16 v[54:57], v[200:203], v[216:219], v[54:57]
	v_mfma_f32_16x16x32_bf16 v[50:53], v[208:211], v[216:219], v[50:53]
	v_mfma_f32_16x16x32_bf16 v[50:53], v[204:207], v[212:215], v[50:53]
	v_mfma_f32_16x16x32_bf16 v[34:37], v[204:207], v[220:223], v[34:37]
	v_mfma_f32_16x16x32_bf16 v[34:37], v[208:211], v[224:227], v[34:37]
	v_mfma_f32_16x16x32_bf16 v[38:41], v[200:203], v[224:227], v[38:41]
	v_mfma_f32_16x16x32_bf16 v[38:41], v[196:199], v[220:223], v[38:41]
	v_mfma_f32_16x16x32_bf16 v[22:25], v[196:199], v[228:231], v[22:25]
	v_mfma_f32_16x16x32_bf16 v[22:25], v[200:203], v[232:235], v[22:25]
	v_mfma_f32_16x16x32_bf16 v[18:21], v[208:211], v[232:235], v[18:21]
	v_mfma_f32_16x16x32_bf16 v[18:21], v[204:207], v[228:231], v[18:21]
	s_barrier
	s_setprio 2
	v_mfma_f32_16x16x32_bf16 v[2:5], v[204:207], v[236:239], v[2:5]
	v_mfma_f32_16x16x32_bf16 v[2:5], v[208:211], v[240:243], v[2:5]
	v_mfma_f32_16x16x32_bf16 v[6:9], v[200:203], v[240:243], v[6:9]
	v_mfma_f32_16x16x32_bf16 v[6:9], v[196:199], v[236:239], v[6:9]
	s_setprio 0
	s_add_i32 s70, s70, 2
	s_add_u32 vcc_lo, vcc_lo, 0x1000
	s_addc_u32 vcc_hi, vcc_hi, 0
	s_add_u32 s16, s16, 0x1000
	s_addc_u32 s17, s17, 0
	s_cmp_gt_u32 s70, 29
	s_cbranch_scc0 .LBB0_114
	s_and_b64 vcc, exec, s[38:39]
	s_cbranch_vccz .LBB0_117
	s_barrier

; #define PG8_STAGE(bufoff, gbase, voff) do { if constexpr (!pg8_noload<Epi>::value) { _Pragma("unroll") for (int _i = 0; _i < 2; ++_i) \
;         __builtin_amdgcn_global_load_lds((const unsigned*)((const char*)(gbase) + (size_t)_i * pstep + (voff)[0]), (PG8_LAS unsigned*)(lds + (bufoff) + ldsw + _i * 8192), 16, 0, 0); } } while (0)
; #define PG8_LDA(dst, b, h) do { _Pragma("unroll") for (int m = 0; m < 4; ++m) _Pragma("unroll") for (int k = 0; k < 2; ++k) dst[m][k] = *(const PG8_LAS bf16x8*)(lds + PG8_SA(b, h) + aoff + m * 2048 + k * 1024); } while (0)
; #define PG8_LDB(dst, b, h) do { _Pragma("unroll") for (int n = 0; n < 2; ++n) _Pragma("unroll") for (int k = 0; k < 2; ++k) dst[n][k] = *(const PG8_LAS bf16x8*)(lds + PG8_SB(b, h) + boff + n * 2048 + k * 1024); } while (0)
; #define PG8_MMA(ai, bj, At, Bt) do { __builtin_amdgcn_s_setprio(1); _Pragma("unroll") for (int m = 0; m < 4; ++m) _Pragma("unroll") for (int n = 0; n < 2; ++n) _Pragma("unroll") for (int k = 0; k < 2; ++k) \
;         acc[ai][bj][m][n] = __builtin_amdgcn_mfma_f32_16x16x32_bf16(Bt[n][k], At[m][k], acc[ai][bj][m][n], 0, 0, 0); __builtin_amdgcn_s_setprio(0); } while (0)
; #define PG8_BAR __builtin_amdgcn_s_barrier()
; template <class Epi, class Sched, bool ALIGN_EPI = false, bool SP2 = false, bool ABLK = false>
; __device__ __forceinline__ void gemm_phase(PG8_LAS unsigned char* lds, const Gemm g, const Sched& S, const Epi& E) {
;     ...
;         for (int t = 0; t < nt; t += 2) {
;             const bool last = (t == nt - 2);
;             const char* a1 = cA + (size_t)(t + 1) * kstep;
;             const char* a2 = last ? nA : cA + (size_t)(t + 2) * kstep; const char* b2 = last ? nB : cB + (size_t)(t + 2) * kstepB;
;             const char* a3 = a2 + kstep; const char* b3 = b2 + kstepB;
;             if (last && has_next) S.a_ready(nxt);
;             if constexpr (SP2) {
;             PG8_LDB(B0, 0, 0); PG8_LDB(B1, 0, 1); PG8_SCHED; PG8_LDA(At, 0, 0); PG8_STAGE(PG8_SA(1, 1), a1 + hstep, voffA);
;             PG8_WAIT_V(8); PG8_WAIT_L(0); PG8_BAR; PG8_MMA(0, 0, At, B0); PG8_MMA(0, 1, At, B1); PG8_BAR; PG8_SCHED;
;             PG8_LDA(At, 0, 1); PG8_STAGE(PG8_SB(0, 0), b2, voffB); PG8_STAGE(PG8_SB(0, 1), b2 + hstep, voffB); PG8_STAGE(PG8_SA(0, 0), a2, voffA);
;             PG8_WAIT_V(8); PG8_WAIT_L(0); PG8_BAR; PG8_MMA(1, 0, At, B0); PG8_MMA(1, 1, At, B1); PG8_BAR; PG8_SCHED;
.LBB0_487:
	ds_read_b128 v[114:117], v167
	ds_read_b128 v[126:129], v167 offset:1024
	ds_read_b128 v[130:133], v167 offset:2048
	ds_read_b128 v[142:145], v167 offset:3072
	ds_read_b128 v[146:149], v168
	ds_read_b128 v[150:153], v168 offset:1024
	ds_read_b128 v[174:177], v168 offset:2048
	ds_read_b128 v[178:181], v168 offset:3072
	s_add_i32 s65, s39, 2
	s_add_u32 s68, s92, 0xfff00800
	s_addc_u32 s69, s93, -1
	s_cmp_eq_u32 s3, s39
	s_cselect_b32 s69, s79, s69
	s_cselect_b32 s68, s78, s68
	s_cselect_b32 s71, s89, s37
	s_cselect_b32 s70, s88, s11
	v_lshl_add_u64 v[162:163], s[92:93], 0, v[158:159]
	s_add_i32 m0, s56, 0xc000
	ds_read_b128 v[184:187], v169
	ds_read_b128 v[188:191], v169 offset:1024
	ds_read_b128 v[192:195], v169 offset:2048
	ds_read_b128 v[196:199], v169 offset:3072
	ds_read_b128 v[200:203], v169 offset:4096
	ds_read_b128 v[204:207], v169 offset:5120
	ds_read_b128 v[208:211], v169 offset:6144
	ds_read_b128 v[212:215], v169 offset:7168
	global_load_lds_dwordx4 v[162:163], off
	v_lshl_add_u64 v[162:163], v[162:163], 0, s[12:13]
	s_add_i32 m0, s56, 0xe000
	s_nop 0
	global_load_lds_dwordx4 v[162:163], off
	s_waitcnt vmcnt(8)
	s_waitcnt lgkmcnt(0)
	s_barrier
	s_setprio 1
	s_waitcnt lgkmcnt(0)
	v_mfma_f32_16x16x32_bf16 v[138:141], v[114:117], v[184:187], v[138:141]
	v_mfma_f32_16x16x32_bf16 v[138:141], v[126:129], v[188:191], v[138:141]
	v_mfma_f32_16x16x32_bf16 v[134:137], v[142:145], v[188:191], v[134:137]
	v_mfma_f32_16x16x32_bf16 v[134:137], v[130:133], v[184:187], v[134:137]
	v_mfma_f32_16x16x32_bf16 v[106:109], v[130:133], v[192:195], v[106:109]
	v_mfma_f32_16x16x32_bf16 v[106:109], v[142:145], v[196:199], v[106:109]
	v_mfma_f32_16x16x32_bf16 v[110:113], v[126:129], v[196:199], v[110:113]
	v_mfma_f32_16x16x32_bf16 v[110:113], v[114:117], v[192:195], v[110:113]
	v_mfma_f32_16x16x32_bf16 v[94:97], v[114:117], v[200:203], v[94:97]
	v_mfma_f32_16x16x32_bf16 v[94:97], v[126:129], v[204:207], v[94:97]
	v_mfma_f32_16x16x32_bf16 v[90:93], v[142:145], v[204:207], v[90:93]
	v_mfma_f32_16x16x32_bf16 v[90:93], v[130:133], v[200:203], v[90:93]
	v_mfma_f32_16x16x32_bf16 v[74:77], v[130:133], v[208:211], v[74:77]
	v_mfma_f32_16x16x32_bf16 v[74:77], v[142:145], v[212:215], v[74:77]
	v_mfma_f32_16x16x32_bf16 v[78:81], v[126:129], v[212:215], v[78:81]
	v_mfma_f32_16x16x32_bf16 v[78:81], v[114:117], v[208:211], v[78:81]
	v_mfma_f32_16x16x32_bf16 v[122:125], v[146:149], v[184:187], v[122:125]
	v_mfma_f32_16x16x32_bf16 v[122:125], v[150:153], v[188:191], v[122:125]
	v_mfma_f32_16x16x32_bf16 v[118:121], v[178:181], v[188:191], v[118:121]
	v_mfma_f32_16x16x32_bf16 v[118:121], v[174:177], v[184:187], v[118:121]
	v_mfma_f32_16x16x32_bf16 v[98:101], v[174:177], v[192:195], v[98:101]
	v_mfma_f32_16x16x32_bf16 v[98:101], v[178:181], v[196:199], v[98:101]
	v_mfma_f32_16x16x32_bf16 v[102:105], v[150:153], v[196:199], v[102:105]
	v_mfma_f32_16x16x32_bf16 v[102:105], v[146:149], v[192:195], v[102:105]
	v_mfma_f32_16x16x32_bf16 v[86:89], v[146:149], v[200:203], v[86:89]
	v_mfma_f32_16x16x32_bf16 v[86:89], v[150:153], v[204:207], v[86:89]
	v_mfma_f32_16x16x32_bf16 v[82:85], v[178:181], v[204:207], v[82:85]
	v_mfma_f32_16x16x32_bf16 v[82:85], v[174:177], v[200:203], v[82:85]
	s_barrier
	s_setprio 2
	v_mfma_f32_16x16x32_bf16 v[66:69], v[174:177], v[208:211], v[66:69]
	v_mfma_f32_16x16x32_bf16 v[66:69], v[178:181], v[212:215], v[66:69]
	v_mfma_f32_16x16x32_bf16 v[70:73], v[150:153], v[212:215], v[70:73]
	v_mfma_f32_16x16x32_bf16 v[70:73], v[146:149], v[208:211], v[70:73]
	s_setprio 0
	s_add_i32 s39, s73, s55
	v_lshl_add_u64 v[162:163], s[70:71], 0, v[154:155]
	s_mov_b32 m0, s39
	ds_read_b128 v[184:187], v169 offset:16384
	ds_read_b128 v[188:191], v169 offset:17408
	ds_read_b128 v[192:195], v169 offset:18432
	ds_read_b128 v[196:199], v169 offset:19456
	ds_read_b128 v[200:203], v169 offset:20480
	ds_read_b128 v[204:207], v169 offset:21504
	ds_read_b128 v[208:211], v169 offset:22528
	ds_read_b128 v[212:215], v169 offset:23552
	global_load_lds_dwordx4 v[162:163], off
	v_lshl_add_u64 v[216:217], v[162:163], 0, s[12:13]
	s_add_i32 m0, s39, 0x2000
	s_add_i32 s39, s74, s55
	global_load_lds_dwordx4 v[216:217], off
	v_lshl_add_u64 v[216:217], v[162:163], 0, s[14:15]
	s_mov_b32 m0, s39
	s_nop 0
	global_load_lds_dwordx4 v[216:217], off
	v_lshl_add_u64 v[216:217], v[162:163], 0, s[16:17]
	s_add_i32 m0, s39, 0x2000
	s_nop 0
	global_load_lds_dwordx4 v[216:217], off
	v_lshl_add_u64 v[216:217], s[68:69], 0, v[154:155]
	s_mov_b32 m0, s56
	v_lshl_add_u64 v[218:219], v[216:217], 0, s[12:13]
	global_load_lds_dwordx4 v[216:217], off
	s_mov_b32 m0, s57
	s_nop 0
	global_load_lds_dwordx4 v[218:219], off
	s_waitcnt vmcnt(8)
	s_waitcnt lgkmcnt(0)
	s_barrier
; #define PG8_STAGE(bufoff, gbase, voff) do { if constexpr (!pg8_noload<Epi>::value) { _Pragma("unroll") for (int _i = 0; _i < 2; ++_i) \
;         __builtin_amdgcn_global_load_lds((const unsigned*)((const char*)(gbase) + (size_t)_i * pstep + (voff)[0]), (PG8_LAS unsigned*)(lds + (bufoff) + ldsw + _i * 8192), 16, 0, 0); } } while (0)
; #define PG8_LDA(dst, b, h) do { _Pragma("unroll") for (int m = 0; m < 4; ++m) _Pragma("unroll") for (int k = 0; k < 2; ++k) dst[m][k] = *(const PG8_LAS bf16x8*)(lds + PG8_SA(b, h) + aoff + m * 2048 + k * 1024); } while (0)
; #define PG8_LDB(dst, b, h) do { _Pragma("unroll") for (int n = 0; n < 2; ++n) _Pragma("unroll") for (int k = 0; k < 2; ++k) dst[n][k] = *(const PG8_LAS bf16x8*)(lds + PG8_SB(b, h) + boff + n * 2048 + k * 1024); } while (0)
; #define PG8_MMA(ai, bj, At, Bt) do { __builtin_amdgcn_s_setprio(1); _Pragma("unroll") for (int m = 0; m < 4; ++m) _Pragma("unroll") for (int n = 0; n < 2; ++n) _Pragma("unroll") for (int k = 0; k < 2; ++k) \
;         acc[ai][bj][m][n] = __builtin_amdgcn_mfma_f32_16x16x32_bf16(Bt[n][k], At[m][k], acc[ai][bj][m][n], 0, 0, 0); __builtin_amdgcn_s_setprio(0); } while (0)
; #define PG8_WAIT_V(n) asm volatile("s_waitcnt vmcnt(" #n ")" ::: "memory")
; #define PG8_WAIT_L(n) asm volatile("s_waitcnt lgkmcnt(" #n ")" ::: "memory")
; #define PG8_BAR __builtin_amdgcn_s_barrier()
; #define PG8_SCHED __builtin_amdgcn_sched_barrier(0)
; template <class Epi, class Sched, bool ALIGN_EPI = false, bool SP2 = false, bool ABLK = false>
; __device__ __forceinline__ void gemm_phase(PG8_LAS unsigned char* lds, const Gemm g, const Sched& S, const Epi& E) {
;     ...
;             PG8_WAIT_V(8); PG8_WAIT_L(0); PG8_BAR; PG8_MMA(1, 0, At, B0); PG8_MMA(1, 1, At, B1); PG8_BAR; PG8_SCHED;
;             PG8_LDB(B0, 1, 0); PG8_LDB(B1, 1, 1); PG8_SCHED; PG8_LDA(At, 1, 0); PG8_STAGE(PG8_SA(0, 1), a2 + hstep, voffA);
;             PG8_WAIT_V(8); PG8_WAIT_L(0); PG8_BAR; PG8_MMA(0, 0, At, B0); PG8_MMA(0, 1, At, B1); PG8_BAR; PG8_SCHED;
	s_setprio 1
	s_waitcnt lgkmcnt(0)
	v_mfma_f32_16x16x32_bf16 v[62:65], v[114:117], v[184:187], v[62:65]
	v_mfma_f32_16x16x32_bf16 v[62:65], v[126:129], v[188:191], v[62:65]
	v_mfma_f32_16x16x32_bf16 v[58:61], v[142:145], v[188:191], v[58:61]
	v_mfma_f32_16x16x32_bf16 v[58:61], v[130:133], v[184:187], v[58:61]
	v_mfma_f32_16x16x32_bf16 v[42:45], v[130:133], v[192:195], v[42:45]
	v_mfma_f32_16x16x32_bf16 v[42:45], v[142:145], v[196:199], v[42:45]
	v_mfma_f32_16x16x32_bf16 v[46:49], v[126:129], v[196:199], v[46:49]
	v_mfma_f32_16x16x32_bf16 v[46:49], v[114:117], v[192:195], v[46:49]
	v_mfma_f32_16x16x32_bf16 v[30:33], v[114:117], v[200:203], v[30:33]
	v_mfma_f32_16x16x32_bf16 v[30:33], v[126:129], v[204:207], v[30:33]
	v_mfma_f32_16x16x32_bf16 v[26:29], v[142:145], v[204:207], v[26:29]
	v_mfma_f32_16x16x32_bf16 v[26:29], v[130:133], v[200:203], v[26:29]
	v_mfma_f32_16x16x32_bf16 v[10:13], v[130:133], v[208:211], v[10:13]
	v_mfma_f32_16x16x32_bf16 v[10:13], v[142:145], v[212:215], v[10:13]
	v_mfma_f32_16x16x32_bf16 v[14:17], v[126:129], v[212:215], v[14:17]
	v_mfma_f32_16x16x32_bf16 v[14:17], v[114:117], v[208:211], v[14:17]
	v_mfma_f32_16x16x32_bf16 v[54:57], v[146:149], v[184:187], v[54:57]
	v_mfma_f32_16x16x32_bf16 v[54:57], v[150:153], v[188:191], v[54:57]
	v_mfma_f32_16x16x32_bf16 v[50:53], v[178:181], v[188:191], v[50:53]
	v_mfma_f32_16x16x32_bf16 v[50:53], v[174:177], v[184:187], v[50:53]
	v_mfma_f32_16x16x32_bf16 v[34:37], v[174:177], v[192:195], v[34:37]
	v_mfma_f32_16x16x32_bf16 v[34:37], v[178:181], v[196:199], v[34:37]
	v_mfma_f32_16x16x32_bf16 v[38:41], v[150:153], v[196:199], v[38:41]
	v_mfma_f32_16x16x32_bf16 v[38:41], v[146:149], v[192:195], v[38:41]
	v_mfma_f32_16x16x32_bf16 v[22:25], v[146:149], v[200:203], v[22:25]
	v_mfma_f32_16x16x32_bf16 v[22:25], v[150:153], v[204:207], v[22:25]
	v_mfma_f32_16x16x32_bf16 v[18:21], v[178:181], v[204:207], v[18:21]
	v_mfma_f32_16x16x32_bf16 v[18:21], v[174:177], v[200:203], v[18:21]
	s_barrier
	s_setprio 2
	v_mfma_f32_16x16x32_bf16 v[2:5], v[174:177], v[208:211], v[2:5]
	v_mfma_f32_16x16x32_bf16 v[2:5], v[178:181], v[212:215], v[2:5]
	v_mfma_f32_16x16x32_bf16 v[6:9], v[150:153], v[212:215], v[6:9]
	v_mfma_f32_16x16x32_bf16 v[6:9], v[146:149], v[208:211], v[6:9]
	s_setprio 0
	s_add_i32 s39, 0, 0x18000
	s_add_i32 s68, 0, 0x1c000
	v_add_u32_e32 v142, s39, v1
	v_add_u32_e32 v173, s68, v1
	ds_read_b128 v[114:117], v142
	ds_read_b128 v[126:129], v142 offset:1024
	ds_read_b128 v[130:133], v142 offset:2048
	ds_read_b128 v[142:145], v142 offset:3072
	ds_read_b128 v[146:149], v173
	ds_read_b128 v[150:153], v173 offset:1024
	ds_read_b128 v[174:177], v173 offset:2048
	ds_read_b128 v[178:181], v173 offset:3072
	s_mov_b32 m0, s58
	v_lshl_add_u64 v[218:219], v[216:217], 0, s[14:15]
	ds_read_b128 v[184:187], v169 offset:32768
	ds_read_b128 v[188:191], v169 offset:33792
	ds_read_b128 v[192:195], v169 offset:34816
	ds_read_b128 v[196:199], v169 offset:35840
	ds_read_b128 v[200:203], v169 offset:36864
	ds_read_b128 v[204:207], v169 offset:37888
	ds_read_b128 v[208:211], v169 offset:38912
	ds_read_b128 v[212:215], v169 offset:39936
	global_load_lds_dwordx4 v[218:219], off
	v_lshl_add_u64 v[218:219], v[216:217], 0, s[16:17]
	s_mov_b32 m0, s59
	s_nop 0
	global_load_lds_dwordx4 v[218:219], off
	s_waitcnt vmcnt(8)
	s_waitcnt lgkmcnt(0)
	s_barrier
	s_setprio 1
	s_waitcnt lgkmcnt(0)
	v_mfma_f32_16x16x32_bf16 v[138:141], v[114:117], v[184:187], v[138:141]
	v_mfma_f32_16x16x32_bf16 v[138:141], v[126:129], v[188:191], v[138:141]
	v_mfma_f32_16x16x32_bf16 v[134:137], v[142:145], v[188:191], v[134:137]
	v_mfma_f32_16x16x32_bf16 v[134:137], v[130:133], v[184:187], v[134:137]
	v_mfma_f32_16x16x32_bf16 v[106:109], v[130:133], v[192:195], v[106:109]
	v_mfma_f32_16x16x32_bf16 v[106:109], v[142:145], v[196:199], v[106:109]
	v_mfma_f32_16x16x32_bf16 v[110:113], v[126:129], v[196:199], v[110:113]
	v_mfma_f32_16x16x32_bf16 v[110:113], v[114:117], v[192:195], v[110:113]
	v_mfma_f32_16x16x32_bf16 v[94:97], v[114:117], v[200:203], v[94:97]
	v_mfma_f32_16x16x32_bf16 v[94:97], v[126:129], v[204:207], v[94:97]
	v_mfma_f32_16x16x32_bf16 v[90:93], v[142:145], v[204:207], v[90:93]
	v_mfma_f32_16x16x32_bf16 v[90:93], v[130:133], v[200:203], v[90:93]
	v_mfma_f32_16x16x32_bf16 v[74:77], v[130:133], v[208:211], v[74:77]
	v_mfma_f32_16x16x32_bf16 v[74:77], v[142:145], v[212:215], v[74:77]
	v_mfma_f32_16x16x32_bf16 v[78:81], v[126:129], v[212:215], v[78:81]
	v_mfma_f32_16x16x32_bf16 v[78:81], v[114:117], v[208:211], v[78:81]
	v_mfma_f32_16x16x32_bf16 v[122:125], v[146:149], v[184:187], v[122:125]
	v_mfma_f32_16x16x32_bf16 v[122:125], v[150:153], v[188:191], v[122:125]
	v_mfma_f32_16x16x32_bf16 v[118:121], v[178:181], v[188:191], v[118:121]
	v_mfma_f32_16x16x32_bf16 v[118:121], v[174:177], v[184:187], v[118:121]
	v_mfma_f32_16x16x32_bf16 v[98:101], v[174:177], v[192:195], v[98:101]
	v_mfma_f32_16x16x32_bf16 v[98:101], v[178:181], v[196:199], v[98:101]
	v_mfma_f32_16x16x32_bf16 v[102:105], v[150:153], v[196:199], v[102:105]
	v_mfma_f32_16x16x32_bf16 v[102:105], v[146:149], v[192:195], v[102:105]
	v_mfma_f32_16x16x32_bf16 v[86:89], v[146:149], v[200:203], v[86:89]
	v_mfma_f32_16x16x32_bf16 v[86:89], v[150:153], v[204:207], v[86:89]
	v_mfma_f32_16x16x32_bf16 v[82:85], v[178:181], v[204:207], v[82:85]
	v_mfma_f32_16x16x32_bf16 v[82:85], v[174:177], v[200:203], v[82:85]
	s_barrier
; #define PG8_STAGE(bufoff, gbase, voff) do { if constexpr (!pg8_noload<Epi>::value) { _Pragma("unroll") for (int _i = 0; _i < 2; ++_i) \
;         __builtin_amdgcn_global_load_lds((const unsigned*)((const char*)(gbase) + (size_t)_i * pstep + (voff)[0]), (PG8_LAS unsigned*)(lds + (bufoff) + ldsw + _i * 8192), 16, 0, 0); } } while (0)
; #define PG8_LDA(dst, b, h) do { _Pragma("unroll") for (int m = 0; m < 4; ++m) _Pragma("unroll") for (int k = 0; k < 2; ++k) dst[m][k] = *(const PG8_LAS bf16x8*)(lds + PG8_SA(b, h) + aoff + m * 2048 + k * 1024); } while (0)
; #define PG8_MMA(ai, bj, At, Bt) do { __builtin_amdgcn_s_setprio(1); _Pragma("unroll") for (int m = 0; m < 4; ++m) _Pragma("unroll") for (int n = 0; n < 2; ++n) _Pragma("unroll") for (int k = 0; k < 2; ++k) \
;         acc[ai][bj][m][n] = __builtin_amdgcn_mfma_f32_16x16x32_bf16(Bt[n][k], At[m][k], acc[ai][bj][m][n], 0, 0, 0); __builtin_amdgcn_s_setprio(0); } while (0)
; #define PG8_WAIT_V(n) asm volatile("s_waitcnt vmcnt(" #n ")" ::: "memory")
; #define PG8_WAIT_L(n) asm volatile("s_waitcnt lgkmcnt(" #n ")" ::: "memory")
; #define PG8_BAR __builtin_amdgcn_s_barrier()
; #define PG8_SCHED __builtin_amdgcn_sched_barrier(0)
; template <class Epi, class Sched, bool ALIGN_EPI = false, bool SP2 = false, bool ABLK = false>
; __device__ __forceinline__ void gemm_phase(PG8_LAS unsigned char* lds, const Gemm g, const Sched& S, const Epi& E) {
;     ...
;             PG8_WAIT_V(8); PG8_WAIT_L(0); PG8_BAR; PG8_MMA(0, 0, At, B0); PG8_MMA(0, 1, At, B1); PG8_BAR; PG8_SCHED;
;             PG8_LDA(At, 1, 1); PG8_STAGE(PG8_SB(1, 0), b3, voffB); PG8_STAGE(PG8_SB(1, 1), b3 + hstep, voffB); PG8_STAGE(PG8_SA(1, 0), a3, voffA);
;             PG8_WAIT_V(8); PG8_WAIT_L(0); PG8_BAR; PG8_MMA(1, 0, At, B0); PG8_MMA(1, 1, At, B1); PG8_BAR; PG8_SCHED;
	s_setprio 2
	v_mfma_f32_16x16x32_bf16 v[66:69], v[174:177], v[208:211], v[66:69]
	v_mfma_f32_16x16x32_bf16 v[66:69], v[178:181], v[212:215], v[66:69]
	v_mfma_f32_16x16x32_bf16 v[70:73], v[150:153], v[212:215], v[70:73]
	v_mfma_f32_16x16x32_bf16 v[70:73], v[146:149], v[208:211], v[70:73]
	s_setprio 0
	s_add_i32 s39, s39, s55
	v_lshl_add_u64 v[218:219], v[162:163], 0, s[24:25]
	s_mov_b32 m0, s39
	ds_read_b128 v[184:187], v169 offset:49152
	ds_read_b128 v[188:191], v169 offset:50176
	ds_read_b128 v[192:195], v169 offset:51200
	ds_read_b128 v[196:199], v169 offset:52224
	ds_read_b128 v[200:203], v169 offset:53248
	ds_read_b128 v[204:207], v169 offset:54272
	ds_read_b128 v[208:211], v169 offset:55296
	ds_read_b128 v[212:215], v169 offset:56320
	global_load_lds_dwordx4 v[218:219], off
	v_lshl_add_u64 v[218:219], v[162:163], 0, s[26:27]
	s_add_i32 m0, s39, 0x2000
	s_add_i32 s39, s68, s55
	global_load_lds_dwordx4 v[218:219], off
	v_lshl_add_u64 v[218:219], v[162:163], 0, s[28:29]
	s_mov_b32 m0, s39
	v_lshl_add_u64 v[162:163], v[162:163], 0, s[30:31]
	global_load_lds_dwordx4 v[218:219], off
	s_add_i32 m0, s39, 0x2000
	s_nop 0
	global_load_lds_dwordx4 v[162:163], off
	v_lshl_add_u64 v[162:163], v[216:217], 0, s[24:25]
	s_mov_b32 m0, s62
	s_nop 0
	global_load_lds_dwordx4 v[162:163], off
	v_lshl_add_u64 v[162:163], v[216:217], 0, s[26:27]
	s_mov_b32 m0, s63
	s_nop 0
	global_load_lds_dwordx4 v[162:163], off
	s_waitcnt vmcnt(8)
	s_waitcnt lgkmcnt(0)
	s_barrier
	s_setprio 1
	s_waitcnt lgkmcnt(0)
	v_mfma_f32_16x16x32_bf16 v[62:65], v[114:117], v[184:187], v[62:65]
	v_mfma_f32_16x16x32_bf16 v[62:65], v[126:129], v[188:191], v[62:65]
	v_mfma_f32_16x16x32_bf16 v[58:61], v[142:145], v[188:191], v[58:61]
	v_mfma_f32_16x16x32_bf16 v[58:61], v[130:133], v[184:187], v[58:61]
	v_mfma_f32_16x16x32_bf16 v[42:45], v[130:133], v[192:195], v[42:45]
	v_mfma_f32_16x16x32_bf16 v[42:45], v[142:145], v[196:199], v[42:45]
	v_mfma_f32_16x16x32_bf16 v[46:49], v[126:129], v[196:199], v[46:49]
	v_mfma_f32_16x16x32_bf16 v[46:49], v[114:117], v[192:195], v[46:49]
	v_mfma_f32_16x16x32_bf16 v[30:33], v[114:117], v[200:203], v[30:33]
	v_mfma_f32_16x16x32_bf16 v[30:33], v[126:129], v[204:207], v[30:33]
	v_mfma_f32_16x16x32_bf16 v[26:29], v[142:145], v[204:207], v[26:29]
	v_mfma_f32_16x16x32_bf16 v[26:29], v[130:133], v[200:203], v[26:29]
	v_mfma_f32_16x16x32_bf16 v[10:13], v[130:133], v[208:211], v[10:13]
	v_mfma_f32_16x16x32_bf16 v[10:13], v[142:145], v[212:215], v[10:13]
	v_mfma_f32_16x16x32_bf16 v[14:17], v[126:129], v[212:215], v[14:17]
	v_mfma_f32_16x16x32_bf16 v[14:17], v[114:117], v[208:211], v[14:17]
	v_mfma_f32_16x16x32_bf16 v[54:57], v[146:149], v[184:187], v[54:57]
	v_mfma_f32_16x16x32_bf16 v[54:57], v[150:153], v[188:191], v[54:57]
	v_mfma_f32_16x16x32_bf16 v[50:53], v[178:181], v[188:191], v[50:53]
	v_mfma_f32_16x16x32_bf16 v[50:53], v[174:177], v[184:187], v[50:53]
	v_mfma_f32_16x16x32_bf16 v[34:37], v[174:177], v[192:195], v[34:37]
	v_mfma_f32_16x16x32_bf16 v[34:37], v[178:181], v[196:199], v[34:37]
	v_mfma_f32_16x16x32_bf16 v[38:41], v[150:153], v[196:199], v[38:41]
	v_mfma_f32_16x16x32_bf16 v[38:41], v[146:149], v[192:195], v[38:41]
	v_mfma_f32_16x16x32_bf16 v[22:25], v[146:149], v[200:203], v[22:25]
	v_mfma_f32_16x16x32_bf16 v[22:25], v[150:153], v[204:207], v[22:25]
	v_mfma_f32_16x16x32_bf16 v[18:21], v[178:181], v[204:207], v[18:21]
	v_mfma_f32_16x16x32_bf16 v[18:21], v[174:177], v[200:203], v[18:21]
	s_barrier
	s_setprio 2
	v_mfma_f32_16x16x32_bf16 v[2:5], v[174:177], v[208:211], v[2:5]
	v_mfma_f32_16x16x32_bf16 v[2:5], v[178:181], v[212:215], v[2:5]
	v_mfma_f32_16x16x32_bf16 v[6:9], v[150:153], v[212:215], v[6:9]
	v_mfma_f32_16x16x32_bf16 v[6:9], v[146:149], v[208:211], v[6:9]
	s_setprio 0
	s_add_u32 s92, s92, 0x1000
	s_addc_u32 s93, s93, 0
	s_add_u32 s11, s11, 0x1000
	s_addc_u32 s37, s37, 0
	s_cmp_ge_i32 s65, s80
	s_mov_b32 s39, s65
	s_cbranch_scc0 .LBB0_487
	s_and_b64 vcc, exec, s[34:35]
	s_cbranch_vccnz .LBB0_492
	s_lshl_b32 s11, s2, 8
	s_cmp_gt_i32 s2, 63
	s_mov_b64 s[68:69], -1
	s_cbranch_scc1 .LBB0_493

; #define PG8_STAGE(bufoff, gbase, voff) do { if constexpr (!pg8_noload<Epi>::value) { _Pragma("unroll") for (int _i = 0; _i < 2; ++_i) \
;         __builtin_amdgcn_global_load_lds((const unsigned*)((const char*)(gbase) + (size_t)_i * pstep + (voff)[0]), (PG8_LAS unsigned*)(lds + (bufoff) + ldsw + _i * 8192), 16, 0, 0); } } while (0)
; #define PG8_LDA(dst, b, h) do { _Pragma("unroll") for (int m = 0; m < 4; ++m) _Pragma("unroll") for (int k = 0; k < 2; ++k) dst[m][k] = *(const PG8_LAS bf16x8*)(lds + PG8_SA(b, h) + aoff + m * 2048 + k * 1024); } while (0)
; #define PG8_LDB(dst, b, h) do { _Pragma("unroll") for (int n = 0; n < 2; ++n) _Pragma("unroll") for (int k = 0; k < 2; ++k) dst[n][k] = *(const PG8_LAS bf16x8*)(lds + PG8_SB(b, h) + boff + n * 2048 + k * 1024); } while (0)
; #define PG8_MMA(ai, bj, At, Bt) do { __builtin_amdgcn_s_setprio(1); _Pragma("unroll") for (int m = 0; m < 4; ++m) _Pragma("unroll") for (int n = 0; n < 2; ++n) _Pragma("unroll") for (int k = 0; k < 2; ++k) \
;         acc[ai][bj][m][n] = __builtin_amdgcn_mfma_f32_16x16x32_bf16(Bt[n][k], At[m][k], acc[ai][bj][m][n], 0, 0, 0); __builtin_amdgcn_s_setprio(0); } while (0)
; #define PG8_BAR __builtin_amdgcn_s_barrier()
; template <class Epi, class Sched, bool ALIGN_EPI = false, bool SP2 = false, bool ABLK = false>
; __device__ __forceinline__ void gemm_phase(PG8_LAS unsigned char* lds, const Gemm g, const Sched& S, const Epi& E) {
;     ...
;         for (int t = 0; t < nt; t += 2) {
;             const bool last = (t == nt - 2);
;             const char* a1 = cA + (size_t)(t + 1) * kstep;
;             const char* a2 = last ? nA : cA + (size_t)(t + 2) * kstep; const char* b2 = last ? nB : cB + (size_t)(t + 2) * kstepB;
;             const char* a3 = a2 + kstep; const char* b3 = b2 + kstepB;
;             if (last && has_next) S.a_ready(nxt);
;             if constexpr (SP2) {
;             PG8_LDB(B0, 0, 0); PG8_LDB(B1, 0, 1); PG8_SCHED; PG8_LDA(At, 0, 0); PG8_STAGE(PG8_SA(1, 1), a1 + hstep, voffA);
;             PG8_WAIT_V(8); PG8_WAIT_L(0); PG8_BAR; PG8_MMA(0, 0, At, B0); PG8_MMA(0, 1, At, B1); PG8_BAR; PG8_SCHED;
;             PG8_LDA(At, 0, 1); PG8_STAGE(PG8_SB(0, 0), b2, voffB); PG8_STAGE(PG8_SB(0, 1), b2 + hstep, voffB); PG8_STAGE(PG8_SA(0, 0), a2, voffA);
;             PG8_WAIT_V(8); PG8_WAIT_L(0); PG8_BAR; PG8_MMA(1, 0, At, B0); PG8_MMA(1, 1, At, B1); PG8_BAR; PG8_SCHED;
.LBB0_619:
	s_or_b32 s28, s57, 1
	s_lshl_b64 s[58:59], s[28:29], 11
	s_add_u32 s58, s2, s58
	s_addc_u32 s59, s3, s59
	s_add_i32 s28, s57, 2
	v_add_u32_e32 v160, s78, v168
	v_add_u32_e32 v180, s79, v168
	s_lshl_b64 s[60:61], s[28:29], 11
	ds_read_b128 v[130:133], v160
	ds_read_b128 v[134:137], v160 offset:1024
	ds_read_b128 v[156:159], v160 offset:2048
	ds_read_b128 v[160:163], v160 offset:3072
	ds_read_b128 v[164:167], v180
	ds_read_b128 v[176:179], v180 offset:1024
	ds_read_b128 v[184:187], v180 offset:2048
	ds_read_b128 v[188:191], v180 offset:3072
	s_add_u32 s66, s2, s60
	s_addc_u32 s67, s3, s61
	s_and_b64 s[62:63], s[68:69], exec
	s_cselect_b32 s73, s67, s7
	s_cselect_b32 s72, s66, s15
	s_add_u32 s62, s16, s60
	s_addc_u32 s63, s17, s61
	s_and_b64 s[60:61], s[68:69], exec
	s_cselect_b32 s61, s63, s9
	s_cselect_b32 s60, s62, s56
	v_lshl_add_u64 v[180:181], s[58:59], 0, v[138:139]
	v_lshl_add_u64 v[224:225], v[180:181], 0, s[24:25]
	s_add_i32 m0, s70, 0xc000
	ds_read_b128 v[192:195], v173
	ds_read_b128 v[196:199], v173 offset:1024
	ds_read_b128 v[200:203], v173 offset:2048
	ds_read_b128 v[204:207], v173 offset:3072
	ds_read_b128 v[208:211], v173 offset:4096
	ds_read_b128 v[212:215], v173 offset:5120
	ds_read_b128 v[216:219], v173 offset:6144
	ds_read_b128 v[220:223], v173 offset:7168
	global_load_lds_dwordx4 v[224:225], off
	v_lshl_add_u64 v[180:181], v[180:181], 0, s[26:27]
	s_add_i32 m0, s70, 0xe000
	s_nop 0
	global_load_lds_dwordx4 v[180:181], off
	s_waitcnt vmcnt(8)
	s_waitcnt lgkmcnt(0)
	s_barrier
	s_setprio 1
	s_waitcnt lgkmcnt(0)
	v_mfma_f32_16x16x32_bf16 v[126:129], v[130:133], v[192:195], v[126:129]
	v_mfma_f32_16x16x32_bf16 v[126:129], v[134:137], v[196:199], v[126:129]
	v_mfma_f32_16x16x32_bf16 v[122:125], v[160:163], v[196:199], v[122:125]
	v_mfma_f32_16x16x32_bf16 v[122:125], v[156:159], v[192:195], v[122:125]
	v_mfma_f32_16x16x32_bf16 v[106:109], v[156:159], v[200:203], v[106:109]
	v_mfma_f32_16x16x32_bf16 v[106:109], v[160:163], v[204:207], v[106:109]
	v_mfma_f32_16x16x32_bf16 v[110:113], v[134:137], v[204:207], v[110:113]
	v_mfma_f32_16x16x32_bf16 v[110:113], v[130:133], v[200:203], v[110:113]
	v_mfma_f32_16x16x32_bf16 v[94:97], v[130:133], v[208:211], v[94:97]
	v_mfma_f32_16x16x32_bf16 v[94:97], v[134:137], v[212:215], v[94:97]
	v_mfma_f32_16x16x32_bf16 v[90:93], v[160:163], v[212:215], v[90:93]
	v_mfma_f32_16x16x32_bf16 v[90:93], v[156:159], v[208:211], v[90:93]
	v_mfma_f32_16x16x32_bf16 v[74:77], v[156:159], v[216:219], v[74:77]
	v_mfma_f32_16x16x32_bf16 v[74:77], v[160:163], v[220:223], v[74:77]
	v_mfma_f32_16x16x32_bf16 v[78:81], v[134:137], v[220:223], v[78:81]
	v_mfma_f32_16x16x32_bf16 v[78:81], v[130:133], v[216:219], v[78:81]
	v_mfma_f32_16x16x32_bf16 v[118:121], v[164:167], v[192:195], v[118:121]
	v_mfma_f32_16x16x32_bf16 v[118:121], v[176:179], v[196:199], v[118:121]
	v_mfma_f32_16x16x32_bf16 v[114:117], v[188:191], v[196:199], v[114:117]
	v_mfma_f32_16x16x32_bf16 v[114:117], v[184:187], v[192:195], v[114:117]
	v_mfma_f32_16x16x32_bf16 v[98:101], v[184:187], v[200:203], v[98:101]
	v_mfma_f32_16x16x32_bf16 v[98:101], v[188:191], v[204:207], v[98:101]
	v_mfma_f32_16x16x32_bf16 v[102:105], v[176:179], v[204:207], v[102:105]
	v_mfma_f32_16x16x32_bf16 v[102:105], v[164:167], v[200:203], v[102:105]
	v_mfma_f32_16x16x32_bf16 v[86:89], v[164:167], v[208:211], v[86:89]
	v_mfma_f32_16x16x32_bf16 v[86:89], v[176:179], v[212:215], v[86:89]
	v_mfma_f32_16x16x32_bf16 v[82:85], v[188:191], v[212:215], v[82:85]
	v_mfma_f32_16x16x32_bf16 v[82:85], v[184:187], v[208:211], v[82:85]
	s_barrier
	s_setprio 2
	v_mfma_f32_16x16x32_bf16 v[66:69], v[184:187], v[216:219], v[66:69]
	v_mfma_f32_16x16x32_bf16 v[66:69], v[188:191], v[220:223], v[66:69]
	v_mfma_f32_16x16x32_bf16 v[70:73], v[176:179], v[220:223], v[70:73]
	v_mfma_f32_16x16x32_bf16 v[70:73], v[164:167], v[216:219], v[70:73]
	s_setprio 0
	s_add_i32 s58, s78, s91
	v_lshl_add_u64 v[180:181], s[60:61], 0, v[138:139]
	s_mov_b32 m0, s58
	ds_read_b128 v[192:195], v173 offset:16384
	ds_read_b128 v[196:199], v173 offset:17408
	ds_read_b128 v[200:203], v173 offset:18432
	ds_read_b128 v[204:207], v173 offset:19456
	ds_read_b128 v[208:211], v173 offset:20480
	ds_read_b128 v[212:215], v173 offset:21504
	ds_read_b128 v[216:219], v173 offset:22528
	ds_read_b128 v[220:223], v173 offset:23552
	global_load_lds_dwordx4 v[180:181], off
	v_lshl_add_u64 v[224:225], v[180:181], 0, s[22:23]
	s_add_i32 m0, s58, 0x2000
	s_add_i32 s58, s79, s91
	global_load_lds_dwordx4 v[224:225], off
	v_lshl_add_u64 v[224:225], v[180:181], 0, s[24:25]
	s_mov_b32 m0, s58
	s_nop 0
	global_load_lds_dwordx4 v[224:225], off
	v_lshl_add_u64 v[224:225], v[180:181], 0, s[26:27]
	s_add_i32 m0, s58, 0x2000
	s_nop 0
	global_load_lds_dwordx4 v[224:225], off
	v_lshl_add_u64 v[224:225], s[72:73], 0, v[138:139]
	s_mov_b32 m0, s70
	v_lshl_add_u64 v[226:227], v[224:225], 0, s[22:23]
	global_load_lds_dwordx4 v[224:225], off
	s_mov_b32 m0, s71
	s_nop 0
	global_load_lds_dwordx4 v[226:227], off
	s_waitcnt vmcnt(8)
	s_waitcnt lgkmcnt(0)
	s_barrier
; #define PG8_STAGE(bufoff, gbase, voff) do { if constexpr (!pg8_noload<Epi>::value) { _Pragma("unroll") for (int _i = 0; _i < 2; ++_i) \
;         __builtin_amdgcn_global_load_lds((const unsigned*)((const char*)(gbase) + (size_t)_i * pstep + (voff)[0]), (PG8_LAS unsigned*)(lds + (bufoff) + ldsw + _i * 8192), 16, 0, 0); } } while (0)
; #define PG8_LDA(dst, b, h) do { _Pragma("unroll") for (int m = 0; m < 4; ++m) _Pragma("unroll") for (int k = 0; k < 2; ++k) dst[m][k] = *(const PG8_LAS bf16x8*)(lds + PG8_SA(b, h) + aoff + m * 2048 + k * 1024); } while (0)
; #define PG8_LDB(dst, b, h) do { _Pragma("unroll") for (int n = 0; n < 2; ++n) _Pragma("unroll") for (int k = 0; k < 2; ++k) dst[n][k] = *(const PG8_LAS bf16x8*)(lds + PG8_SB(b, h) + boff + n * 2048 + k * 1024); } while (0)
; #define PG8_MMA(ai, bj, At, Bt) do { __builtin_amdgcn_s_setprio(1); _Pragma("unroll") for (int m = 0; m < 4; ++m) _Pragma("unroll") for (int n = 0; n < 2; ++n) _Pragma("unroll") for (int k = 0; k < 2; ++k) \
;         acc[ai][bj][m][n] = __builtin_amdgcn_mfma_f32_16x16x32_bf16(Bt[n][k], At[m][k], acc[ai][bj][m][n], 0, 0, 0); __builtin_amdgcn_s_setprio(0); } while (0)
; #define PG8_WAIT_V(n) asm volatile("s_waitcnt vmcnt(" #n ")" ::: "memory")
; #define PG8_WAIT_L(n) asm volatile("s_waitcnt lgkmcnt(" #n ")" ::: "memory")
; #define PG8_BAR __builtin_amdgcn_s_barrier()
; #define PG8_SCHED __builtin_amdgcn_sched_barrier(0)
; template <class Epi, class Sched, bool ALIGN_EPI = false, bool SP2 = false, bool ABLK = false>
; __device__ __forceinline__ void gemm_phase(PG8_LAS unsigned char* lds, const Gemm g, const Sched& S, const Epi& E) {
;     ...
;             PG8_WAIT_V(8); PG8_WAIT_L(0); PG8_BAR; PG8_MMA(1, 0, At, B0); PG8_MMA(1, 1, At, B1); PG8_BAR; PG8_SCHED;
;             PG8_LDB(B0, 1, 0); PG8_LDB(B1, 1, 1); PG8_SCHED; PG8_LDA(At, 1, 0); PG8_STAGE(PG8_SA(0, 1), a2 + hstep, voffA);
;             PG8_WAIT_V(8); PG8_WAIT_L(0); PG8_BAR; PG8_MMA(0, 0, At, B0); PG8_MMA(0, 1, At, B1); PG8_BAR; PG8_SCHED;
	s_setprio 1
	s_waitcnt lgkmcnt(0)
	v_mfma_f32_16x16x32_bf16 v[62:65], v[130:133], v[192:195], v[62:65]
	v_mfma_f32_16x16x32_bf16 v[62:65], v[134:137], v[196:199], v[62:65]
	v_mfma_f32_16x16x32_bf16 v[58:61], v[160:163], v[196:199], v[58:61]
	v_mfma_f32_16x16x32_bf16 v[58:61], v[156:159], v[192:195], v[58:61]
	v_mfma_f32_16x16x32_bf16 v[42:45], v[156:159], v[200:203], v[42:45]
	v_mfma_f32_16x16x32_bf16 v[42:45], v[160:163], v[204:207], v[42:45]
	v_mfma_f32_16x16x32_bf16 v[46:49], v[134:137], v[204:207], v[46:49]
	v_mfma_f32_16x16x32_bf16 v[46:49], v[130:133], v[200:203], v[46:49]
	v_mfma_f32_16x16x32_bf16 v[30:33], v[130:133], v[208:211], v[30:33]
	v_mfma_f32_16x16x32_bf16 v[30:33], v[134:137], v[212:215], v[30:33]
	v_mfma_f32_16x16x32_bf16 v[26:29], v[160:163], v[212:215], v[26:29]
	v_mfma_f32_16x16x32_bf16 v[26:29], v[156:159], v[208:211], v[26:29]
	v_mfma_f32_16x16x32_bf16 v[10:13], v[156:159], v[216:219], v[10:13]
	v_mfma_f32_16x16x32_bf16 v[10:13], v[160:163], v[220:223], v[10:13]
	v_mfma_f32_16x16x32_bf16 v[14:17], v[134:137], v[220:223], v[14:17]
	v_mfma_f32_16x16x32_bf16 v[14:17], v[130:133], v[216:219], v[14:17]
	v_mfma_f32_16x16x32_bf16 v[54:57], v[164:167], v[192:195], v[54:57]
	v_mfma_f32_16x16x32_bf16 v[54:57], v[176:179], v[196:199], v[54:57]
	v_mfma_f32_16x16x32_bf16 v[50:53], v[188:191], v[196:199], v[50:53]
	v_mfma_f32_16x16x32_bf16 v[50:53], v[184:187], v[192:195], v[50:53]
	v_mfma_f32_16x16x32_bf16 v[34:37], v[184:187], v[200:203], v[34:37]
	v_mfma_f32_16x16x32_bf16 v[34:37], v[188:191], v[204:207], v[34:37]
	v_mfma_f32_16x16x32_bf16 v[38:41], v[176:179], v[204:207], v[38:41]
	v_mfma_f32_16x16x32_bf16 v[38:41], v[164:167], v[200:203], v[38:41]
	v_mfma_f32_16x16x32_bf16 v[22:25], v[164:167], v[208:211], v[22:25]
	v_mfma_f32_16x16x32_bf16 v[22:25], v[176:179], v[212:215], v[22:25]
	v_mfma_f32_16x16x32_bf16 v[18:21], v[188:191], v[212:215], v[18:21]
	v_mfma_f32_16x16x32_bf16 v[18:21], v[184:187], v[208:211], v[18:21]
	s_barrier
	s_setprio 2
	v_mfma_f32_16x16x32_bf16 v[2:5], v[184:187], v[216:219], v[2:5]
	v_mfma_f32_16x16x32_bf16 v[2:5], v[188:191], v[220:223], v[2:5]
	v_mfma_f32_16x16x32_bf16 v[6:9], v[176:179], v[220:223], v[6:9]
	v_mfma_f32_16x16x32_bf16 v[6:9], v[164:167], v[216:219], v[6:9]
	s_setprio 0
	s_add_i32 s58, 0, 0x18000
	s_add_i32 s59, 0, 0x1c000
	v_add_u32_e32 v160, s58, v168
	v_add_u32_e32 v188, s59, v168
	ds_read_b128 v[130:133], v160
	ds_read_b128 v[134:137], v160 offset:1024
	ds_read_b128 v[156:159], v160 offset:2048
	ds_read_b128 v[160:163], v160 offset:3072
	ds_read_b128 v[164:167], v188
	ds_read_b128 v[176:179], v188 offset:1024
	ds_read_b128 v[184:187], v188 offset:2048
	ds_read_b128 v[188:191], v188 offset:3072
	s_mov_b32 m0, s34
	v_lshl_add_u64 v[226:227], v[224:225], 0, s[24:25]
	ds_read_b128 v[192:195], v173 offset:32768
	ds_read_b128 v[196:199], v173 offset:33792
	ds_read_b128 v[200:203], v173 offset:34816
	ds_read_b128 v[204:207], v173 offset:35840
	ds_read_b128 v[208:211], v173 offset:36864
	ds_read_b128 v[212:215], v173 offset:37888
	ds_read_b128 v[216:219], v173 offset:38912
	ds_read_b128 v[220:223], v173 offset:39936
	global_load_lds_dwordx4 v[226:227], off
	v_lshl_add_u64 v[226:227], v[224:225], 0, s[26:27]
	s_mov_b32 m0, s35
	s_nop 0
	global_load_lds_dwordx4 v[226:227], off
	s_waitcnt vmcnt(8)
	s_waitcnt lgkmcnt(0)
	s_barrier
	s_setprio 1
	s_waitcnt lgkmcnt(0)
	v_mfma_f32_16x16x32_bf16 v[126:129], v[130:133], v[192:195], v[126:129]
	v_mfma_f32_16x16x32_bf16 v[126:129], v[134:137], v[196:199], v[126:129]
	v_mfma_f32_16x16x32_bf16 v[122:125], v[160:163], v[196:199], v[122:125]
	v_mfma_f32_16x16x32_bf16 v[122:125], v[156:159], v[192:195], v[122:125]
	v_mfma_f32_16x16x32_bf16 v[106:109], v[156:159], v[200:203], v[106:109]
	v_mfma_f32_16x16x32_bf16 v[106:109], v[160:163], v[204:207], v[106:109]
	v_mfma_f32_16x16x32_bf16 v[110:113], v[134:137], v[204:207], v[110:113]
	v_mfma_f32_16x16x32_bf16 v[110:113], v[130:133], v[200:203], v[110:113]
	v_mfma_f32_16x16x32_bf16 v[94:97], v[130:133], v[208:211], v[94:97]
	v_mfma_f32_16x16x32_bf16 v[94:97], v[134:137], v[212:215], v[94:97]
	v_mfma_f32_16x16x32_bf16 v[90:93], v[160:163], v[212:215], v[90:93]
	v_mfma_f32_16x16x32_bf16 v[90:93], v[156:159], v[208:211], v[90:93]
	v_mfma_f32_16x16x32_bf16 v[74:77], v[156:159], v[216:219], v[74:77]
	v_mfma_f32_16x16x32_bf16 v[74:77], v[160:163], v[220:223], v[74:77]
	v_mfma_f32_16x16x32_bf16 v[78:81], v[134:137], v[220:223], v[78:81]
	v_mfma_f32_16x16x32_bf16 v[78:81], v[130:133], v[216:219], v[78:81]
	v_mfma_f32_16x16x32_bf16 v[118:121], v[164:167], v[192:195], v[118:121]
	v_mfma_f32_16x16x32_bf16 v[118:121], v[176:179], v[196:199], v[118:121]
	v_mfma_f32_16x16x32_bf16 v[114:117], v[188:191], v[196:199], v[114:117]
	v_mfma_f32_16x16x32_bf16 v[114:117], v[184:187], v[192:195], v[114:117]
	v_mfma_f32_16x16x32_bf16 v[98:101], v[184:187], v[200:203], v[98:101]
	v_mfma_f32_16x16x32_bf16 v[98:101], v[188:191], v[204:207], v[98:101]
	v_mfma_f32_16x16x32_bf16 v[102:105], v[176:179], v[204:207], v[102:105]
	v_mfma_f32_16x16x32_bf16 v[102:105], v[164:167], v[200:203], v[102:105]
	v_mfma_f32_16x16x32_bf16 v[86:89], v[164:167], v[208:211], v[86:89]
	v_mfma_f32_16x16x32_bf16 v[86:89], v[176:179], v[212:215], v[86:89]
	v_mfma_f32_16x16x32_bf16 v[82:85], v[188:191], v[212:215], v[82:85]
	v_mfma_f32_16x16x32_bf16 v[82:85], v[184:187], v[208:211], v[82:85]
	s_barrier
; #define PG8_STAGE(bufoff, gbase, voff) do { if constexpr (!pg8_noload<Epi>::value) { _Pragma("unroll") for (int _i = 0; _i < 2; ++_i) \
;         __builtin_amdgcn_global_load_lds((const unsigned*)((const char*)(gbase) + (size_t)_i * pstep + (voff)[0]), (PG8_LAS unsigned*)(lds + (bufoff) + ldsw + _i * 8192), 16, 0, 0); } } while (0)
; #define PG8_LDA(dst, b, h) do { _Pragma("unroll") for (int m = 0; m < 4; ++m) _Pragma("unroll") for (int k = 0; k < 2; ++k) dst[m][k] = *(const PG8_LAS bf16x8*)(lds + PG8_SA(b, h) + aoff + m * 2048 + k * 1024); } while (0)
; #define PG8_MMA(ai, bj, At, Bt) do { __builtin_amdgcn_s_setprio(1); _Pragma("unroll") for (int m = 0; m < 4; ++m) _Pragma("unroll") for (int n = 0; n < 2; ++n) _Pragma("unroll") for (int k = 0; k < 2; ++k) \
;         acc[ai][bj][m][n] = __builtin_amdgcn_mfma_f32_16x16x32_bf16(Bt[n][k], At[m][k], acc[ai][bj][m][n], 0, 0, 0); __builtin_amdgcn_s_setprio(0); } while (0)
; #define PG8_WAIT_V(n) asm volatile("s_waitcnt vmcnt(" #n ")" ::: "memory")
; #define PG8_WAIT_L(n) asm volatile("s_waitcnt lgkmcnt(" #n ")" ::: "memory")
; #define PG8_BAR __builtin_amdgcn_s_barrier()
; #define PG8_SCHED __builtin_amdgcn_sched_barrier(0)
; template <class Epi, class Sched, bool ALIGN_EPI = false, bool SP2 = false, bool ABLK = false>
; __device__ __forceinline__ void gemm_phase(PG8_LAS unsigned char* lds, const Gemm g, const Sched& S, const Epi& E) {
;     ...
;             PG8_WAIT_V(8); PG8_WAIT_L(0); PG8_BAR; PG8_MMA(0, 0, At, B0); PG8_MMA(0, 1, At, B1); PG8_BAR; PG8_SCHED;
;             PG8_LDA(At, 1, 1); PG8_STAGE(PG8_SB(1, 0), b3, voffB); PG8_STAGE(PG8_SB(1, 1), b3 + hstep, voffB); PG8_STAGE(PG8_SA(1, 0), a3, voffA);
;             PG8_WAIT_V(8); PG8_WAIT_L(0); PG8_BAR; PG8_MMA(1, 0, At, B0); PG8_MMA(1, 1, At, B1); PG8_BAR; PG8_SCHED;
	s_setprio 2
	v_mfma_f32_16x16x32_bf16 v[66:69], v[184:187], v[216:219], v[66:69]
	v_mfma_f32_16x16x32_bf16 v[66:69], v[188:191], v[220:223], v[66:69]
	v_mfma_f32_16x16x32_bf16 v[70:73], v[176:179], v[220:223], v[70:73]
	v_mfma_f32_16x16x32_bf16 v[70:73], v[164:167], v[216:219], v[70:73]
	s_setprio 0
	s_add_i32 s58, s58, s91
	v_lshl_add_u64 v[226:227], v[180:181], 0, s[92:93]
	s_mov_b32 m0, s58
	ds_read_b128 v[192:195], v173 offset:49152
	ds_read_b128 v[196:199], v173 offset:50176
	ds_read_b128 v[200:203], v173 offset:51200
	ds_read_b128 v[204:207], v173 offset:52224
	ds_read_b128 v[208:211], v173 offset:53248
	ds_read_b128 v[212:215], v173 offset:54272
	ds_read_b128 v[216:219], v173 offset:55296
	ds_read_b128 v[220:223], v173 offset:56320
	global_load_lds_dwordx4 v[226:227], off
	v_lshl_add_u64 v[226:227], v[180:181], 0, s[94:95]
	s_add_i32 m0, s58, 0x2000
	s_add_i32 s58, s59, s91
	global_load_lds_dwordx4 v[226:227], off
	v_lshl_add_u64 v[226:227], v[180:181], 0, s[96:97]
	s_mov_b32 m0, s58
	v_lshl_add_u64 v[180:181], v[180:181], 0, s[88:89]
	global_load_lds_dwordx4 v[226:227], off
	s_add_i32 m0, s58, 0x2000
	s_nop 0
	global_load_lds_dwordx4 v[180:181], off
	v_lshl_add_u64 v[180:181], v[224:225], 0, s[92:93]
	s_mov_b32 m0, s10
	s_nop 0
	global_load_lds_dwordx4 v[180:181], off
	v_lshl_add_u64 v[180:181], v[224:225], 0, s[94:95]
	s_mov_b32 m0, s11
	s_nop 0
	global_load_lds_dwordx4 v[180:181], off
	s_waitcnt vmcnt(8)
	s_waitcnt lgkmcnt(0)
	s_barrier
	s_setprio 1
	s_waitcnt lgkmcnt(0)
	v_mfma_f32_16x16x32_bf16 v[62:65], v[130:133], v[192:195], v[62:65]
	v_mfma_f32_16x16x32_bf16 v[62:65], v[134:137], v[196:199], v[62:65]
	v_mfma_f32_16x16x32_bf16 v[58:61], v[160:163], v[196:199], v[58:61]
	v_mfma_f32_16x16x32_bf16 v[58:61], v[156:159], v[192:195], v[58:61]
	v_mfma_f32_16x16x32_bf16 v[42:45], v[156:159], v[200:203], v[42:45]
	v_mfma_f32_16x16x32_bf16 v[42:45], v[160:163], v[204:207], v[42:45]
	v_mfma_f32_16x16x32_bf16 v[46:49], v[134:137], v[204:207], v[46:49]
	v_mfma_f32_16x16x32_bf16 v[46:49], v[130:133], v[200:203], v[46:49]
	v_mfma_f32_16x16x32_bf16 v[30:33], v[130:133], v[208:211], v[30:33]
	v_mfma_f32_16x16x32_bf16 v[30:33], v[134:137], v[212:215], v[30:33]
	v_mfma_f32_16x16x32_bf16 v[26:29], v[160:163], v[212:215], v[26:29]
	v_mfma_f32_16x16x32_bf16 v[26:29], v[156:159], v[208:211], v[26:29]
	v_mfma_f32_16x16x32_bf16 v[10:13], v[156:159], v[216:219], v[10:13]
	v_mfma_f32_16x16x32_bf16 v[10:13], v[160:163], v[220:223], v[10:13]
	v_mfma_f32_16x16x32_bf16 v[14:17], v[134:137], v[220:223], v[14:17]
	v_mfma_f32_16x16x32_bf16 v[14:17], v[130:133], v[216:219], v[14:17]
	v_mfma_f32_16x16x32_bf16 v[54:57], v[164:167], v[192:195], v[54:57]
	v_mfma_f32_16x16x32_bf16 v[54:57], v[176:179], v[196:199], v[54:57]
	v_mfma_f32_16x16x32_bf16 v[50:53], v[188:191], v[196:199], v[50:53]
	v_mfma_f32_16x16x32_bf16 v[50:53], v[184:187], v[192:195], v[50:53]
	v_mfma_f32_16x16x32_bf16 v[34:37], v[184:187], v[200:203], v[34:37]
	v_mfma_f32_16x16x32_bf16 v[34:37], v[188:191], v[204:207], v[34:37]
	v_mfma_f32_16x16x32_bf16 v[38:41], v[176:179], v[204:207], v[38:41]
	v_mfma_f32_16x16x32_bf16 v[38:41], v[164:167], v[200:203], v[38:41]
	v_mfma_f32_16x16x32_bf16 v[22:25], v[164:167], v[208:211], v[22:25]
	v_mfma_f32_16x16x32_bf16 v[22:25], v[176:179], v[212:215], v[22:25]
	v_mfma_f32_16x16x32_bf16 v[18:21], v[188:191], v[212:215], v[18:21]
	v_mfma_f32_16x16x32_bf16 v[18:21], v[184:187], v[208:211], v[18:21]
	s_barrier
	s_setprio 2
	v_mfma_f32_16x16x32_bf16 v[2:5], v[184:187], v[216:219], v[2:5]
	v_mfma_f32_16x16x32_bf16 v[2:5], v[188:191], v[220:223], v[2:5]
	v_mfma_f32_16x16x32_bf16 v[6:9], v[176:179], v[220:223], v[6:9]
	v_mfma_f32_16x16x32_bf16 v[6:9], v[164:167], v[216:219], v[6:9]
	s_setprio 0
	s_cmp_gt_u32 s57, 29
	s_mov_b32 s57, s28
	s_cbranch_scc1 .LBB0_631

; #define PG8_STAGE(bufoff, gbase, voff) do { if constexpr (!pg8_noload<Epi>::value) { _Pragma("unroll") for (int _i = 0; _i < 2; ++_i) \
;         __builtin_amdgcn_global_load_lds((const unsigned*)((const char*)(gbase) + (size_t)_i * pstep + (voff)[0]), (PG8_LAS unsigned*)(lds + (bufoff) + ldsw + _i * 8192), 16, 0, 0); } } while (0)
; #define PG8_LDA(dst, b, h) do { _Pragma("unroll") for (int m = 0; m < 4; ++m) _Pragma("unroll") for (int k = 0; k < 2; ++k) dst[m][k] = *(const PG8_LAS bf16x8*)(lds + PG8_SA(b, h) + aoff + m * 2048 + k * 1024); } while (0)
; #define PG8_LDB(dst, b, h) do { _Pragma("unroll") for (int n = 0; n < 2; ++n) _Pragma("unroll") for (int k = 0; k < 2; ++k) dst[n][k] = *(const PG8_LAS bf16x8*)(lds + PG8_SB(b, h) + boff + n * 2048 + k * 1024); } while (0)
; #define PG8_MMA(ai, bj, At, Bt) do { __builtin_amdgcn_s_setprio(1); _Pragma("unroll") for (int m = 0; m < 4; ++m) _Pragma("unroll") for (int n = 0; n < 2; ++n) _Pragma("unroll") for (int k = 0; k < 2; ++k) \
;         acc[ai][bj][m][n] = __builtin_amdgcn_mfma_f32_16x16x32_bf16(Bt[n][k], At[m][k], acc[ai][bj][m][n], 0, 0, 0); __builtin_amdgcn_s_setprio(0); } while (0)
; #define PG8_BAR __builtin_amdgcn_s_barrier()
; template <class Epi, class Sched, bool ALIGN_EPI = false, bool SP2 = false, bool ABLK = false>
; __device__ __forceinline__ void gemm_phase(PG8_LAS unsigned char* lds, const Gemm g, const Sched& S, const Epi& E) {
;     ...
;         for (int t = 0; t < nt; t += 2) {
;             const bool last = (t == nt - 2);
;             const char* a1 = cA + (size_t)(t + 1) * kstep;
;             const char* a2 = last ? nA : cA + (size_t)(t + 2) * kstep; const char* b2 = last ? nB : cB + (size_t)(t + 2) * kstepB;
;             const char* a3 = a2 + kstep; const char* b3 = b2 + kstepB;
;             if (last && has_next) S.a_ready(nxt);
;             if constexpr (SP2) {
;             PG8_LDB(B0, 0, 0); PG8_LDB(B1, 0, 1); PG8_SCHED; PG8_LDA(At, 0, 0); PG8_STAGE(PG8_SA(1, 1), a1 + hstep, voffA);
;             PG8_WAIT_V(8); PG8_WAIT_L(0); PG8_BAR; PG8_MMA(0, 0, At, B0); PG8_MMA(0, 1, At, B1); PG8_BAR; PG8_SCHED;
;             PG8_LDA(At, 0, 1); PG8_STAGE(PG8_SB(0, 0), b2, voffB); PG8_STAGE(PG8_SB(0, 1), b2 + hstep, voffB); PG8_STAGE(PG8_SA(0, 0), a2, voffA);
;             PG8_WAIT_V(8); PG8_WAIT_L(0); PG8_BAR; PG8_MMA(1, 0, At, B0); PG8_MMA(1, 1, At, B1); PG8_BAR; PG8_SCHED;
.LBB0_1533:
	ds_read_b128 v[114:117], v167
	ds_read_b128 v[126:129], v167 offset:1024
	ds_read_b128 v[130:133], v167 offset:2048
	ds_read_b128 v[142:145], v167 offset:3072
	ds_read_b128 v[146:149], v168
	ds_read_b128 v[150:153], v168 offset:1024
	ds_read_b128 v[174:177], v168 offset:2048
	ds_read_b128 v[178:181], v168 offset:3072
	s_add_i32 s41, s39, 2
	s_add_u32 s70, s68, 0xfff00800
	s_addc_u32 s71, s69, -1
	s_cmp_eq_u32 s3, s39
	s_cselect_b32 s71, s43, s71
	s_cselect_b32 s70, s42, s70
	s_cselect_b32 s81, s65, s37
	s_cselect_b32 s80, s64, s11
	v_lshl_add_u64 v[162:163], s[68:69], 0, v[158:159]
	s_add_i32 m0, s56, 0xc000
	ds_read_b128 v[184:187], v169
	ds_read_b128 v[188:191], v169 offset:1024
	ds_read_b128 v[192:195], v169 offset:2048
	ds_read_b128 v[196:199], v169 offset:3072
	ds_read_b128 v[200:203], v169 offset:4096
	ds_read_b128 v[204:207], v169 offset:5120
	ds_read_b128 v[208:211], v169 offset:6144
	ds_read_b128 v[212:215], v169 offset:7168
	global_load_lds_dwordx4 v[162:163], off
	v_lshl_add_u64 v[162:163], v[162:163], 0, s[12:13]
	s_add_i32 m0, s56, 0xe000
	s_nop 0
	global_load_lds_dwordx4 v[162:163], off
	s_waitcnt vmcnt(8)
	s_waitcnt lgkmcnt(0)
	s_barrier
	s_setprio 1
	s_waitcnt lgkmcnt(0)
	v_mfma_f32_16x16x32_bf16 v[138:141], v[114:117], v[184:187], v[138:141]
	v_mfma_f32_16x16x32_bf16 v[138:141], v[126:129], v[188:191], v[138:141]
	v_mfma_f32_16x16x32_bf16 v[134:137], v[142:145], v[188:191], v[134:137]
	v_mfma_f32_16x16x32_bf16 v[134:137], v[130:133], v[184:187], v[134:137]
	v_mfma_f32_16x16x32_bf16 v[106:109], v[130:133], v[192:195], v[106:109]
	v_mfma_f32_16x16x32_bf16 v[106:109], v[142:145], v[196:199], v[106:109]
	v_mfma_f32_16x16x32_bf16 v[110:113], v[126:129], v[196:199], v[110:113]
	v_mfma_f32_16x16x32_bf16 v[110:113], v[114:117], v[192:195], v[110:113]
	v_mfma_f32_16x16x32_bf16 v[94:97], v[114:117], v[200:203], v[94:97]
	v_mfma_f32_16x16x32_bf16 v[94:97], v[126:129], v[204:207], v[94:97]
	v_mfma_f32_16x16x32_bf16 v[90:93], v[142:145], v[204:207], v[90:93]
	v_mfma_f32_16x16x32_bf16 v[90:93], v[130:133], v[200:203], v[90:93]
	v_mfma_f32_16x16x32_bf16 v[74:77], v[130:133], v[208:211], v[74:77]
	v_mfma_f32_16x16x32_bf16 v[74:77], v[142:145], v[212:215], v[74:77]
	v_mfma_f32_16x16x32_bf16 v[78:81], v[126:129], v[212:215], v[78:81]
	v_mfma_f32_16x16x32_bf16 v[78:81], v[114:117], v[208:211], v[78:81]
	v_mfma_f32_16x16x32_bf16 v[122:125], v[146:149], v[184:187], v[122:125]
	v_mfma_f32_16x16x32_bf16 v[122:125], v[150:153], v[188:191], v[122:125]
	v_mfma_f32_16x16x32_bf16 v[118:121], v[178:181], v[188:191], v[118:121]
	v_mfma_f32_16x16x32_bf16 v[118:121], v[174:177], v[184:187], v[118:121]
	v_mfma_f32_16x16x32_bf16 v[98:101], v[174:177], v[192:195], v[98:101]
	v_mfma_f32_16x16x32_bf16 v[98:101], v[178:181], v[196:199], v[98:101]
	v_mfma_f32_16x16x32_bf16 v[102:105], v[150:153], v[196:199], v[102:105]
	v_mfma_f32_16x16x32_bf16 v[102:105], v[146:149], v[192:195], v[102:105]
	v_mfma_f32_16x16x32_bf16 v[86:89], v[146:149], v[200:203], v[86:89]
	v_mfma_f32_16x16x32_bf16 v[86:89], v[150:153], v[204:207], v[86:89]
	v_mfma_f32_16x16x32_bf16 v[82:85], v[178:181], v[204:207], v[82:85]
	v_mfma_f32_16x16x32_bf16 v[82:85], v[174:177], v[200:203], v[82:85]
	s_barrier
	s_setprio 2
	v_mfma_f32_16x16x32_bf16 v[66:69], v[174:177], v[208:211], v[66:69]
	v_mfma_f32_16x16x32_bf16 v[66:69], v[178:181], v[212:215], v[66:69]
	v_mfma_f32_16x16x32_bf16 v[70:73], v[150:153], v[212:215], v[70:73]
	v_mfma_f32_16x16x32_bf16 v[70:73], v[146:149], v[208:211], v[70:73]
	s_setprio 0
	s_add_i32 s39, s74, s55
	v_lshl_add_u64 v[162:163], s[80:81], 0, v[154:155]
	s_mov_b32 m0, s39
	ds_read_b128 v[184:187], v169 offset:16384
	ds_read_b128 v[188:191], v169 offset:17408
	ds_read_b128 v[192:195], v169 offset:18432
	ds_read_b128 v[196:199], v169 offset:19456
	ds_read_b128 v[200:203], v169 offset:20480
	ds_read_b128 v[204:207], v169 offset:21504
	ds_read_b128 v[208:211], v169 offset:22528
	ds_read_b128 v[212:215], v169 offset:23552
	global_load_lds_dwordx4 v[162:163], off
	v_lshl_add_u64 v[216:217], v[162:163], 0, s[12:13]
	s_add_i32 m0, s39, 0x2000
	s_add_i32 s39, s75, s55
	global_load_lds_dwordx4 v[216:217], off
	v_lshl_add_u64 v[216:217], v[162:163], 0, s[14:15]
	s_mov_b32 m0, s39
	s_nop 0
	global_load_lds_dwordx4 v[216:217], off
	v_lshl_add_u64 v[216:217], v[162:163], 0, s[16:17]
	s_add_i32 m0, s39, 0x2000
	s_nop 0
	global_load_lds_dwordx4 v[216:217], off
	v_lshl_add_u64 v[216:217], s[70:71], 0, v[154:155]
	s_mov_b32 m0, s56
	v_lshl_add_u64 v[218:219], v[216:217], 0, s[12:13]
	global_load_lds_dwordx4 v[216:217], off
	s_mov_b32 m0, s57
	s_nop 0
	global_load_lds_dwordx4 v[218:219], off
	s_waitcnt vmcnt(8)
	s_waitcnt lgkmcnt(0)
	s_barrier
; #define PG8_STAGE(bufoff, gbase, voff) do { if constexpr (!pg8_noload<Epi>::value) { _Pragma("unroll") for (int _i = 0; _i < 2; ++_i) \
;         __builtin_amdgcn_global_load_lds((const unsigned*)((const char*)(gbase) + (size_t)_i * pstep + (voff)[0]), (PG8_LAS unsigned*)(lds + (bufoff) + ldsw + _i * 8192), 16, 0, 0); } } while (0)
; #define PG8_LDA(dst, b, h) do { _Pragma("unroll") for (int m = 0; m < 4; ++m) _Pragma("unroll") for (int k = 0; k < 2; ++k) dst[m][k] = *(const PG8_LAS bf16x8*)(lds + PG8_SA(b, h) + aoff + m * 2048 + k * 1024); } while (0)
; #define PG8_LDB(dst, b, h) do { _Pragma("unroll") for (int n = 0; n < 2; ++n) _Pragma("unroll") for (int k = 0; k < 2; ++k) dst[n][k] = *(const PG8_LAS bf16x8*)(lds + PG8_SB(b, h) + boff + n * 2048 + k * 1024); } while (0)
; #define PG8_MMA(ai, bj, At, Bt) do { __builtin_amdgcn_s_setprio(1); _Pragma("unroll") for (int m = 0; m < 4; ++m) _Pragma("unroll") for (int n = 0; n < 2; ++n) _Pragma("unroll") for (int k = 0; k < 2; ++k) \
;         acc[ai][bj][m][n] = __builtin_amdgcn_mfma_f32_16x16x32_bf16(Bt[n][k], At[m][k], acc[ai][bj][m][n], 0, 0, 0); __builtin_amdgcn_s_setprio(0); } while (0)
; #define PG8_WAIT_V(n) asm volatile("s_waitcnt vmcnt(" #n ")" ::: "memory")
; #define PG8_WAIT_L(n) asm volatile("s_waitcnt lgkmcnt(" #n ")" ::: "memory")
; #define PG8_BAR __builtin_amdgcn_s_barrier()
; #define PG8_SCHED __builtin_amdgcn_sched_barrier(0)
; template <class Epi, class Sched, bool ALIGN_EPI = false, bool SP2 = false, bool ABLK = false>
; __device__ __forceinline__ void gemm_phase(PG8_LAS unsigned char* lds, const Gemm g, const Sched& S, const Epi& E) {
;     ...
;             PG8_WAIT_V(8); PG8_WAIT_L(0); PG8_BAR; PG8_MMA(1, 0, At, B0); PG8_MMA(1, 1, At, B1); PG8_BAR; PG8_SCHED;
;             PG8_LDB(B0, 1, 0); PG8_LDB(B1, 1, 1); PG8_SCHED; PG8_LDA(At, 1, 0); PG8_STAGE(PG8_SA(0, 1), a2 + hstep, voffA);
;             PG8_WAIT_V(8); PG8_WAIT_L(0); PG8_BAR; PG8_MMA(0, 0, At, B0); PG8_MMA(0, 1, At, B1); PG8_BAR; PG8_SCHED;
	s_setprio 1
	s_waitcnt lgkmcnt(0)
	v_mfma_f32_16x16x32_bf16 v[62:65], v[114:117], v[184:187], v[62:65]
	v_mfma_f32_16x16x32_bf16 v[62:65], v[126:129], v[188:191], v[62:65]
	v_mfma_f32_16x16x32_bf16 v[58:61], v[142:145], v[188:191], v[58:61]
	v_mfma_f32_16x16x32_bf16 v[58:61], v[130:133], v[184:187], v[58:61]
	v_mfma_f32_16x16x32_bf16 v[42:45], v[130:133], v[192:195], v[42:45]
	v_mfma_f32_16x16x32_bf16 v[42:45], v[142:145], v[196:199], v[42:45]
	v_mfma_f32_16x16x32_bf16 v[46:49], v[126:129], v[196:199], v[46:49]
	v_mfma_f32_16x16x32_bf16 v[46:49], v[114:117], v[192:195], v[46:49]
	v_mfma_f32_16x16x32_bf16 v[30:33], v[114:117], v[200:203], v[30:33]
	v_mfma_f32_16x16x32_bf16 v[30:33], v[126:129], v[204:207], v[30:33]
	v_mfma_f32_16x16x32_bf16 v[26:29], v[142:145], v[204:207], v[26:29]
	v_mfma_f32_16x16x32_bf16 v[26:29], v[130:133], v[200:203], v[26:29]
	v_mfma_f32_16x16x32_bf16 v[10:13], v[130:133], v[208:211], v[10:13]
	v_mfma_f32_16x16x32_bf16 v[10:13], v[142:145], v[212:215], v[10:13]
	v_mfma_f32_16x16x32_bf16 v[14:17], v[126:129], v[212:215], v[14:17]
	v_mfma_f32_16x16x32_bf16 v[14:17], v[114:117], v[208:211], v[14:17]
	v_mfma_f32_16x16x32_bf16 v[54:57], v[146:149], v[184:187], v[54:57]
	v_mfma_f32_16x16x32_bf16 v[54:57], v[150:153], v[188:191], v[54:57]
	v_mfma_f32_16x16x32_bf16 v[50:53], v[178:181], v[188:191], v[50:53]
	v_mfma_f32_16x16x32_bf16 v[50:53], v[174:177], v[184:187], v[50:53]
	v_mfma_f32_16x16x32_bf16 v[34:37], v[174:177], v[192:195], v[34:37]
	v_mfma_f32_16x16x32_bf16 v[34:37], v[178:181], v[196:199], v[34:37]
	v_mfma_f32_16x16x32_bf16 v[38:41], v[150:153], v[196:199], v[38:41]
	v_mfma_f32_16x16x32_bf16 v[38:41], v[146:149], v[192:195], v[38:41]
	v_mfma_f32_16x16x32_bf16 v[22:25], v[146:149], v[200:203], v[22:25]
	v_mfma_f32_16x16x32_bf16 v[22:25], v[150:153], v[204:207], v[22:25]
	v_mfma_f32_16x16x32_bf16 v[18:21], v[178:181], v[204:207], v[18:21]
	v_mfma_f32_16x16x32_bf16 v[18:21], v[174:177], v[200:203], v[18:21]
	s_barrier
	s_setprio 2
	v_mfma_f32_16x16x32_bf16 v[2:5], v[174:177], v[208:211], v[2:5]
	v_mfma_f32_16x16x32_bf16 v[2:5], v[178:181], v[212:215], v[2:5]
	v_mfma_f32_16x16x32_bf16 v[6:9], v[150:153], v[212:215], v[6:9]
	v_mfma_f32_16x16x32_bf16 v[6:9], v[146:149], v[208:211], v[6:9]
	s_setprio 0
	s_add_i32 s39, 0, 0x18000
	s_add_i32 s70, 0, 0x1c000
	v_add_u32_e32 v142, s39, v1
	v_add_u32_e32 v173, s70, v1
	ds_read_b128 v[114:117], v142
	ds_read_b128 v[126:129], v142 offset:1024
	ds_read_b128 v[130:133], v142 offset:2048
	ds_read_b128 v[142:145], v142 offset:3072
	ds_read_b128 v[146:149], v173
	ds_read_b128 v[150:153], v173 offset:1024
	ds_read_b128 v[174:177], v173 offset:2048
	ds_read_b128 v[178:181], v173 offset:3072
	s_mov_b32 m0, s58
	v_lshl_add_u64 v[218:219], v[216:217], 0, s[14:15]
	ds_read_b128 v[184:187], v169 offset:32768
	ds_read_b128 v[188:191], v169 offset:33792
	ds_read_b128 v[192:195], v169 offset:34816
	ds_read_b128 v[196:199], v169 offset:35840
	ds_read_b128 v[200:203], v169 offset:36864
	ds_read_b128 v[204:207], v169 offset:37888
	ds_read_b128 v[208:211], v169 offset:38912
	ds_read_b128 v[212:215], v169 offset:39936
	global_load_lds_dwordx4 v[218:219], off
	v_lshl_add_u64 v[218:219], v[216:217], 0, s[16:17]
	s_mov_b32 m0, s59
	s_nop 0
	global_load_lds_dwordx4 v[218:219], off
	s_waitcnt vmcnt(8)
	s_waitcnt lgkmcnt(0)
	s_barrier
	s_setprio 1
	s_waitcnt lgkmcnt(0)
	v_mfma_f32_16x16x32_bf16 v[138:141], v[114:117], v[184:187], v[138:141]
	v_mfma_f32_16x16x32_bf16 v[138:141], v[126:129], v[188:191], v[138:141]
	v_mfma_f32_16x16x32_bf16 v[134:137], v[142:145], v[188:191], v[134:137]
	v_mfma_f32_16x16x32_bf16 v[134:137], v[130:133], v[184:187], v[134:137]
	v_mfma_f32_16x16x32_bf16 v[106:109], v[130:133], v[192:195], v[106:109]
	v_mfma_f32_16x16x32_bf16 v[106:109], v[142:145], v[196:199], v[106:109]
	v_mfma_f32_16x16x32_bf16 v[110:113], v[126:129], v[196:199], v[110:113]
	v_mfma_f32_16x16x32_bf16 v[110:113], v[114:117], v[192:195], v[110:113]
	v_mfma_f32_16x16x32_bf16 v[94:97], v[114:117], v[200:203], v[94:97]
	v_mfma_f32_16x16x32_bf16 v[94:97], v[126:129], v[204:207], v[94:97]
	v_mfma_f32_16x16x32_bf16 v[90:93], v[142:145], v[204:207], v[90:93]
	v_mfma_f32_16x16x32_bf16 v[90:93], v[130:133], v[200:203], v[90:93]
	v_mfma_f32_16x16x32_bf16 v[74:77], v[130:133], v[208:211], v[74:77]
	v_mfma_f32_16x16x32_bf16 v[74:77], v[142:145], v[212:215], v[74:77]
	v_mfma_f32_16x16x32_bf16 v[78:81], v[126:129], v[212:215], v[78:81]
	v_mfma_f32_16x16x32_bf16 v[78:81], v[114:117], v[208:211], v[78:81]
	v_mfma_f32_16x16x32_bf16 v[122:125], v[146:149], v[184:187], v[122:125]
	v_mfma_f32_16x16x32_bf16 v[122:125], v[150:153], v[188:191], v[122:125]
	v_mfma_f32_16x16x32_bf16 v[118:121], v[178:181], v[188:191], v[118:121]
	v_mfma_f32_16x16x32_bf16 v[118:121], v[174:177], v[184:187], v[118:121]
	v_mfma_f32_16x16x32_bf16 v[98:101], v[174:177], v[192:195], v[98:101]
	v_mfma_f32_16x16x32_bf16 v[98:101], v[178:181], v[196:199], v[98:101]
	v_mfma_f32_16x16x32_bf16 v[102:105], v[150:153], v[196:199], v[102:105]
	v_mfma_f32_16x16x32_bf16 v[102:105], v[146:149], v[192:195], v[102:105]
	v_mfma_f32_16x16x32_bf16 v[86:89], v[146:149], v[200:203], v[86:89]
	v_mfma_f32_16x16x32_bf16 v[86:89], v[150:153], v[204:207], v[86:89]
	v_mfma_f32_16x16x32_bf16 v[82:85], v[178:181], v[204:207], v[82:85]
	v_mfma_f32_16x16x32_bf16 v[82:85], v[174:177], v[200:203], v[82:85]
	s_barrier
; #define PG8_STAGE(bufoff, gbase, voff) do { if constexpr (!pg8_noload<Epi>::value) { _Pragma("unroll") for (int _i = 0; _i < 2; ++_i) \
;         __builtin_amdgcn_global_load_lds((const unsigned*)((const char*)(gbase) + (size_t)_i * pstep + (voff)[0]), (PG8_LAS unsigned*)(lds + (bufoff) + ldsw + _i * 8192), 16, 0, 0); } } while (0)
; #define PG8_LDA(dst, b, h) do { _Pragma("unroll") for (int m = 0; m < 4; ++m) _Pragma("unroll") for (int k = 0; k < 2; ++k) dst[m][k] = *(const PG8_LAS bf16x8*)(lds + PG8_SA(b, h) + aoff + m * 2048 + k * 1024); } while (0)
; #define PG8_MMA(ai, bj, At, Bt) do { __builtin_amdgcn_s_setprio(1); _Pragma("unroll") for (int m = 0; m < 4; ++m) _Pragma("unroll") for (int n = 0; n < 2; ++n) _Pragma("unroll") for (int k = 0; k < 2; ++k) \
;         acc[ai][bj][m][n] = __builtin_amdgcn_mfma_f32_16x16x32_bf16(Bt[n][k], At[m][k], acc[ai][bj][m][n], 0, 0, 0); __builtin_amdgcn_s_setprio(0); } while (0)
; #define PG8_WAIT_V(n) asm volatile("s_waitcnt vmcnt(" #n ")" ::: "memory")
; #define PG8_WAIT_L(n) asm volatile("s_waitcnt lgkmcnt(" #n ")" ::: "memory")
; #define PG8_BAR __builtin_amdgcn_s_barrier()
; #define PG8_SCHED __builtin_amdgcn_sched_barrier(0)
; template <class Epi, class Sched, bool ALIGN_EPI = false, bool SP2 = false, bool ABLK = false>
; __device__ __forceinline__ void gemm_phase(PG8_LAS unsigned char* lds, const Gemm g, const Sched& S, const Epi& E) {
;     ...
;             PG8_WAIT_V(8); PG8_WAIT_L(0); PG8_BAR; PG8_MMA(0, 0, At, B0); PG8_MMA(0, 1, At, B1); PG8_BAR; PG8_SCHED;
;             PG8_LDA(At, 1, 1); PG8_STAGE(PG8_SB(1, 0), b3, voffB); PG8_STAGE(PG8_SB(1, 1), b3 + hstep, voffB); PG8_STAGE(PG8_SA(1, 0), a3, voffA);
;             PG8_WAIT_V(8); PG8_WAIT_L(0); PG8_BAR; PG8_MMA(1, 0, At, B0); PG8_MMA(1, 1, At, B1); PG8_BAR; PG8_SCHED;
	s_setprio 2
	v_mfma_f32_16x16x32_bf16 v[66:69], v[174:177], v[208:211], v[66:69]
	v_mfma_f32_16x16x32_bf16 v[66:69], v[178:181], v[212:215], v[66:69]
	v_mfma_f32_16x16x32_bf16 v[70:73], v[150:153], v[212:215], v[70:73]
	v_mfma_f32_16x16x32_bf16 v[70:73], v[146:149], v[208:211], v[70:73]
	s_setprio 0
	s_add_i32 s39, s39, s55
	v_lshl_add_u64 v[218:219], v[162:163], 0, s[24:25]
	s_mov_b32 m0, s39
	ds_read_b128 v[184:187], v169 offset:49152
	ds_read_b128 v[188:191], v169 offset:50176
	ds_read_b128 v[192:195], v169 offset:51200
	ds_read_b128 v[196:199], v169 offset:52224
	ds_read_b128 v[200:203], v169 offset:53248
	ds_read_b128 v[204:207], v169 offset:54272
	ds_read_b128 v[208:211], v169 offset:55296
	ds_read_b128 v[212:215], v169 offset:56320
	global_load_lds_dwordx4 v[218:219], off
	v_lshl_add_u64 v[218:219], v[162:163], 0, s[26:27]
	s_add_i32 m0, s39, 0x2000
	s_add_i32 s39, s70, s55
	global_load_lds_dwordx4 v[218:219], off
	v_lshl_add_u64 v[218:219], v[162:163], 0, s[28:29]
	s_mov_b32 m0, s39
	v_lshl_add_u64 v[162:163], v[162:163], 0, s[30:31]
	global_load_lds_dwordx4 v[218:219], off
	s_add_i32 m0, s39, 0x2000
	s_nop 0
	global_load_lds_dwordx4 v[162:163], off
	v_lshl_add_u64 v[162:163], v[216:217], 0, s[24:25]
	s_mov_b32 m0, s62
	s_nop 0
	global_load_lds_dwordx4 v[162:163], off
	v_lshl_add_u64 v[162:163], v[216:217], 0, s[26:27]
	s_mov_b32 m0, s63
	s_nop 0
	global_load_lds_dwordx4 v[162:163], off
	s_waitcnt vmcnt(8)
	s_waitcnt lgkmcnt(0)
	s_barrier
	s_setprio 1
	s_waitcnt lgkmcnt(0)
	v_mfma_f32_16x16x32_bf16 v[62:65], v[114:117], v[184:187], v[62:65]
	v_mfma_f32_16x16x32_bf16 v[62:65], v[126:129], v[188:191], v[62:65]
	v_mfma_f32_16x16x32_bf16 v[58:61], v[142:145], v[188:191], v[58:61]
	v_mfma_f32_16x16x32_bf16 v[58:61], v[130:133], v[184:187], v[58:61]
	v_mfma_f32_16x16x32_bf16 v[42:45], v[130:133], v[192:195], v[42:45]
	v_mfma_f32_16x16x32_bf16 v[42:45], v[142:145], v[196:199], v[42:45]
	v_mfma_f32_16x16x32_bf16 v[46:49], v[126:129], v[196:199], v[46:49]
	v_mfma_f32_16x16x32_bf16 v[46:49], v[114:117], v[192:195], v[46:49]
	v_mfma_f32_16x16x32_bf16 v[30:33], v[114:117], v[200:203], v[30:33]
	v_mfma_f32_16x16x32_bf16 v[30:33], v[126:129], v[204:207], v[30:33]
	v_mfma_f32_16x16x32_bf16 v[26:29], v[142:145], v[204:207], v[26:29]
	v_mfma_f32_16x16x32_bf16 v[26:29], v[130:133], v[200:203], v[26:29]
	v_mfma_f32_16x16x32_bf16 v[10:13], v[130:133], v[208:211], v[10:13]
	v_mfma_f32_16x16x32_bf16 v[10:13], v[142:145], v[212:215], v[10:13]
	v_mfma_f32_16x16x32_bf16 v[14:17], v[126:129], v[212:215], v[14:17]
	v_mfma_f32_16x16x32_bf16 v[14:17], v[114:117], v[208:211], v[14:17]
	v_mfma_f32_16x16x32_bf16 v[54:57], v[146:149], v[184:187], v[54:57]
	v_mfma_f32_16x16x32_bf16 v[54:57], v[150:153], v[188:191], v[54:57]
	v_mfma_f32_16x16x32_bf16 v[50:53], v[178:181], v[188:191], v[50:53]
	v_mfma_f32_16x16x32_bf16 v[50:53], v[174:177], v[184:187], v[50:53]
	v_mfma_f32_16x16x32_bf16 v[34:37], v[174:177], v[192:195], v[34:37]
	v_mfma_f32_16x16x32_bf16 v[34:37], v[178:181], v[196:199], v[34:37]
	v_mfma_f32_16x16x32_bf16 v[38:41], v[150:153], v[196:199], v[38:41]
	v_mfma_f32_16x16x32_bf16 v[38:41], v[146:149], v[192:195], v[38:41]
	v_mfma_f32_16x16x32_bf16 v[22:25], v[146:149], v[200:203], v[22:25]
	v_mfma_f32_16x16x32_bf16 v[22:25], v[150:153], v[204:207], v[22:25]
	v_mfma_f32_16x16x32_bf16 v[18:21], v[178:181], v[204:207], v[18:21]
	v_mfma_f32_16x16x32_bf16 v[18:21], v[174:177], v[200:203], v[18:21]
	s_barrier
	s_setprio 2
	v_mfma_f32_16x16x32_bf16 v[2:5], v[174:177], v[208:211], v[2:5]
	v_mfma_f32_16x16x32_bf16 v[2:5], v[178:181], v[212:215], v[2:5]
	v_mfma_f32_16x16x32_bf16 v[6:9], v[150:153], v[212:215], v[6:9]
	v_mfma_f32_16x16x32_bf16 v[6:9], v[146:149], v[208:211], v[6:9]
	s_setprio 0
	s_add_u32 s68, s68, 0x1000
	s_addc_u32 s69, s69, 0
	s_add_u32 s11, s11, 0x1000
	s_addc_u32 s37, s37, 0
	s_cmp_ge_i32 s41, s79
	s_mov_b32 s39, s41
	s_cbranch_scc0 .LBB0_1533
	s_and_b64 vcc, exec, s[34:35]
	s_cbranch_vccnz .LBB0_1538
	s_lshl_b32 s11, s2, 8
	s_cmp_gt_i32 s2, 63
	s_mov_b64 s[68:69], -1
	s_cbranch_scc1 .LBB0_1539

; #define PG8_STAGE(bufoff, gbase, voff) do { if constexpr (!pg8_noload<Epi>::value) { _Pragma("unroll") for (int _i = 0; _i < 2; ++_i) \
;         __builtin_amdgcn_global_load_lds((const unsigned*)((const char*)(gbase) + (size_t)_i * pstep + (voff)[0]), (PG8_LAS unsigned*)(lds + (bufoff) + ldsw + _i * 8192), 16, 0, 0); } } while (0)
; #define PG8_LDA(dst, b, h) do { _Pragma("unroll") for (int m = 0; m < 4; ++m) _Pragma("unroll") for (int k = 0; k < 2; ++k) dst[m][k] = *(const PG8_LAS bf16x8*)(lds + PG8_SA(b, h) + aoff + m * 2048 + k * 1024); } while (0)
; #define PG8_LDB(dst, b, h) do { _Pragma("unroll") for (int n = 0; n < 2; ++n) _Pragma("unroll") for (int k = 0; k < 2; ++k) dst[n][k] = *(const PG8_LAS bf16x8*)(lds + PG8_SB(b, h) + boff + n * 2048 + k * 1024); } while (0)
; #define PG8_MMA(ai, bj, At, Bt) do { __builtin_amdgcn_s_setprio(1); _Pragma("unroll") for (int m = 0; m < 4; ++m) _Pragma("unroll") for (int n = 0; n < 2; ++n) _Pragma("unroll") for (int k = 0; k < 2; ++k) \
;         acc[ai][bj][m][n] = __builtin_amdgcn_mfma_f32_16x16x32_bf16(Bt[n][k], At[m][k], acc[ai][bj][m][n], 0, 0, 0); __builtin_amdgcn_s_setprio(0); } while (0)
; #define PG8_BAR __builtin_amdgcn_s_barrier()
; template <class Epi, class Sched, bool ALIGN_EPI = false, bool SP2 = false, bool ABLK = false>
; __device__ __forceinline__ void gemm_phase(PG8_LAS unsigned char* lds, const Gemm g, const Sched& S, const Epi& E) {
;     ...
;         for (int t = 0; t < nt; t += 2) {
;             const bool last = (t == nt - 2);
;             const char* a1 = cA + (size_t)(t + 1) * kstep;
;             const char* a2 = last ? nA : cA + (size_t)(t + 2) * kstep; const char* b2 = last ? nB : cB + (size_t)(t + 2) * kstepB;
;             const char* a3 = a2 + kstep; const char* b3 = b2 + kstepB;
;             if (last && has_next) S.a_ready(nxt);
;             if constexpr (SP2) {
;             PG8_LDB(B0, 0, 0); PG8_LDB(B1, 0, 1); PG8_SCHED; PG8_LDA(At, 0, 0); PG8_STAGE(PG8_SA(1, 1), a1 + hstep, voffA);
;             PG8_WAIT_V(8); PG8_WAIT_L(0); PG8_BAR; PG8_MMA(0, 0, At, B0); PG8_MMA(0, 1, At, B1); PG8_BAR; PG8_SCHED;
;             PG8_LDA(At, 0, 1); PG8_STAGE(PG8_SB(0, 0), b2, voffB); PG8_STAGE(PG8_SB(0, 1), b2 + hstep, voffB); PG8_STAGE(PG8_SA(0, 0), a2, voffA);
;             PG8_WAIT_V(8); PG8_WAIT_L(0); PG8_BAR; PG8_MMA(1, 0, At, B0); PG8_MMA(1, 1, At, B1); PG8_BAR; PG8_SCHED;
.LBB0_1657:
	s_or_b32 s26, s94, 1
	s_lshl_b64 s[82:83], s[26:27], 11
	s_add_u32 s88, s74, s82
	v_add_u32_e32 v140, s12, v173
	s_addc_u32 s89, s75, s83
	s_add_i32 s26, s94, 2
	ds_read_b128 v[130:133], v140
	ds_read_b128 v[134:137], v140 offset:1024
	ds_read_b128 v[154:157], v140 offset:2048
	ds_read_b128 v[158:161], v140 offset:3072
	v_add_u32_e32 v140, s13, v173
	s_lshl_b64 s[90:91], s[26:27], 11
	ds_read_b128 v[162:165], v140
	ds_read_b128 v[166:169], v140 offset:1024
	ds_read_b128 v[184:187], v140 offset:2048
	ds_read_b128 v[188:191], v140 offset:3072
	s_add_u32 s92, s74, s90
	s_addc_u32 s93, s75, s91
	s_and_b64 s[82:83], s[80:81], exec
	s_cselect_b32 s83, s93, s3
	s_cselect_b32 s82, s92, s25
	s_add_u32 s90, s76, s90
	s_addc_u32 s91, s77, s91
	s_and_b64 s[80:81], s[80:81], exec
	s_cselect_b32 s81, s91, s65
	s_cselect_b32 s80, s90, s67
	v_lshl_add_u64 v[170:171], s[88:89], 0, v[138:139]
	v_lshl_add_u64 v[224:225], v[170:171], 0, s[20:21]
	s_add_i32 m0, s56, 0xc000
	ds_read_b128 v[192:195], v178
	ds_read_b128 v[196:199], v178 offset:1024
	ds_read_b128 v[200:203], v178 offset:2048
	ds_read_b128 v[204:207], v178 offset:3072
	ds_read_b128 v[208:211], v178 offset:4096
	ds_read_b128 v[212:215], v178 offset:5120
	ds_read_b128 v[216:219], v178 offset:6144
	ds_read_b128 v[220:223], v178 offset:7168
	global_load_lds_dwordx4 v[224:225], off
	v_lshl_add_u64 v[170:171], v[170:171], 0, s[22:23]
	s_add_i32 m0, s56, 0xe000
	s_nop 0
	global_load_lds_dwordx4 v[170:171], off
	s_waitcnt vmcnt(8)
	s_waitcnt lgkmcnt(0)
	s_barrier
	s_setprio 1
	s_waitcnt lgkmcnt(0)
	v_mfma_f32_16x16x32_bf16 v[126:129], v[130:133], v[192:195], v[126:129]
	v_mfma_f32_16x16x32_bf16 v[126:129], v[134:137], v[196:199], v[126:129]
	v_mfma_f32_16x16x32_bf16 v[122:125], v[158:161], v[196:199], v[122:125]
	v_mfma_f32_16x16x32_bf16 v[122:125], v[154:157], v[192:195], v[122:125]
	v_mfma_f32_16x16x32_bf16 v[106:109], v[154:157], v[200:203], v[106:109]
	v_mfma_f32_16x16x32_bf16 v[106:109], v[158:161], v[204:207], v[106:109]
	v_mfma_f32_16x16x32_bf16 v[110:113], v[134:137], v[204:207], v[110:113]
	v_mfma_f32_16x16x32_bf16 v[110:113], v[130:133], v[200:203], v[110:113]
	v_mfma_f32_16x16x32_bf16 v[94:97], v[130:133], v[208:211], v[94:97]
	v_mfma_f32_16x16x32_bf16 v[94:97], v[134:137], v[212:215], v[94:97]
	v_mfma_f32_16x16x32_bf16 v[90:93], v[158:161], v[212:215], v[90:93]
	v_mfma_f32_16x16x32_bf16 v[90:93], v[154:157], v[208:211], v[90:93]
	v_mfma_f32_16x16x32_bf16 v[74:77], v[154:157], v[216:219], v[74:77]
	v_mfma_f32_16x16x32_bf16 v[74:77], v[158:161], v[220:223], v[74:77]
	v_mfma_f32_16x16x32_bf16 v[78:81], v[134:137], v[220:223], v[78:81]
	v_mfma_f32_16x16x32_bf16 v[78:81], v[130:133], v[216:219], v[78:81]
	v_mfma_f32_16x16x32_bf16 v[118:121], v[162:165], v[192:195], v[118:121]
	v_mfma_f32_16x16x32_bf16 v[118:121], v[166:169], v[196:199], v[118:121]
	v_mfma_f32_16x16x32_bf16 v[114:117], v[188:191], v[196:199], v[114:117]
	v_mfma_f32_16x16x32_bf16 v[114:117], v[184:187], v[192:195], v[114:117]
	v_mfma_f32_16x16x32_bf16 v[98:101], v[184:187], v[200:203], v[98:101]
	v_mfma_f32_16x16x32_bf16 v[98:101], v[188:191], v[204:207], v[98:101]
	v_mfma_f32_16x16x32_bf16 v[102:105], v[166:169], v[204:207], v[102:105]
	v_mfma_f32_16x16x32_bf16 v[102:105], v[162:165], v[200:203], v[102:105]
	v_mfma_f32_16x16x32_bf16 v[86:89], v[162:165], v[208:211], v[86:89]
	v_mfma_f32_16x16x32_bf16 v[86:89], v[166:169], v[212:215], v[86:89]
	v_mfma_f32_16x16x32_bf16 v[82:85], v[188:191], v[212:215], v[82:85]
	v_mfma_f32_16x16x32_bf16 v[82:85], v[184:187], v[208:211], v[82:85]
	s_barrier
	s_setprio 2
	v_mfma_f32_16x16x32_bf16 v[66:69], v[184:187], v[216:219], v[66:69]
	v_mfma_f32_16x16x32_bf16 v[66:69], v[188:191], v[220:223], v[66:69]
	v_mfma_f32_16x16x32_bf16 v[70:73], v[166:169], v[220:223], v[70:73]
	v_mfma_f32_16x16x32_bf16 v[70:73], v[162:165], v[216:219], v[70:73]
	s_setprio 0
	v_lshl_add_u64 v[170:171], s[80:81], 0, v[138:139]
	s_add_i32 s80, s12, s55
	s_mov_b32 m0, s80
	ds_read_b128 v[192:195], v178 offset:16384
	ds_read_b128 v[196:199], v178 offset:17408
	ds_read_b128 v[200:203], v178 offset:18432
	ds_read_b128 v[204:207], v178 offset:19456
	ds_read_b128 v[208:211], v178 offset:20480
	ds_read_b128 v[212:215], v178 offset:21504
	ds_read_b128 v[216:219], v178 offset:22528
	ds_read_b128 v[220:223], v178 offset:23552
	global_load_lds_dwordx4 v[170:171], off
	v_lshl_add_u64 v[224:225], v[170:171], 0, s[18:19]
	s_add_i32 m0, s80, 0x2000
	s_add_i32 s80, s13, s55
	global_load_lds_dwordx4 v[224:225], off
	v_lshl_add_u64 v[224:225], v[170:171], 0, s[20:21]
	s_mov_b32 m0, s80
	s_nop 0
	global_load_lds_dwordx4 v[224:225], off
	v_lshl_add_u64 v[224:225], v[170:171], 0, s[22:23]
	s_add_i32 m0, s80, 0x2000
	s_nop 0
	global_load_lds_dwordx4 v[224:225], off
	v_lshl_add_u64 v[224:225], s[82:83], 0, v[138:139]
	s_mov_b32 m0, s56
	v_lshl_add_u64 v[226:227], v[224:225], 0, s[18:19]
	global_load_lds_dwordx4 v[224:225], off
	s_mov_b32 m0, s57
	s_nop 0
	global_load_lds_dwordx4 v[226:227], off
	s_waitcnt vmcnt(8)
	s_waitcnt lgkmcnt(0)
	s_barrier
; #define PG8_STAGE(bufoff, gbase, voff) do { if constexpr (!pg8_noload<Epi>::value) { _Pragma("unroll") for (int _i = 0; _i < 2; ++_i) \
;         __builtin_amdgcn_global_load_lds((const unsigned*)((const char*)(gbase) + (size_t)_i * pstep + (voff)[0]), (PG8_LAS unsigned*)(lds + (bufoff) + ldsw + _i * 8192), 16, 0, 0); } } while (0)
; #define PG8_LDA(dst, b, h) do { _Pragma("unroll") for (int m = 0; m < 4; ++m) _Pragma("unroll") for (int k = 0; k < 2; ++k) dst[m][k] = *(const PG8_LAS bf16x8*)(lds + PG8_SA(b, h) + aoff + m * 2048 + k * 1024); } while (0)
; #define PG8_LDB(dst, b, h) do { _Pragma("unroll") for (int n = 0; n < 2; ++n) _Pragma("unroll") for (int k = 0; k < 2; ++k) dst[n][k] = *(const PG8_LAS bf16x8*)(lds + PG8_SB(b, h) + boff + n * 2048 + k * 1024); } while (0)
; #define PG8_MMA(ai, bj, At, Bt) do { __builtin_amdgcn_s_setprio(1); _Pragma("unroll") for (int m = 0; m < 4; ++m) _Pragma("unroll") for (int n = 0; n < 2; ++n) _Pragma("unroll") for (int k = 0; k < 2; ++k) \
;         acc[ai][bj][m][n] = __builtin_amdgcn_mfma_f32_16x16x32_bf16(Bt[n][k], At[m][k], acc[ai][bj][m][n], 0, 0, 0); __builtin_amdgcn_s_setprio(0); } while (0)
; #define PG8_WAIT_V(n) asm volatile("s_waitcnt vmcnt(" #n ")" ::: "memory")
; #define PG8_WAIT_L(n) asm volatile("s_waitcnt lgkmcnt(" #n ")" ::: "memory")
; #define PG8_BAR __builtin_amdgcn_s_barrier()
; #define PG8_SCHED __builtin_amdgcn_sched_barrier(0)
; template <class Epi, class Sched, bool ALIGN_EPI = false, bool SP2 = false, bool ABLK = false>
; __device__ __forceinline__ void gemm_phase(PG8_LAS unsigned char* lds, const Gemm g, const Sched& S, const Epi& E) {
;     ...
;             PG8_WAIT_V(8); PG8_WAIT_L(0); PG8_BAR; PG8_MMA(1, 0, At, B0); PG8_MMA(1, 1, At, B1); PG8_BAR; PG8_SCHED;
;             PG8_LDB(B0, 1, 0); PG8_LDB(B1, 1, 1); PG8_SCHED; PG8_LDA(At, 1, 0); PG8_STAGE(PG8_SA(0, 1), a2 + hstep, voffA);
;             PG8_WAIT_V(8); PG8_WAIT_L(0); PG8_BAR; PG8_MMA(0, 0, At, B0); PG8_MMA(0, 1, At, B1); PG8_BAR; PG8_SCHED;
	s_setprio 1
	s_waitcnt lgkmcnt(0)
	v_mfma_f32_16x16x32_bf16 v[62:65], v[130:133], v[192:195], v[62:65]
	v_mfma_f32_16x16x32_bf16 v[62:65], v[134:137], v[196:199], v[62:65]
	v_mfma_f32_16x16x32_bf16 v[58:61], v[158:161], v[196:199], v[58:61]
	v_mfma_f32_16x16x32_bf16 v[58:61], v[154:157], v[192:195], v[58:61]
	v_mfma_f32_16x16x32_bf16 v[42:45], v[154:157], v[200:203], v[42:45]
	v_mfma_f32_16x16x32_bf16 v[42:45], v[158:161], v[204:207], v[42:45]
	v_mfma_f32_16x16x32_bf16 v[46:49], v[134:137], v[204:207], v[46:49]
	v_mfma_f32_16x16x32_bf16 v[46:49], v[130:133], v[200:203], v[46:49]
	v_mfma_f32_16x16x32_bf16 v[30:33], v[130:133], v[208:211], v[30:33]
	v_mfma_f32_16x16x32_bf16 v[30:33], v[134:137], v[212:215], v[30:33]
	v_mfma_f32_16x16x32_bf16 v[26:29], v[158:161], v[212:215], v[26:29]
	v_mfma_f32_16x16x32_bf16 v[26:29], v[154:157], v[208:211], v[26:29]
	v_mfma_f32_16x16x32_bf16 v[10:13], v[154:157], v[216:219], v[10:13]
	v_mfma_f32_16x16x32_bf16 v[10:13], v[158:161], v[220:223], v[10:13]
	v_mfma_f32_16x16x32_bf16 v[14:17], v[134:137], v[220:223], v[14:17]
	v_mfma_f32_16x16x32_bf16 v[14:17], v[130:133], v[216:219], v[14:17]
	v_mfma_f32_16x16x32_bf16 v[54:57], v[162:165], v[192:195], v[54:57]
	v_mfma_f32_16x16x32_bf16 v[54:57], v[166:169], v[196:199], v[54:57]
	v_mfma_f32_16x16x32_bf16 v[50:53], v[188:191], v[196:199], v[50:53]
	v_mfma_f32_16x16x32_bf16 v[50:53], v[184:187], v[192:195], v[50:53]
	v_mfma_f32_16x16x32_bf16 v[34:37], v[184:187], v[200:203], v[34:37]
	v_mfma_f32_16x16x32_bf16 v[34:37], v[188:191], v[204:207], v[34:37]
	v_mfma_f32_16x16x32_bf16 v[38:41], v[166:169], v[204:207], v[38:41]
	v_mfma_f32_16x16x32_bf16 v[38:41], v[162:165], v[200:203], v[38:41]
	v_mfma_f32_16x16x32_bf16 v[22:25], v[162:165], v[208:211], v[22:25]
	v_mfma_f32_16x16x32_bf16 v[22:25], v[166:169], v[212:215], v[22:25]
	v_mfma_f32_16x16x32_bf16 v[18:21], v[188:191], v[212:215], v[18:21]
	v_mfma_f32_16x16x32_bf16 v[18:21], v[184:187], v[208:211], v[18:21]
	s_barrier
	s_setprio 2
	v_mfma_f32_16x16x32_bf16 v[2:5], v[184:187], v[216:219], v[2:5]
	v_mfma_f32_16x16x32_bf16 v[2:5], v[188:191], v[220:223], v[2:5]
	v_mfma_f32_16x16x32_bf16 v[6:9], v[166:169], v[220:223], v[6:9]
	v_mfma_f32_16x16x32_bf16 v[6:9], v[162:165], v[216:219], v[6:9]
	s_setprio 0
	s_add_i32 s80, 0, 0x18000
	v_add_u32_e32 v140, s80, v173
	s_add_i32 s81, 0, 0x1c000
	ds_read_b128 v[130:133], v140
	ds_read_b128 v[134:137], v140 offset:1024
	ds_read_b128 v[154:157], v140 offset:2048
	ds_read_b128 v[158:161], v140 offset:3072
	v_add_u32_e32 v140, s81, v173
	ds_read_b128 v[162:165], v140
	ds_read_b128 v[166:169], v140 offset:1024
	ds_read_b128 v[184:187], v140 offset:2048
	ds_read_b128 v[188:191], v140 offset:3072
	s_mov_b32 m0, s58
	v_lshl_add_u64 v[226:227], v[224:225], 0, s[20:21]
	ds_read_b128 v[192:195], v178 offset:32768
	ds_read_b128 v[196:199], v178 offset:33792
	ds_read_b128 v[200:203], v178 offset:34816
	ds_read_b128 v[204:207], v178 offset:35840
	ds_read_b128 v[208:211], v178 offset:36864
	ds_read_b128 v[212:215], v178 offset:37888
	ds_read_b128 v[216:219], v178 offset:38912
	ds_read_b128 v[220:223], v178 offset:39936
	global_load_lds_dwordx4 v[226:227], off
	v_lshl_add_u64 v[226:227], v[224:225], 0, s[22:23]
	s_mov_b32 m0, s59
	s_nop 0
	global_load_lds_dwordx4 v[226:227], off
	s_waitcnt vmcnt(8)
	s_waitcnt lgkmcnt(0)
	s_barrier
	s_setprio 1
	s_waitcnt lgkmcnt(0)
	v_mfma_f32_16x16x32_bf16 v[126:129], v[130:133], v[192:195], v[126:129]
	v_mfma_f32_16x16x32_bf16 v[126:129], v[134:137], v[196:199], v[126:129]
	v_mfma_f32_16x16x32_bf16 v[122:125], v[158:161], v[196:199], v[122:125]
	v_mfma_f32_16x16x32_bf16 v[122:125], v[154:157], v[192:195], v[122:125]
	v_mfma_f32_16x16x32_bf16 v[106:109], v[154:157], v[200:203], v[106:109]
	v_mfma_f32_16x16x32_bf16 v[106:109], v[158:161], v[204:207], v[106:109]
	v_mfma_f32_16x16x32_bf16 v[110:113], v[134:137], v[204:207], v[110:113]
	v_mfma_f32_16x16x32_bf16 v[110:113], v[130:133], v[200:203], v[110:113]
	v_mfma_f32_16x16x32_bf16 v[94:97], v[130:133], v[208:211], v[94:97]
	v_mfma_f32_16x16x32_bf16 v[94:97], v[134:137], v[212:215], v[94:97]
	v_mfma_f32_16x16x32_bf16 v[90:93], v[158:161], v[212:215], v[90:93]
	v_mfma_f32_16x16x32_bf16 v[90:93], v[154:157], v[208:211], v[90:93]
	v_mfma_f32_16x16x32_bf16 v[74:77], v[154:157], v[216:219], v[74:77]
	v_mfma_f32_16x16x32_bf16 v[74:77], v[158:161], v[220:223], v[74:77]
	v_mfma_f32_16x16x32_bf16 v[78:81], v[134:137], v[220:223], v[78:81]
	v_mfma_f32_16x16x32_bf16 v[78:81], v[130:133], v[216:219], v[78:81]
	v_mfma_f32_16x16x32_bf16 v[118:121], v[162:165], v[192:195], v[118:121]
	v_mfma_f32_16x16x32_bf16 v[118:121], v[166:169], v[196:199], v[118:121]
	v_mfma_f32_16x16x32_bf16 v[114:117], v[188:191], v[196:199], v[114:117]
	v_mfma_f32_16x16x32_bf16 v[114:117], v[184:187], v[192:195], v[114:117]
	v_mfma_f32_16x16x32_bf16 v[98:101], v[184:187], v[200:203], v[98:101]
	v_mfma_f32_16x16x32_bf16 v[98:101], v[188:191], v[204:207], v[98:101]
	v_mfma_f32_16x16x32_bf16 v[102:105], v[166:169], v[204:207], v[102:105]
	v_mfma_f32_16x16x32_bf16 v[102:105], v[162:165], v[200:203], v[102:105]
	v_mfma_f32_16x16x32_bf16 v[86:89], v[162:165], v[208:211], v[86:89]
	v_mfma_f32_16x16x32_bf16 v[86:89], v[166:169], v[212:215], v[86:89]
	v_mfma_f32_16x16x32_bf16 v[82:85], v[188:191], v[212:215], v[82:85]
	v_mfma_f32_16x16x32_bf16 v[82:85], v[184:187], v[208:211], v[82:85]
	s_barrier
; #define PG8_STAGE(bufoff, gbase, voff) do { if constexpr (!pg8_noload<Epi>::value) { _Pragma("unroll") for (int _i = 0; _i < 2; ++_i) \
;         __builtin_amdgcn_global_load_lds((const unsigned*)((const char*)(gbase) + (size_t)_i * pstep + (voff)[0]), (PG8_LAS unsigned*)(lds + (bufoff) + ldsw + _i * 8192), 16, 0, 0); } } while (0)
; #define PG8_LDA(dst, b, h) do { _Pragma("unroll") for (int m = 0; m < 4; ++m) _Pragma("unroll") for (int k = 0; k < 2; ++k) dst[m][k] = *(const PG8_LAS bf16x8*)(lds + PG8_SA(b, h) + aoff + m * 2048 + k * 1024); } while (0)
; #define PG8_MMA(ai, bj, At, Bt) do { __builtin_amdgcn_s_setprio(1); _Pragma("unroll") for (int m = 0; m < 4; ++m) _Pragma("unroll") for (int n = 0; n < 2; ++n) _Pragma("unroll") for (int k = 0; k < 2; ++k) \
;         acc[ai][bj][m][n] = __builtin_amdgcn_mfma_f32_16x16x32_bf16(Bt[n][k], At[m][k], acc[ai][bj][m][n], 0, 0, 0); __builtin_amdgcn_s_setprio(0); } while (0)
; #define PG8_WAIT_V(n) asm volatile("s_waitcnt vmcnt(" #n ")" ::: "memory")
; #define PG8_WAIT_L(n) asm volatile("s_waitcnt lgkmcnt(" #n ")" ::: "memory")
; #define PG8_BAR __builtin_amdgcn_s_barrier()
; #define PG8_SCHED __builtin_amdgcn_sched_barrier(0)
; template <class Epi, class Sched, bool ALIGN_EPI = false, bool SP2 = false, bool ABLK = false>
; __device__ __forceinline__ void gemm_phase(PG8_LAS unsigned char* lds, const Gemm g, const Sched& S, const Epi& E) {
;     ...
;             PG8_WAIT_V(8); PG8_WAIT_L(0); PG8_BAR; PG8_MMA(0, 0, At, B0); PG8_MMA(0, 1, At, B1); PG8_BAR; PG8_SCHED;
;             PG8_LDA(At, 1, 1); PG8_STAGE(PG8_SB(1, 0), b3, voffB); PG8_STAGE(PG8_SB(1, 1), b3 + hstep, voffB); PG8_STAGE(PG8_SA(1, 0), a3, voffA);
;             PG8_WAIT_V(8); PG8_WAIT_L(0); PG8_BAR; PG8_MMA(1, 0, At, B0); PG8_MMA(1, 1, At, B1); PG8_BAR; PG8_SCHED;
	s_setprio 2
	v_mfma_f32_16x16x32_bf16 v[66:69], v[184:187], v[216:219], v[66:69]
	v_mfma_f32_16x16x32_bf16 v[66:69], v[188:191], v[220:223], v[66:69]
	v_mfma_f32_16x16x32_bf16 v[70:73], v[166:169], v[220:223], v[70:73]
	v_mfma_f32_16x16x32_bf16 v[70:73], v[162:165], v[216:219], v[70:73]
	s_setprio 0
	s_add_i32 s80, s80, s55
	v_lshl_add_u64 v[226:227], v[170:171], 0, s[30:31]
	s_mov_b32 m0, s80
	ds_read_b128 v[192:195], v178 offset:49152
	ds_read_b128 v[196:199], v178 offset:50176
	ds_read_b128 v[200:203], v178 offset:51200
	ds_read_b128 v[204:207], v178 offset:52224
	ds_read_b128 v[208:211], v178 offset:53248
	ds_read_b128 v[212:215], v178 offset:54272
	ds_read_b128 v[216:219], v178 offset:55296
	ds_read_b128 v[220:223], v178 offset:56320
	global_load_lds_dwordx4 v[226:227], off
	v_lshl_add_u64 v[226:227], v[170:171], 0, s[34:35]
	s_add_i32 m0, s80, 0x2000
	s_add_i32 s80, s81, s55
	global_load_lds_dwordx4 v[226:227], off
	v_lshl_add_u64 v[226:227], v[170:171], 0, s[36:37]
	s_mov_b32 m0, s80
	v_lshl_add_u64 v[170:171], v[170:171], 0, s[38:39]
	global_load_lds_dwordx4 v[226:227], off
	s_add_i32 m0, s80, 0x2000
	s_nop 0
	global_load_lds_dwordx4 v[170:171], off
	v_lshl_add_u64 v[170:171], v[224:225], 0, s[30:31]
	s_mov_b32 m0, s63
	s_nop 0
	global_load_lds_dwordx4 v[170:171], off
	v_lshl_add_u64 v[170:171], v[224:225], 0, s[34:35]
	s_mov_b32 m0, s73
	s_nop 0
	global_load_lds_dwordx4 v[170:171], off
	s_waitcnt vmcnt(8)
	s_waitcnt lgkmcnt(0)
	s_barrier
	s_setprio 1
	s_waitcnt lgkmcnt(0)
	v_mfma_f32_16x16x32_bf16 v[62:65], v[130:133], v[192:195], v[62:65]
	v_mfma_f32_16x16x32_bf16 v[62:65], v[134:137], v[196:199], v[62:65]
	v_mfma_f32_16x16x32_bf16 v[58:61], v[158:161], v[196:199], v[58:61]
	v_mfma_f32_16x16x32_bf16 v[58:61], v[154:157], v[192:195], v[58:61]
	v_mfma_f32_16x16x32_bf16 v[42:45], v[154:157], v[200:203], v[42:45]
	v_mfma_f32_16x16x32_bf16 v[42:45], v[158:161], v[204:207], v[42:45]
	v_mfma_f32_16x16x32_bf16 v[46:49], v[134:137], v[204:207], v[46:49]
	v_mfma_f32_16x16x32_bf16 v[46:49], v[130:133], v[200:203], v[46:49]
	v_mfma_f32_16x16x32_bf16 v[30:33], v[130:133], v[208:211], v[30:33]
	v_mfma_f32_16x16x32_bf16 v[30:33], v[134:137], v[212:215], v[30:33]
	v_mfma_f32_16x16x32_bf16 v[26:29], v[158:161], v[212:215], v[26:29]
	v_mfma_f32_16x16x32_bf16 v[26:29], v[154:157], v[208:211], v[26:29]
	v_mfma_f32_16x16x32_bf16 v[10:13], v[154:157], v[216:219], v[10:13]
	v_mfma_f32_16x16x32_bf16 v[10:13], v[158:161], v[220:223], v[10:13]
	v_mfma_f32_16x16x32_bf16 v[14:17], v[134:137], v[220:223], v[14:17]
	v_mfma_f32_16x16x32_bf16 v[14:17], v[130:133], v[216:219], v[14:17]
	v_mfma_f32_16x16x32_bf16 v[54:57], v[162:165], v[192:195], v[54:57]
	v_mfma_f32_16x16x32_bf16 v[54:57], v[166:169], v[196:199], v[54:57]
	v_mfma_f32_16x16x32_bf16 v[50:53], v[188:191], v[196:199], v[50:53]
	v_mfma_f32_16x16x32_bf16 v[50:53], v[184:187], v[192:195], v[50:53]
	v_mfma_f32_16x16x32_bf16 v[34:37], v[184:187], v[200:203], v[34:37]
	v_mfma_f32_16x16x32_bf16 v[34:37], v[188:191], v[204:207], v[34:37]
	v_mfma_f32_16x16x32_bf16 v[38:41], v[166:169], v[204:207], v[38:41]
	v_mfma_f32_16x16x32_bf16 v[38:41], v[162:165], v[200:203], v[38:41]
	v_mfma_f32_16x16x32_bf16 v[22:25], v[162:165], v[208:211], v[22:25]
	v_mfma_f32_16x16x32_bf16 v[22:25], v[166:169], v[212:215], v[22:25]
	v_mfma_f32_16x16x32_bf16 v[18:21], v[188:191], v[212:215], v[18:21]
	v_mfma_f32_16x16x32_bf16 v[18:21], v[184:187], v[208:211], v[18:21]
	s_barrier
	s_setprio 2
	v_mfma_f32_16x16x32_bf16 v[2:5], v[184:187], v[216:219], v[2:5]
	v_mfma_f32_16x16x32_bf16 v[2:5], v[188:191], v[220:223], v[2:5]
	v_mfma_f32_16x16x32_bf16 v[6:9], v[166:169], v[220:223], v[6:9]
	v_mfma_f32_16x16x32_bf16 v[6:9], v[162:165], v[216:219], v[6:9]
	s_setprio 0
	s_cmp_gt_u32 s94, 29
	s_mov_b32 s94, s26
	s_cbranch_scc1 .LBB0_1669

; #define PG8_STAGE(bufoff, gbase, voff) do { if constexpr (!pg8_noload<Epi>::value) { _Pragma("unroll") for (int _i = 0; _i < 2; ++_i) \
;         __builtin_amdgcn_global_load_lds((const unsigned*)((const char*)(gbase) + (size_t)_i * pstep + (voff)[0]), (PG8_LAS unsigned*)(lds + (bufoff) + ldsw + _i * 8192), 16, 0, 0); } } while (0)
; #define PG8_LDA(dst, b, h) do { _Pragma("unroll") for (int m = 0; m < 4; ++m) _Pragma("unroll") for (int k = 0; k < 2; ++k) dst[m][k] = *(const PG8_LAS bf16x8*)(lds + PG8_SA(b, h) + aoff + m * 2048 + k * 1024); } while (0)
; #define PG8_LDB(dst, b, h) do { _Pragma("unroll") for (int n = 0; n < 2; ++n) _Pragma("unroll") for (int k = 0; k < 2; ++k) dst[n][k] = *(const PG8_LAS bf16x8*)(lds + PG8_SB(b, h) + boff + n * 2048 + k * 1024); } while (0)
; #define PG8_MMA(ai, bj, At, Bt) do { __builtin_amdgcn_s_setprio(1); _Pragma("unroll") for (int m = 0; m < 4; ++m) _Pragma("unroll") for (int n = 0; n < 2; ++n) _Pragma("unroll") for (int k = 0; k < 2; ++k) \
;         acc[ai][bj][m][n] = __builtin_amdgcn_mfma_f32_16x16x32_bf16(Bt[n][k], At[m][k], acc[ai][bj][m][n], 0, 0, 0); __builtin_amdgcn_s_setprio(0); } while (0)
; #define PG8_BAR __builtin_amdgcn_s_barrier()
; template <class Epi, class Sched, bool ALIGN_EPI = false, bool SP2 = false, bool ABLK = false>
; __device__ __forceinline__ void gemm_phase(PG8_LAS unsigned char* lds, const Gemm g, const Sched& S, const Epi& E) {
;     ...
;         for (int t = 0; t < nt; t += 2) {
;             const bool last = (t == nt - 2);
;             const char* a1 = cA + (size_t)(t + 1) * kstep;
;             const char* a2 = last ? nA : cA + (size_t)(t + 2) * kstep; const char* b2 = last ? nB : cB + (size_t)(t + 2) * kstepB;
;             const char* a3 = a2 + kstep; const char* b3 = b2 + kstepB;
;             if (last && has_next) S.a_ready(nxt);
;             if constexpr (SP2) {
;             PG8_LDB(B0, 0, 0); PG8_LDB(B1, 0, 1); PG8_SCHED; PG8_LDA(At, 0, 0); PG8_STAGE(PG8_SA(1, 1), a1 + hstep, voffA);
;             PG8_WAIT_V(8); PG8_WAIT_L(0); PG8_BAR; PG8_MMA(0, 0, At, B0); PG8_MMA(0, 1, At, B1); PG8_BAR; PG8_SCHED;
;             PG8_LDA(At, 0, 1); PG8_STAGE(PG8_SB(0, 0), b2, voffB); PG8_STAGE(PG8_SB(0, 1), b2 + hstep, voffB); PG8_STAGE(PG8_SA(0, 0), a2, voffA);
;             PG8_WAIT_V(8); PG8_WAIT_L(0); PG8_BAR; PG8_MMA(1, 0, At, B0); PG8_MMA(1, 1, At, B1); PG8_BAR; PG8_SCHED;
.LBB0_1997:
	ds_read_b128 v[130:133], v175
	ds_read_b128 v[134:137], v175 offset:1024
	ds_read_b128 v[138:141], v175 offset:2048
	ds_read_b128 v[142:145], v175 offset:3072
	ds_read_b128 v[146:149], v176
	ds_read_b128 v[150:153], v176 offset:1024
	ds_read_b128 v[154:157], v176 offset:2048
	ds_read_b128 v[158:161], v176 offset:3072
	s_add_i32 s43, s41, 2
	s_add_u32 s62, s52, 0xfff80800
	s_addc_u32 s63, s53, -1
	s_cmp_eq_u32 s3, s41
	s_cselect_b32 s63, s45, s63
	s_cselect_b32 s62, s44, s62
	s_cselect_b32 s77, s47, s39
	s_cselect_b32 s76, s46, s11
	v_lshl_add_u64 v[170:171], s[52:53], 0, v[166:167]
	s_add_i32 m0, s49, 0xc000
	ds_read_b128 v[184:187], v177
	ds_read_b128 v[188:191], v177 offset:1024
	ds_read_b128 v[192:195], v177 offset:2048
	ds_read_b128 v[196:199], v177 offset:3072
	ds_read_b128 v[200:203], v177 offset:4096
	ds_read_b128 v[204:207], v177 offset:5120
	ds_read_b128 v[208:211], v177 offset:6144
	ds_read_b128 v[212:215], v177 offset:7168
	global_load_lds_dwordx4 v[170:171], off
	v_lshl_add_u64 v[170:171], v[170:171], 0, s[12:13]
	s_add_i32 m0, s49, 0xe000
	s_nop 0
	global_load_lds_dwordx4 v[170:171], off
	s_waitcnt vmcnt(8)
	s_waitcnt lgkmcnt(0)
	s_barrier
	s_setprio 1
	s_waitcnt lgkmcnt(0)
	v_mfma_f32_16x16x32_bf16 v[126:129], v[130:133], v[184:187], v[126:129]
	v_mfma_f32_16x16x32_bf16 v[126:129], v[134:137], v[188:191], v[126:129]
	v_mfma_f32_16x16x32_bf16 v[122:125], v[142:145], v[188:191], v[122:125]
	v_mfma_f32_16x16x32_bf16 v[122:125], v[138:141], v[184:187], v[122:125]
	v_mfma_f32_16x16x32_bf16 v[106:109], v[138:141], v[192:195], v[106:109]
	v_mfma_f32_16x16x32_bf16 v[106:109], v[142:145], v[196:199], v[106:109]
	v_mfma_f32_16x16x32_bf16 v[110:113], v[134:137], v[196:199], v[110:113]
	v_mfma_f32_16x16x32_bf16 v[110:113], v[130:133], v[192:195], v[110:113]
	v_mfma_f32_16x16x32_bf16 v[94:97], v[130:133], v[200:203], v[94:97]
	v_mfma_f32_16x16x32_bf16 v[94:97], v[134:137], v[204:207], v[94:97]
	v_mfma_f32_16x16x32_bf16 v[90:93], v[142:145], v[204:207], v[90:93]
	v_mfma_f32_16x16x32_bf16 v[90:93], v[138:141], v[200:203], v[90:93]
	v_mfma_f32_16x16x32_bf16 v[74:77], v[138:141], v[208:211], v[74:77]
	v_mfma_f32_16x16x32_bf16 v[74:77], v[142:145], v[212:215], v[74:77]
	v_mfma_f32_16x16x32_bf16 v[78:81], v[134:137], v[212:215], v[78:81]
	v_mfma_f32_16x16x32_bf16 v[78:81], v[130:133], v[208:211], v[78:81]
	v_mfma_f32_16x16x32_bf16 v[118:121], v[146:149], v[184:187], v[118:121]
	v_mfma_f32_16x16x32_bf16 v[118:121], v[150:153], v[188:191], v[118:121]
	v_mfma_f32_16x16x32_bf16 v[114:117], v[158:161], v[188:191], v[114:117]
	v_mfma_f32_16x16x32_bf16 v[114:117], v[154:157], v[184:187], v[114:117]
	v_mfma_f32_16x16x32_bf16 v[98:101], v[154:157], v[192:195], v[98:101]
	v_mfma_f32_16x16x32_bf16 v[98:101], v[158:161], v[196:199], v[98:101]
	v_mfma_f32_16x16x32_bf16 v[102:105], v[150:153], v[196:199], v[102:105]
	v_mfma_f32_16x16x32_bf16 v[102:105], v[146:149], v[192:195], v[102:105]
	v_mfma_f32_16x16x32_bf16 v[86:89], v[146:149], v[200:203], v[86:89]
	v_mfma_f32_16x16x32_bf16 v[86:89], v[150:153], v[204:207], v[86:89]
	v_mfma_f32_16x16x32_bf16 v[82:85], v[158:161], v[204:207], v[82:85]
	v_mfma_f32_16x16x32_bf16 v[82:85], v[154:157], v[200:203], v[82:85]
	s_barrier
	s_setprio 2
	v_mfma_f32_16x16x32_bf16 v[66:69], v[154:157], v[208:211], v[66:69]
	v_mfma_f32_16x16x32_bf16 v[66:69], v[158:161], v[212:215], v[66:69]
	v_mfma_f32_16x16x32_bf16 v[70:73], v[150:153], v[212:215], v[70:73]
	v_mfma_f32_16x16x32_bf16 v[70:73], v[146:149], v[208:211], v[70:73]
	s_setprio 0
	s_add_i32 s41, s70, s57
	v_lshl_add_u64 v[170:171], s[76:77], 0, v[162:163]
	s_mov_b32 m0, s41
	ds_read_b128 v[184:187], v177 offset:16384
	ds_read_b128 v[188:191], v177 offset:17408
	ds_read_b128 v[192:195], v177 offset:18432
	ds_read_b128 v[196:199], v177 offset:19456
	ds_read_b128 v[200:203], v177 offset:20480
	ds_read_b128 v[204:207], v177 offset:21504
	ds_read_b128 v[208:211], v177 offset:22528
	ds_read_b128 v[212:215], v177 offset:23552
	global_load_lds_dwordx4 v[170:171], off
	v_lshl_add_u64 v[216:217], v[170:171], 0, s[12:13]
	s_add_i32 m0, s41, 0x2000
	s_add_i32 s41, s71, s57
	global_load_lds_dwordx4 v[216:217], off
	v_lshl_add_u64 v[216:217], v[170:171], 0, s[14:15]
	s_mov_b32 m0, s41
	s_nop 0
	global_load_lds_dwordx4 v[216:217], off
	v_lshl_add_u64 v[216:217], v[170:171], 0, s[16:17]
	s_add_i32 m0, s41, 0x2000
	s_nop 0
	global_load_lds_dwordx4 v[216:217], off
	v_lshl_add_u64 v[216:217], s[62:63], 0, v[162:163]
	s_mov_b32 m0, s49
	v_lshl_add_u64 v[218:219], v[216:217], 0, s[12:13]
	global_load_lds_dwordx4 v[216:217], off
	s_mov_b32 m0, s58
	s_nop 0
	global_load_lds_dwordx4 v[218:219], off
	s_waitcnt vmcnt(8)
	s_waitcnt lgkmcnt(0)
	s_barrier
; #define PG8_STAGE(bufoff, gbase, voff) do { if constexpr (!pg8_noload<Epi>::value) { _Pragma("unroll") for (int _i = 0; _i < 2; ++_i) \
;         __builtin_amdgcn_global_load_lds((const unsigned*)((const char*)(gbase) + (size_t)_i * pstep + (voff)[0]), (PG8_LAS unsigned*)(lds + (bufoff) + ldsw + _i * 8192), 16, 0, 0); } } while (0)
; #define PG8_LDA(dst, b, h) do { _Pragma("unroll") for (int m = 0; m < 4; ++m) _Pragma("unroll") for (int k = 0; k < 2; ++k) dst[m][k] = *(const PG8_LAS bf16x8*)(lds + PG8_SA(b, h) + aoff + m * 2048 + k * 1024); } while (0)
; #define PG8_LDB(dst, b, h) do { _Pragma("unroll") for (int n = 0; n < 2; ++n) _Pragma("unroll") for (int k = 0; k < 2; ++k) dst[n][k] = *(const PG8_LAS bf16x8*)(lds + PG8_SB(b, h) + boff + n * 2048 + k * 1024); } while (0)
; #define PG8_MMA(ai, bj, At, Bt) do { __builtin_amdgcn_s_setprio(1); _Pragma("unroll") for (int m = 0; m < 4; ++m) _Pragma("unroll") for (int n = 0; n < 2; ++n) _Pragma("unroll") for (int k = 0; k < 2; ++k) \
;         acc[ai][bj][m][n] = __builtin_amdgcn_mfma_f32_16x16x32_bf16(Bt[n][k], At[m][k], acc[ai][bj][m][n], 0, 0, 0); __builtin_amdgcn_s_setprio(0); } while (0)
; #define PG8_WAIT_V(n) asm volatile("s_waitcnt vmcnt(" #n ")" ::: "memory")
; #define PG8_WAIT_L(n) asm volatile("s_waitcnt lgkmcnt(" #n ")" ::: "memory")
; #define PG8_BAR __builtin_amdgcn_s_barrier()
; #define PG8_SCHED __builtin_amdgcn_sched_barrier(0)
; template <class Epi, class Sched, bool ALIGN_EPI = false, bool SP2 = false, bool ABLK = false>
; __device__ __forceinline__ void gemm_phase(PG8_LAS unsigned char* lds, const Gemm g, const Sched& S, const Epi& E) {
;     ...
;             PG8_WAIT_V(8); PG8_WAIT_L(0); PG8_BAR; PG8_MMA(1, 0, At, B0); PG8_MMA(1, 1, At, B1); PG8_BAR; PG8_SCHED;
;             PG8_LDB(B0, 1, 0); PG8_LDB(B1, 1, 1); PG8_SCHED; PG8_LDA(At, 1, 0); PG8_STAGE(PG8_SA(0, 1), a2 + hstep, voffA);
;             PG8_WAIT_V(8); PG8_WAIT_L(0); PG8_BAR; PG8_MMA(0, 0, At, B0); PG8_MMA(0, 1, At, B1); PG8_BAR; PG8_SCHED;
	s_setprio 1
	s_waitcnt lgkmcnt(0)
	v_mfma_f32_16x16x32_bf16 v[62:65], v[130:133], v[184:187], v[62:65]
	v_mfma_f32_16x16x32_bf16 v[62:65], v[134:137], v[188:191], v[62:65]
	v_mfma_f32_16x16x32_bf16 v[58:61], v[142:145], v[188:191], v[58:61]
	v_mfma_f32_16x16x32_bf16 v[58:61], v[138:141], v[184:187], v[58:61]
	v_mfma_f32_16x16x32_bf16 v[42:45], v[138:141], v[192:195], v[42:45]
	v_mfma_f32_16x16x32_bf16 v[42:45], v[142:145], v[196:199], v[42:45]
	v_mfma_f32_16x16x32_bf16 v[46:49], v[134:137], v[196:199], v[46:49]
	v_mfma_f32_16x16x32_bf16 v[46:49], v[130:133], v[192:195], v[46:49]
	v_mfma_f32_16x16x32_bf16 v[30:33], v[130:133], v[200:203], v[30:33]
	v_mfma_f32_16x16x32_bf16 v[30:33], v[134:137], v[204:207], v[30:33]
	v_mfma_f32_16x16x32_bf16 v[26:29], v[142:145], v[204:207], v[26:29]
	v_mfma_f32_16x16x32_bf16 v[26:29], v[138:141], v[200:203], v[26:29]
	v_mfma_f32_16x16x32_bf16 v[10:13], v[138:141], v[208:211], v[10:13]
	v_mfma_f32_16x16x32_bf16 v[10:13], v[142:145], v[212:215], v[10:13]
	v_mfma_f32_16x16x32_bf16 v[14:17], v[134:137], v[212:215], v[14:17]
	v_mfma_f32_16x16x32_bf16 v[14:17], v[130:133], v[208:211], v[14:17]
	v_mfma_f32_16x16x32_bf16 v[54:57], v[146:149], v[184:187], v[54:57]
	v_mfma_f32_16x16x32_bf16 v[54:57], v[150:153], v[188:191], v[54:57]
	v_mfma_f32_16x16x32_bf16 v[50:53], v[158:161], v[188:191], v[50:53]
	v_mfma_f32_16x16x32_bf16 v[50:53], v[154:157], v[184:187], v[50:53]
	v_mfma_f32_16x16x32_bf16 v[34:37], v[154:157], v[192:195], v[34:37]
	v_mfma_f32_16x16x32_bf16 v[34:37], v[158:161], v[196:199], v[34:37]
	v_mfma_f32_16x16x32_bf16 v[38:41], v[150:153], v[196:199], v[38:41]
	v_mfma_f32_16x16x32_bf16 v[38:41], v[146:149], v[192:195], v[38:41]
	v_mfma_f32_16x16x32_bf16 v[22:25], v[146:149], v[200:203], v[22:25]
	v_mfma_f32_16x16x32_bf16 v[22:25], v[150:153], v[204:207], v[22:25]
	v_mfma_f32_16x16x32_bf16 v[18:21], v[158:161], v[204:207], v[18:21]
	v_mfma_f32_16x16x32_bf16 v[18:21], v[154:157], v[200:203], v[18:21]
	s_barrier
	s_setprio 2
	v_mfma_f32_16x16x32_bf16 v[2:5], v[154:157], v[208:211], v[2:5]
	v_mfma_f32_16x16x32_bf16 v[2:5], v[158:161], v[212:215], v[2:5]
	v_mfma_f32_16x16x32_bf16 v[6:9], v[150:153], v[212:215], v[6:9]
	v_mfma_f32_16x16x32_bf16 v[6:9], v[146:149], v[208:211], v[6:9]
	s_setprio 0
	s_add_i32 s41, 0, 0x18000
	s_add_i32 s62, 0, 0x1c000
	v_add_u32_e32 v142, s41, v1
	v_add_u32_e32 v158, s62, v1
	ds_read_b128 v[130:133], v142
	ds_read_b128 v[134:137], v142 offset:1024
	ds_read_b128 v[138:141], v142 offset:2048
	ds_read_b128 v[142:145], v142 offset:3072
	ds_read_b128 v[146:149], v158
	ds_read_b128 v[150:153], v158 offset:1024
	ds_read_b128 v[154:157], v158 offset:2048
	ds_read_b128 v[158:161], v158 offset:3072
	s_mov_b32 m0, s59
	v_lshl_add_u64 v[218:219], v[216:217], 0, s[14:15]
	ds_read_b128 v[184:187], v177 offset:32768
	ds_read_b128 v[188:191], v177 offset:33792
	ds_read_b128 v[192:195], v177 offset:34816
	ds_read_b128 v[196:199], v177 offset:35840
	ds_read_b128 v[200:203], v177 offset:36864
	ds_read_b128 v[204:207], v177 offset:37888
	ds_read_b128 v[208:211], v177 offset:38912
	ds_read_b128 v[212:215], v177 offset:39936
	global_load_lds_dwordx4 v[218:219], off
	v_lshl_add_u64 v[218:219], v[216:217], 0, s[16:17]
	s_mov_b32 m0, s60
	s_nop 0
	global_load_lds_dwordx4 v[218:219], off
	s_waitcnt vmcnt(8)
	s_waitcnt lgkmcnt(0)
	s_barrier
	s_setprio 1
	s_waitcnt lgkmcnt(0)
	v_mfma_f32_16x16x32_bf16 v[126:129], v[130:133], v[184:187], v[126:129]
	v_mfma_f32_16x16x32_bf16 v[126:129], v[134:137], v[188:191], v[126:129]
	v_mfma_f32_16x16x32_bf16 v[122:125], v[142:145], v[188:191], v[122:125]
	v_mfma_f32_16x16x32_bf16 v[122:125], v[138:141], v[184:187], v[122:125]
	v_mfma_f32_16x16x32_bf16 v[106:109], v[138:141], v[192:195], v[106:109]
	v_mfma_f32_16x16x32_bf16 v[106:109], v[142:145], v[196:199], v[106:109]
	v_mfma_f32_16x16x32_bf16 v[110:113], v[134:137], v[196:199], v[110:113]
	v_mfma_f32_16x16x32_bf16 v[110:113], v[130:133], v[192:195], v[110:113]
	v_mfma_f32_16x16x32_bf16 v[94:97], v[130:133], v[200:203], v[94:97]
	v_mfma_f32_16x16x32_bf16 v[94:97], v[134:137], v[204:207], v[94:97]
	v_mfma_f32_16x16x32_bf16 v[90:93], v[142:145], v[204:207], v[90:93]
	v_mfma_f32_16x16x32_bf16 v[90:93], v[138:141], v[200:203], v[90:93]
	v_mfma_f32_16x16x32_bf16 v[74:77], v[138:141], v[208:211], v[74:77]
	v_mfma_f32_16x16x32_bf16 v[74:77], v[142:145], v[212:215], v[74:77]
	v_mfma_f32_16x16x32_bf16 v[78:81], v[134:137], v[212:215], v[78:81]
	v_mfma_f32_16x16x32_bf16 v[78:81], v[130:133], v[208:211], v[78:81]
	v_mfma_f32_16x16x32_bf16 v[118:121], v[146:149], v[184:187], v[118:121]
	v_mfma_f32_16x16x32_bf16 v[118:121], v[150:153], v[188:191], v[118:121]
	v_mfma_f32_16x16x32_bf16 v[114:117], v[158:161], v[188:191], v[114:117]
	v_mfma_f32_16x16x32_bf16 v[114:117], v[154:157], v[184:187], v[114:117]
	v_mfma_f32_16x16x32_bf16 v[98:101], v[154:157], v[192:195], v[98:101]
	v_mfma_f32_16x16x32_bf16 v[98:101], v[158:161], v[196:199], v[98:101]
	v_mfma_f32_16x16x32_bf16 v[102:105], v[150:153], v[196:199], v[102:105]
	v_mfma_f32_16x16x32_bf16 v[102:105], v[146:149], v[192:195], v[102:105]
	v_mfma_f32_16x16x32_bf16 v[86:89], v[146:149], v[200:203], v[86:89]
	v_mfma_f32_16x16x32_bf16 v[86:89], v[150:153], v[204:207], v[86:89]
	v_mfma_f32_16x16x32_bf16 v[82:85], v[158:161], v[204:207], v[82:85]
	v_mfma_f32_16x16x32_bf16 v[82:85], v[154:157], v[200:203], v[82:85]
	s_barrier
; #define PG8_STAGE(bufoff, gbase, voff) do { if constexpr (!pg8_noload<Epi>::value) { _Pragma("unroll") for (int _i = 0; _i < 2; ++_i) \
;         __builtin_amdgcn_global_load_lds((const unsigned*)((const char*)(gbase) + (size_t)_i * pstep + (voff)[0]), (PG8_LAS unsigned*)(lds + (bufoff) + ldsw + _i * 8192), 16, 0, 0); } } while (0)
; #define PG8_LDA(dst, b, h) do { _Pragma("unroll") for (int m = 0; m < 4; ++m) _Pragma("unroll") for (int k = 0; k < 2; ++k) dst[m][k] = *(const PG8_LAS bf16x8*)(lds + PG8_SA(b, h) + aoff + m * 2048 + k * 1024); } while (0)
; #define PG8_MMA(ai, bj, At, Bt) do { __builtin_amdgcn_s_setprio(1); _Pragma("unroll") for (int m = 0; m < 4; ++m) _Pragma("unroll") for (int n = 0; n < 2; ++n) _Pragma("unroll") for (int k = 0; k < 2; ++k) \
;         acc[ai][bj][m][n] = __builtin_amdgcn_mfma_f32_16x16x32_bf16(Bt[n][k], At[m][k], acc[ai][bj][m][n], 0, 0, 0); __builtin_amdgcn_s_setprio(0); } while (0)
; #define PG8_WAIT_V(n) asm volatile("s_waitcnt vmcnt(" #n ")" ::: "memory")
; #define PG8_WAIT_L(n) asm volatile("s_waitcnt lgkmcnt(" #n ")" ::: "memory")
; #define PG8_BAR __builtin_amdgcn_s_barrier()
; #define PG8_SCHED __builtin_amdgcn_sched_barrier(0)
; template <class Epi, class Sched, bool ALIGN_EPI = false, bool SP2 = false, bool ABLK = false>
; __device__ __forceinline__ void gemm_phase(PG8_LAS unsigned char* lds, const Gemm g, const Sched& S, const Epi& E) {
;     ...
;             PG8_WAIT_V(8); PG8_WAIT_L(0); PG8_BAR; PG8_MMA(0, 0, At, B0); PG8_MMA(0, 1, At, B1); PG8_BAR; PG8_SCHED;
;             PG8_LDA(At, 1, 1); PG8_STAGE(PG8_SB(1, 0), b3, voffB); PG8_STAGE(PG8_SB(1, 1), b3 + hstep, voffB); PG8_STAGE(PG8_SA(1, 0), a3, voffA);
;             PG8_WAIT_V(8); PG8_WAIT_L(0); PG8_BAR; PG8_MMA(1, 0, At, B0); PG8_MMA(1, 1, At, B1); PG8_BAR; PG8_SCHED;
	s_setprio 2
	v_mfma_f32_16x16x32_bf16 v[66:69], v[154:157], v[208:211], v[66:69]
	v_mfma_f32_16x16x32_bf16 v[66:69], v[158:161], v[212:215], v[66:69]
	v_mfma_f32_16x16x32_bf16 v[70:73], v[150:153], v[212:215], v[70:73]
	v_mfma_f32_16x16x32_bf16 v[70:73], v[146:149], v[208:211], v[70:73]
	s_setprio 0
	s_add_i32 s41, s41, s57
	v_lshl_add_u64 v[218:219], v[170:171], 0, s[24:25]
	s_mov_b32 m0, s41
	ds_read_b128 v[184:187], v177 offset:49152
	ds_read_b128 v[188:191], v177 offset:50176
	ds_read_b128 v[192:195], v177 offset:51200
	ds_read_b128 v[196:199], v177 offset:52224
	ds_read_b128 v[200:203], v177 offset:53248
	ds_read_b128 v[204:207], v177 offset:54272
	ds_read_b128 v[208:211], v177 offset:55296
	ds_read_b128 v[212:215], v177 offset:56320
	global_load_lds_dwordx4 v[218:219], off
	v_lshl_add_u64 v[218:219], v[170:171], 0, s[26:27]
	s_add_i32 m0, s41, 0x2000
	s_add_i32 s41, s62, s57
	global_load_lds_dwordx4 v[218:219], off
	v_lshl_add_u64 v[218:219], v[170:171], 0, s[28:29]
	s_mov_b32 m0, s41
	v_lshl_add_u64 v[170:171], v[170:171], 0, s[30:31]
	global_load_lds_dwordx4 v[218:219], off
	s_add_i32 m0, s41, 0x2000
	s_nop 0
	global_load_lds_dwordx4 v[170:171], off
	v_lshl_add_u64 v[170:171], v[216:217], 0, s[24:25]
	s_mov_b32 m0, s65
	s_nop 0
	global_load_lds_dwordx4 v[170:171], off
	v_lshl_add_u64 v[170:171], v[216:217], 0, s[26:27]
	s_mov_b32 m0, s66
	s_nop 0
	global_load_lds_dwordx4 v[170:171], off
	s_waitcnt vmcnt(8)
	s_waitcnt lgkmcnt(0)
	s_barrier
	s_setprio 1
	s_waitcnt lgkmcnt(0)
	v_mfma_f32_16x16x32_bf16 v[62:65], v[130:133], v[184:187], v[62:65]
	v_mfma_f32_16x16x32_bf16 v[62:65], v[134:137], v[188:191], v[62:65]
	v_mfma_f32_16x16x32_bf16 v[58:61], v[142:145], v[188:191], v[58:61]
	v_mfma_f32_16x16x32_bf16 v[58:61], v[138:141], v[184:187], v[58:61]
	v_mfma_f32_16x16x32_bf16 v[42:45], v[138:141], v[192:195], v[42:45]
	v_mfma_f32_16x16x32_bf16 v[42:45], v[142:145], v[196:199], v[42:45]
	v_mfma_f32_16x16x32_bf16 v[46:49], v[134:137], v[196:199], v[46:49]
	v_mfma_f32_16x16x32_bf16 v[46:49], v[130:133], v[192:195], v[46:49]
	v_mfma_f32_16x16x32_bf16 v[30:33], v[130:133], v[200:203], v[30:33]
	v_mfma_f32_16x16x32_bf16 v[30:33], v[134:137], v[204:207], v[30:33]
	v_mfma_f32_16x16x32_bf16 v[26:29], v[142:145], v[204:207], v[26:29]
	v_mfma_f32_16x16x32_bf16 v[26:29], v[138:141], v[200:203], v[26:29]
	v_mfma_f32_16x16x32_bf16 v[10:13], v[138:141], v[208:211], v[10:13]
	v_mfma_f32_16x16x32_bf16 v[10:13], v[142:145], v[212:215], v[10:13]
	v_mfma_f32_16x16x32_bf16 v[14:17], v[134:137], v[212:215], v[14:17]
	v_mfma_f32_16x16x32_bf16 v[14:17], v[130:133], v[208:211], v[14:17]
	v_mfma_f32_16x16x32_bf16 v[54:57], v[146:149], v[184:187], v[54:57]
	v_mfma_f32_16x16x32_bf16 v[54:57], v[150:153], v[188:191], v[54:57]
	v_mfma_f32_16x16x32_bf16 v[50:53], v[158:161], v[188:191], v[50:53]
	v_mfma_f32_16x16x32_bf16 v[50:53], v[154:157], v[184:187], v[50:53]
	v_mfma_f32_16x16x32_bf16 v[34:37], v[154:157], v[192:195], v[34:37]
	v_mfma_f32_16x16x32_bf16 v[34:37], v[158:161], v[196:199], v[34:37]
	v_mfma_f32_16x16x32_bf16 v[38:41], v[150:153], v[196:199], v[38:41]
	v_mfma_f32_16x16x32_bf16 v[38:41], v[146:149], v[192:195], v[38:41]
	v_mfma_f32_16x16x32_bf16 v[22:25], v[146:149], v[200:203], v[22:25]
	v_mfma_f32_16x16x32_bf16 v[22:25], v[150:153], v[204:207], v[22:25]
	v_mfma_f32_16x16x32_bf16 v[18:21], v[158:161], v[204:207], v[18:21]
	v_mfma_f32_16x16x32_bf16 v[18:21], v[154:157], v[200:203], v[18:21]
	s_barrier
	s_setprio 2
	v_mfma_f32_16x16x32_bf16 v[2:5], v[154:157], v[208:211], v[2:5]
	v_mfma_f32_16x16x32_bf16 v[2:5], v[158:161], v[212:215], v[2:5]
	v_mfma_f32_16x16x32_bf16 v[6:9], v[150:153], v[212:215], v[6:9]
	v_mfma_f32_16x16x32_bf16 v[6:9], v[146:149], v[208:211], v[6:9]
	s_setprio 0
	s_add_u32 s52, s52, 0x1000
	s_addc_u32 s53, s53, 0
	s_add_u32 s11, s11, 0x1000
	s_addc_u32 s39, s39, 0
	s_cmp_ge_i32 s43, s75
	s_mov_b32 s41, s43
	s_cbranch_scc0 .LBB0_1997
	s_and_b64 vcc, exec, s[34:35]
	s_cbranch_vccnz .LBB0_2002
	s_lshl_b32 s11, s2, 8
	s_cmp_gt_i32 s2, 63
	s_mov_b64 s[52:53], -1
	s_cbranch_scc1 .LBB0_2003

; #define PG8_STAGE(bufoff, gbase, voff) do { if constexpr (!pg8_noload<Epi>::value) { _Pragma("unroll") for (int _i = 0; _i < 2; ++_i) \
;         __builtin_amdgcn_global_load_lds((const unsigned*)((const char*)(gbase) + (size_t)_i * pstep + (voff)[0]), (PG8_LAS unsigned*)(lds + (bufoff) + ldsw + _i * 8192), 16, 0, 0); } } while (0)
; #define PG8_LDA(dst, b, h) do { _Pragma("unroll") for (int m = 0; m < 4; ++m) _Pragma("unroll") for (int k = 0; k < 2; ++k) dst[m][k] = *(const PG8_LAS bf16x8*)(lds + PG8_SA(b, h) + aoff + m * 2048 + k * 1024); } while (0)
; #define PG8_LDB(dst, b, h) do { _Pragma("unroll") for (int n = 0; n < 2; ++n) _Pragma("unroll") for (int k = 0; k < 2; ++k) dst[n][k] = *(const PG8_LAS bf16x8*)(lds + PG8_SB(b, h) + boff + n * 2048 + k * 1024); } while (0)
; #define PG8_MMA(ai, bj, At, Bt) do { __builtin_amdgcn_s_setprio(1); _Pragma("unroll") for (int m = 0; m < 4; ++m) _Pragma("unroll") for (int n = 0; n < 2; ++n) _Pragma("unroll") for (int k = 0; k < 2; ++k) \
;         acc[ai][bj][m][n] = __builtin_amdgcn_mfma_f32_16x16x32_bf16(Bt[n][k], At[m][k], acc[ai][bj][m][n], 0, 0, 0); __builtin_amdgcn_s_setprio(0); } while (0)
; #define PG8_WAIT_V(n) asm volatile("s_waitcnt vmcnt(" #n ")" ::: "memory")
; #define PG8_WAIT_L(n) asm volatile("s_waitcnt lgkmcnt(" #n ")" ::: "memory")
; #define PG8_BAR __builtin_amdgcn_s_barrier()
; template <class Epi, class Sched, bool ALIGN_EPI = false, bool SP2 = false, bool ABLK = false>
; __device__ __forceinline__ void gemm_phase(PG8_LAS unsigned char* lds, const Gemm g, const Sched& S, const Epi& E) {
;     ...
;             const bool last = (t == nt - 2);
;             const char* a1 = cA + (size_t)(t + 1) * kstep;
;             const char* a2 = last ? nA : cA + (size_t)(t + 2) * kstep; const char* b2 = last ? nB : cB + (size_t)(t + 2) * kstepB;
;             const char* a3 = a2 + kstep; const char* b3 = b2 + kstepB;
;             if (last && has_next) S.a_ready(nxt);
;             if constexpr (SP2) {
;             PG8_LDB(B0, 0, 0); PG8_LDB(B1, 0, 1); PG8_SCHED; PG8_LDA(At, 0, 0); PG8_STAGE(PG8_SA(1, 1), a1 + hstep, voffA);
;             PG8_WAIT_V(8); PG8_WAIT_L(0); PG8_BAR; PG8_MMA(0, 0, At, B0); PG8_MMA(0, 1, At, B1); PG8_BAR; PG8_SCHED;
;             PG8_LDA(At, 0, 1); PG8_STAGE(PG8_SB(0, 0), b2, voffB); PG8_STAGE(PG8_SB(0, 1), b2 + hstep, voffB); PG8_STAGE(PG8_SA(0, 0), a2, voffA);
.LBB0_2119:
	s_or_b32 s30, s59, 1
	s_lshl_b64 s[14:15], s[30:31], 11
	s_add_u32 s14, s82, s14
	v_add_u32_e32 v133, s71, v148
	s_addc_u32 s15, s83, s15
	s_add_i32 s30, s59, 2
	ds_read_b128 v[144:147], v133
	ds_read_b128 v[184:187], v133 offset:1024
	ds_read_b128 v[188:191], v133 offset:2048
	ds_read_b128 v[192:195], v133 offset:3072
	v_add_u32_e32 v133, s73, v148
	s_lshl_b64 s[34:35], s[30:31], 11
	ds_read_b128 v[196:199], v133
	ds_read_b128 v[200:203], v133 offset:1024
	ds_read_b128 v[204:207], v133 offset:2048
	ds_read_b128 v[208:211], v133 offset:3072
	s_add_u32 s96, s82, s34
	s_addc_u32 s97, s83, s35
	s_and_b64 s[94:95], s[92:93], exec
	s_cselect_b32 s95, s97, s77
	s_cselect_b32 s94, s96, s28
	s_add_u32 s96, s88, s34
	s_addc_u32 s97, s89, s35
	s_and_b64 s[34:35], s[92:93], exec
	s_cselect_b32 s35, s97, s29
	s_cselect_b32 s34, s96, s75
	v_lshl_add_u64 v[180:181], s[14:15], 0, v[130:131]
	v_lshl_add_u64 v[244:245], v[180:181], 0, s[24:25]
	s_add_i32 m0, s17, 0xc000
	ds_read_b128 v[212:215], v168
	ds_read_b128 v[216:219], v168 offset:1024
	ds_read_b128 v[220:223], v168 offset:2048
	ds_read_b128 v[224:227], v168 offset:3072
	ds_read_b128 v[228:231], v168 offset:4096
	ds_read_b128 v[232:235], v168 offset:5120
	ds_read_b128 v[236:239], v168 offset:6144
	ds_read_b128 v[240:243], v168 offset:7168
	global_load_lds_dwordx4 v[244:245], off
	v_lshl_add_u64 v[180:181], v[180:181], 0, s[26:27]
	s_add_i32 m0, s17, 0xe000
	s_nop 0
	global_load_lds_dwordx4 v[180:181], off
	s_waitcnt vmcnt(8)
	s_waitcnt lgkmcnt(0)
	s_barrier
	s_setprio 1
	s_waitcnt lgkmcnt(0)
	v_mfma_f32_16x16x32_bf16 v[126:129], v[144:147], v[212:215], v[126:129]
	v_mfma_f32_16x16x32_bf16 v[126:129], v[184:187], v[216:219], v[126:129]
	v_mfma_f32_16x16x32_bf16 v[122:125], v[192:195], v[216:219], v[122:125]
	v_mfma_f32_16x16x32_bf16 v[122:125], v[188:191], v[212:215], v[122:125]
	v_mfma_f32_16x16x32_bf16 v[106:109], v[188:191], v[220:223], v[106:109]
	v_mfma_f32_16x16x32_bf16 v[106:109], v[192:195], v[224:227], v[106:109]
	v_mfma_f32_16x16x32_bf16 v[110:113], v[184:187], v[224:227], v[110:113]
	v_mfma_f32_16x16x32_bf16 v[110:113], v[144:147], v[220:223], v[110:113]
	v_mfma_f32_16x16x32_bf16 v[94:97], v[144:147], v[228:231], v[94:97]
	v_mfma_f32_16x16x32_bf16 v[94:97], v[184:187], v[232:235], v[94:97]
	v_mfma_f32_16x16x32_bf16 v[90:93], v[192:195], v[232:235], v[90:93]
	v_mfma_f32_16x16x32_bf16 v[90:93], v[188:191], v[228:231], v[90:93]
	v_mfma_f32_16x16x32_bf16 v[74:77], v[188:191], v[236:239], v[74:77]
	v_mfma_f32_16x16x32_bf16 v[74:77], v[192:195], v[240:243], v[74:77]
	v_mfma_f32_16x16x32_bf16 v[78:81], v[184:187], v[240:243], v[78:81]
	v_mfma_f32_16x16x32_bf16 v[78:81], v[144:147], v[236:239], v[78:81]
	v_mfma_f32_16x16x32_bf16 v[118:121], v[196:199], v[212:215], v[118:121]
	v_mfma_f32_16x16x32_bf16 v[118:121], v[200:203], v[216:219], v[118:121]
	v_mfma_f32_16x16x32_bf16 v[114:117], v[208:211], v[216:219], v[114:117]
	v_mfma_f32_16x16x32_bf16 v[114:117], v[204:207], v[212:215], v[114:117]
	v_mfma_f32_16x16x32_bf16 v[98:101], v[204:207], v[220:223], v[98:101]
	v_mfma_f32_16x16x32_bf16 v[98:101], v[208:211], v[224:227], v[98:101]
	v_mfma_f32_16x16x32_bf16 v[102:105], v[200:203], v[224:227], v[102:105]
	v_mfma_f32_16x16x32_bf16 v[102:105], v[196:199], v[220:223], v[102:105]
	v_mfma_f32_16x16x32_bf16 v[86:89], v[196:199], v[228:231], v[86:89]
	v_mfma_f32_16x16x32_bf16 v[86:89], v[200:203], v[232:235], v[86:89]
	v_mfma_f32_16x16x32_bf16 v[82:85], v[208:211], v[232:235], v[82:85]
	v_mfma_f32_16x16x32_bf16 v[82:85], v[204:207], v[228:231], v[82:85]
	s_barrier
	s_setprio 2
	v_mfma_f32_16x16x32_bf16 v[66:69], v[204:207], v[236:239], v[66:69]
	v_mfma_f32_16x16x32_bf16 v[66:69], v[208:211], v[240:243], v[66:69]
	v_mfma_f32_16x16x32_bf16 v[70:73], v[200:203], v[240:243], v[70:73]
	v_mfma_f32_16x16x32_bf16 v[70:73], v[196:199], v[236:239], v[70:73]
	s_setprio 0
	s_add_i32 s14, s71, s3
	v_lshl_add_u64 v[180:181], s[34:35], 0, v[130:131]
	s_mov_b32 m0, s14
	ds_read_b128 v[212:215], v168 offset:16384
	ds_read_b128 v[216:219], v168 offset:17408
	ds_read_b128 v[220:223], v168 offset:18432
	ds_read_b128 v[224:227], v168 offset:19456
	ds_read_b128 v[228:231], v168 offset:20480
	ds_read_b128 v[232:235], v168 offset:21504
	ds_read_b128 v[236:239], v168 offset:22528
	ds_read_b128 v[240:243], v168 offset:23552
	global_load_lds_dwordx4 v[180:181], off
	v_lshl_add_u64 v[244:245], v[180:181], 0, s[22:23]
	s_add_i32 m0, s14, 0x2000
	s_add_i32 s14, s73, s3
	global_load_lds_dwordx4 v[244:245], off
	v_lshl_add_u64 v[244:245], v[180:181], 0, s[24:25]
	s_mov_b32 m0, s14
	s_nop 0
	global_load_lds_dwordx4 v[244:245], off
	v_lshl_add_u64 v[244:245], v[180:181], 0, s[26:27]
	s_add_i32 m0, s14, 0x2000
	s_nop 0
	global_load_lds_dwordx4 v[244:245], off
	v_lshl_add_u64 v[244:245], s[94:95], 0, v[130:131]
	s_mov_b32 m0, s17
	v_lshl_add_u64 v[246:247], v[244:245], 0, s[22:23]
	global_load_lds_dwordx4 v[244:245], off
	s_mov_b32 m0, s56
	s_nop 0
	global_load_lds_dwordx4 v[246:247], off
	s_waitcnt vmcnt(8)
	s_waitcnt lgkmcnt(0)
	s_barrier
; #define PG8_STAGE(bufoff, gbase, voff) do { if constexpr (!pg8_noload<Epi>::value) { _Pragma("unroll") for (int _i = 0; _i < 2; ++_i) \
;         __builtin_amdgcn_global_load_lds((const unsigned*)((const char*)(gbase) + (size_t)_i * pstep + (voff)[0]), (PG8_LAS unsigned*)(lds + (bufoff) + ldsw + _i * 8192), 16, 0, 0); } } while (0)
; #define PG8_LDA(dst, b, h) do { _Pragma("unroll") for (int m = 0; m < 4; ++m) _Pragma("unroll") for (int k = 0; k < 2; ++k) dst[m][k] = *(const PG8_LAS bf16x8*)(lds + PG8_SA(b, h) + aoff + m * 2048 + k * 1024); } while (0)
; #define PG8_LDB(dst, b, h) do { _Pragma("unroll") for (int n = 0; n < 2; ++n) _Pragma("unroll") for (int k = 0; k < 2; ++k) dst[n][k] = *(const PG8_LAS bf16x8*)(lds + PG8_SB(b, h) + boff + n * 2048 + k * 1024); } while (0)
; #define PG8_MMA(ai, bj, At, Bt) do { __builtin_amdgcn_s_setprio(1); _Pragma("unroll") for (int m = 0; m < 4; ++m) _Pragma("unroll") for (int n = 0; n < 2; ++n) _Pragma("unroll") for (int k = 0; k < 2; ++k) \
;         acc[ai][bj][m][n] = __builtin_amdgcn_mfma_f32_16x16x32_bf16(Bt[n][k], At[m][k], acc[ai][bj][m][n], 0, 0, 0); __builtin_amdgcn_s_setprio(0); } while (0)
; #define PG8_WAIT_V(n) asm volatile("s_waitcnt vmcnt(" #n ")" ::: "memory")
; #define PG8_WAIT_L(n) asm volatile("s_waitcnt lgkmcnt(" #n ")" ::: "memory")
; #define PG8_BAR __builtin_amdgcn_s_barrier()
; #define PG8_SCHED __builtin_amdgcn_sched_barrier(0)
; template <class Epi, class Sched, bool ALIGN_EPI = false, bool SP2 = false, bool ABLK = false>
; __device__ __forceinline__ void gemm_phase(PG8_LAS unsigned char* lds, const Gemm g, const Sched& S, const Epi& E) {
;     ...
;             PG8_WAIT_V(8); PG8_WAIT_L(0); PG8_BAR; PG8_MMA(1, 0, At, B0); PG8_MMA(1, 1, At, B1); PG8_BAR; PG8_SCHED;
;             PG8_LDB(B0, 1, 0); PG8_LDB(B1, 1, 1); PG8_SCHED; PG8_LDA(At, 1, 0); PG8_STAGE(PG8_SA(0, 1), a2 + hstep, voffA);
;             PG8_WAIT_V(8); PG8_WAIT_L(0); PG8_BAR; PG8_MMA(0, 0, At, B0); PG8_MMA(0, 1, At, B1); PG8_BAR; PG8_SCHED;
	s_setprio 1
	s_waitcnt lgkmcnt(0)
	v_mfma_f32_16x16x32_bf16 v[62:65], v[144:147], v[212:215], v[62:65]
	v_mfma_f32_16x16x32_bf16 v[62:65], v[184:187], v[216:219], v[62:65]
	v_mfma_f32_16x16x32_bf16 v[58:61], v[192:195], v[216:219], v[58:61]
	v_mfma_f32_16x16x32_bf16 v[58:61], v[188:191], v[212:215], v[58:61]
	v_mfma_f32_16x16x32_bf16 v[42:45], v[188:191], v[220:223], v[42:45]
	v_mfma_f32_16x16x32_bf16 v[42:45], v[192:195], v[224:227], v[42:45]
	v_mfma_f32_16x16x32_bf16 v[46:49], v[184:187], v[224:227], v[46:49]
	v_mfma_f32_16x16x32_bf16 v[46:49], v[144:147], v[220:223], v[46:49]
	v_mfma_f32_16x16x32_bf16 v[30:33], v[144:147], v[228:231], v[30:33]
	v_mfma_f32_16x16x32_bf16 v[30:33], v[184:187], v[232:235], v[30:33]
	v_mfma_f32_16x16x32_bf16 v[26:29], v[192:195], v[232:235], v[26:29]
	v_mfma_f32_16x16x32_bf16 v[26:29], v[188:191], v[228:231], v[26:29]
	v_mfma_f32_16x16x32_bf16 v[10:13], v[188:191], v[236:239], v[10:13]
	v_mfma_f32_16x16x32_bf16 v[10:13], v[192:195], v[240:243], v[10:13]
	v_mfma_f32_16x16x32_bf16 v[14:17], v[184:187], v[240:243], v[14:17]
	v_mfma_f32_16x16x32_bf16 v[14:17], v[144:147], v[236:239], v[14:17]
	v_mfma_f32_16x16x32_bf16 v[54:57], v[196:199], v[212:215], v[54:57]
	v_mfma_f32_16x16x32_bf16 v[54:57], v[200:203], v[216:219], v[54:57]
	v_mfma_f32_16x16x32_bf16 v[50:53], v[208:211], v[216:219], v[50:53]
	v_mfma_f32_16x16x32_bf16 v[50:53], v[204:207], v[212:215], v[50:53]
	v_mfma_f32_16x16x32_bf16 v[34:37], v[204:207], v[220:223], v[34:37]
	v_mfma_f32_16x16x32_bf16 v[34:37], v[208:211], v[224:227], v[34:37]
	v_mfma_f32_16x16x32_bf16 v[38:41], v[200:203], v[224:227], v[38:41]
	v_mfma_f32_16x16x32_bf16 v[38:41], v[196:199], v[220:223], v[38:41]
	v_mfma_f32_16x16x32_bf16 v[22:25], v[196:199], v[228:231], v[22:25]
	v_mfma_f32_16x16x32_bf16 v[22:25], v[200:203], v[232:235], v[22:25]
	v_mfma_f32_16x16x32_bf16 v[18:21], v[208:211], v[232:235], v[18:21]
	v_mfma_f32_16x16x32_bf16 v[18:21], v[204:207], v[228:231], v[18:21]
	s_barrier
	s_setprio 2
	v_mfma_f32_16x16x32_bf16 v[2:5], v[204:207], v[236:239], v[2:5]
	v_mfma_f32_16x16x32_bf16 v[2:5], v[208:211], v[240:243], v[2:5]
	v_mfma_f32_16x16x32_bf16 v[6:9], v[200:203], v[240:243], v[6:9]
	v_mfma_f32_16x16x32_bf16 v[6:9], v[196:199], v[236:239], v[6:9]
	s_setprio 0
	s_add_i32 s14, 0, 0x18000
	v_add_u32_e32 v133, s14, v148
	s_add_i32 s15, 0, 0x1c000
	ds_read_b128 v[144:147], v133
	ds_read_b128 v[184:187], v133 offset:1024
	ds_read_b128 v[188:191], v133 offset:2048
	ds_read_b128 v[192:195], v133 offset:3072
	v_add_u32_e32 v133, s15, v148
	ds_read_b128 v[196:199], v133
	ds_read_b128 v[200:203], v133 offset:1024
	ds_read_b128 v[204:207], v133 offset:2048
	ds_read_b128 v[208:211], v133 offset:3072
	s_mov_b32 m0, s57
	v_lshl_add_u64 v[246:247], v[244:245], 0, s[24:25]
	ds_read_b128 v[212:215], v168 offset:32768
	ds_read_b128 v[216:219], v168 offset:33792
	ds_read_b128 v[220:223], v168 offset:34816
	ds_read_b128 v[224:227], v168 offset:35840
	ds_read_b128 v[228:231], v168 offset:36864
	ds_read_b128 v[232:235], v168 offset:37888
	ds_read_b128 v[236:239], v168 offset:38912
	ds_read_b128 v[240:243], v168 offset:39936
	global_load_lds_dwordx4 v[246:247], off
	v_lshl_add_u64 v[246:247], v[244:245], 0, s[26:27]
	s_mov_b32 m0, s58
	s_nop 0
	global_load_lds_dwordx4 v[246:247], off
	s_waitcnt vmcnt(8)
	s_waitcnt lgkmcnt(0)
	s_barrier
	s_setprio 1
	s_waitcnt lgkmcnt(0)
	v_mfma_f32_16x16x32_bf16 v[126:129], v[144:147], v[212:215], v[126:129]
	v_mfma_f32_16x16x32_bf16 v[126:129], v[184:187], v[216:219], v[126:129]
	v_mfma_f32_16x16x32_bf16 v[122:125], v[192:195], v[216:219], v[122:125]
	v_mfma_f32_16x16x32_bf16 v[122:125], v[188:191], v[212:215], v[122:125]
	v_mfma_f32_16x16x32_bf16 v[106:109], v[188:191], v[220:223], v[106:109]
	v_mfma_f32_16x16x32_bf16 v[106:109], v[192:195], v[224:227], v[106:109]
	v_mfma_f32_16x16x32_bf16 v[110:113], v[184:187], v[224:227], v[110:113]
	v_mfma_f32_16x16x32_bf16 v[110:113], v[144:147], v[220:223], v[110:113]
	v_mfma_f32_16x16x32_bf16 v[94:97], v[144:147], v[228:231], v[94:97]
	v_mfma_f32_16x16x32_bf16 v[94:97], v[184:187], v[232:235], v[94:97]
	v_mfma_f32_16x16x32_bf16 v[90:93], v[192:195], v[232:235], v[90:93]
	v_mfma_f32_16x16x32_bf16 v[90:93], v[188:191], v[228:231], v[90:93]
	v_mfma_f32_16x16x32_bf16 v[74:77], v[188:191], v[236:239], v[74:77]
	v_mfma_f32_16x16x32_bf16 v[74:77], v[192:195], v[240:243], v[74:77]
	v_mfma_f32_16x16x32_bf16 v[78:81], v[184:187], v[240:243], v[78:81]
	v_mfma_f32_16x16x32_bf16 v[78:81], v[144:147], v[236:239], v[78:81]
	v_mfma_f32_16x16x32_bf16 v[118:121], v[196:199], v[212:215], v[118:121]
	v_mfma_f32_16x16x32_bf16 v[118:121], v[200:203], v[216:219], v[118:121]
	v_mfma_f32_16x16x32_bf16 v[114:117], v[208:211], v[216:219], v[114:117]
	v_mfma_f32_16x16x32_bf16 v[114:117], v[204:207], v[212:215], v[114:117]
	v_mfma_f32_16x16x32_bf16 v[98:101], v[204:207], v[220:223], v[98:101]
	v_mfma_f32_16x16x32_bf16 v[98:101], v[208:211], v[224:227], v[98:101]
	v_mfma_f32_16x16x32_bf16 v[102:105], v[200:203], v[224:227], v[102:105]
	v_mfma_f32_16x16x32_bf16 v[102:105], v[196:199], v[220:223], v[102:105]
	v_mfma_f32_16x16x32_bf16 v[86:89], v[196:199], v[228:231], v[86:89]
	v_mfma_f32_16x16x32_bf16 v[86:89], v[200:203], v[232:235], v[86:89]
	v_mfma_f32_16x16x32_bf16 v[82:85], v[208:211], v[232:235], v[82:85]
	v_mfma_f32_16x16x32_bf16 v[82:85], v[204:207], v[228:231], v[82:85]
	s_barrier
; #define PG8_STAGE(bufoff, gbase, voff) do { if constexpr (!pg8_noload<Epi>::value) { _Pragma("unroll") for (int _i = 0; _i < 2; ++_i) \
;         __builtin_amdgcn_global_load_lds((const unsigned*)((const char*)(gbase) + (size_t)_i * pstep + (voff)[0]), (PG8_LAS unsigned*)(lds + (bufoff) + ldsw + _i * 8192), 16, 0, 0); } } while (0)
; #define PG8_LDA(dst, b, h) do { _Pragma("unroll") for (int m = 0; m < 4; ++m) _Pragma("unroll") for (int k = 0; k < 2; ++k) dst[m][k] = *(const PG8_LAS bf16x8*)(lds + PG8_SA(b, h) + aoff + m * 2048 + k * 1024); } while (0)
; #define PG8_MMA(ai, bj, At, Bt) do { __builtin_amdgcn_s_setprio(1); _Pragma("unroll") for (int m = 0; m < 4; ++m) _Pragma("unroll") for (int n = 0; n < 2; ++n) _Pragma("unroll") for (int k = 0; k < 2; ++k) \
;         acc[ai][bj][m][n] = __builtin_amdgcn_mfma_f32_16x16x32_bf16(Bt[n][k], At[m][k], acc[ai][bj][m][n], 0, 0, 0); __builtin_amdgcn_s_setprio(0); } while (0)
; #define PG8_WAIT_V(n) asm volatile("s_waitcnt vmcnt(" #n ")" ::: "memory")
; #define PG8_WAIT_L(n) asm volatile("s_waitcnt lgkmcnt(" #n ")" ::: "memory")
; #define PG8_BAR __builtin_amdgcn_s_barrier()
; #define PG8_SCHED __builtin_amdgcn_sched_barrier(0)
; template <class Epi, class Sched, bool ALIGN_EPI = false, bool SP2 = false, bool ABLK = false>
; __device__ __forceinline__ void gemm_phase(PG8_LAS unsigned char* lds, const Gemm g, const Sched& S, const Epi& E) {
;     ...
;             PG8_WAIT_V(8); PG8_WAIT_L(0); PG8_BAR; PG8_MMA(0, 0, At, B0); PG8_MMA(0, 1, At, B1); PG8_BAR; PG8_SCHED;
;             PG8_LDA(At, 1, 1); PG8_STAGE(PG8_SB(1, 0), b3, voffB); PG8_STAGE(PG8_SB(1, 1), b3 + hstep, voffB); PG8_STAGE(PG8_SA(1, 0), a3, voffA);
;             PG8_WAIT_V(8); PG8_WAIT_L(0); PG8_BAR; PG8_MMA(1, 0, At, B0); PG8_MMA(1, 1, At, B1); PG8_BAR; PG8_SCHED;
	s_setprio 2
	v_mfma_f32_16x16x32_bf16 v[66:69], v[204:207], v[236:239], v[66:69]
	v_mfma_f32_16x16x32_bf16 v[66:69], v[208:211], v[240:243], v[66:69]
	v_mfma_f32_16x16x32_bf16 v[70:73], v[200:203], v[240:243], v[70:73]
	v_mfma_f32_16x16x32_bf16 v[70:73], v[196:199], v[236:239], v[70:73]
	s_setprio 0
	s_add_i32 s14, s14, s3
	v_lshl_add_u64 v[246:247], v[180:181], 0, s[38:39]
	s_mov_b32 m0, s14
	ds_read_b128 v[212:215], v168 offset:49152
	ds_read_b128 v[216:219], v168 offset:50176
	ds_read_b128 v[220:223], v168 offset:51200
	ds_read_b128 v[224:227], v168 offset:52224
	ds_read_b128 v[228:231], v168 offset:53248
	ds_read_b128 v[232:235], v168 offset:54272
	ds_read_b128 v[236:239], v168 offset:55296
	ds_read_b128 v[240:243], v168 offset:56320
	global_load_lds_dwordx4 v[246:247], off
	v_lshl_add_u64 v[246:247], v[180:181], 0, s[40:41]
	s_add_i32 m0, s14, 0x2000
	s_add_i32 s14, s15, s3
	global_load_lds_dwordx4 v[246:247], off
	v_lshl_add_u64 v[246:247], v[180:181], 0, s[42:43]
	s_mov_b32 m0, s14
	v_lshl_add_u64 v[180:181], v[180:181], 0, s[44:45]
	global_load_lds_dwordx4 v[246:247], off
	s_add_i32 m0, s14, 0x2000
	s_nop 0
	global_load_lds_dwordx4 v[180:181], off
	v_lshl_add_u64 v[180:181], v[244:245], 0, s[38:39]
	s_mov_b32 m0, s61
	s_nop 0
	global_load_lds_dwordx4 v[180:181], off
	v_lshl_add_u64 v[180:181], v[244:245], 0, s[40:41]
	s_mov_b32 m0, s63
	s_nop 0
	global_load_lds_dwordx4 v[180:181], off
	s_waitcnt vmcnt(8)
	s_waitcnt lgkmcnt(0)
	s_barrier
	s_setprio 1
	s_waitcnt lgkmcnt(0)
	v_mfma_f32_16x16x32_bf16 v[62:65], v[144:147], v[212:215], v[62:65]
	v_mfma_f32_16x16x32_bf16 v[62:65], v[184:187], v[216:219], v[62:65]
	v_mfma_f32_16x16x32_bf16 v[58:61], v[192:195], v[216:219], v[58:61]
	v_mfma_f32_16x16x32_bf16 v[58:61], v[188:191], v[212:215], v[58:61]
	v_mfma_f32_16x16x32_bf16 v[42:45], v[188:191], v[220:223], v[42:45]
	v_mfma_f32_16x16x32_bf16 v[42:45], v[192:195], v[224:227], v[42:45]
	v_mfma_f32_16x16x32_bf16 v[46:49], v[184:187], v[224:227], v[46:49]
	v_mfma_f32_16x16x32_bf16 v[46:49], v[144:147], v[220:223], v[46:49]
	v_mfma_f32_16x16x32_bf16 v[30:33], v[144:147], v[228:231], v[30:33]
	v_mfma_f32_16x16x32_bf16 v[30:33], v[184:187], v[232:235], v[30:33]
	v_mfma_f32_16x16x32_bf16 v[26:29], v[192:195], v[232:235], v[26:29]
	v_mfma_f32_16x16x32_bf16 v[26:29], v[188:191], v[228:231], v[26:29]
	v_mfma_f32_16x16x32_bf16 v[10:13], v[188:191], v[236:239], v[10:13]
	v_mfma_f32_16x16x32_bf16 v[10:13], v[192:195], v[240:243], v[10:13]
	v_mfma_f32_16x16x32_bf16 v[14:17], v[184:187], v[240:243], v[14:17]
	v_mfma_f32_16x16x32_bf16 v[14:17], v[144:147], v[236:239], v[14:17]
	v_mfma_f32_16x16x32_bf16 v[54:57], v[196:199], v[212:215], v[54:57]
	v_mfma_f32_16x16x32_bf16 v[54:57], v[200:203], v[216:219], v[54:57]
	v_mfma_f32_16x16x32_bf16 v[50:53], v[208:211], v[216:219], v[50:53]
	v_mfma_f32_16x16x32_bf16 v[50:53], v[204:207], v[212:215], v[50:53]
	v_mfma_f32_16x16x32_bf16 v[34:37], v[204:207], v[220:223], v[34:37]
	v_mfma_f32_16x16x32_bf16 v[34:37], v[208:211], v[224:227], v[34:37]
	v_mfma_f32_16x16x32_bf16 v[38:41], v[200:203], v[224:227], v[38:41]
	v_mfma_f32_16x16x32_bf16 v[38:41], v[196:199], v[220:223], v[38:41]
	v_mfma_f32_16x16x32_bf16 v[22:25], v[196:199], v[228:231], v[22:25]
	v_mfma_f32_16x16x32_bf16 v[22:25], v[200:203], v[232:235], v[22:25]
	v_mfma_f32_16x16x32_bf16 v[18:21], v[208:211], v[232:235], v[18:21]
	v_mfma_f32_16x16x32_bf16 v[18:21], v[204:207], v[228:231], v[18:21]
	s_barrier
	s_setprio 2
	v_mfma_f32_16x16x32_bf16 v[2:5], v[204:207], v[236:239], v[2:5]
	v_mfma_f32_16x16x32_bf16 v[2:5], v[208:211], v[240:243], v[2:5]
	v_mfma_f32_16x16x32_bf16 v[6:9], v[200:203], v[240:243], v[6:9]
	v_mfma_f32_16x16x32_bf16 v[6:9], v[196:199], v[236:239], v[6:9]
	s_setprio 0
	s_cmp_gt_u32 s59, 29
	s_mov_b32 s59, s30
	s_cbranch_scc1 .LBB0_2131

; #define PG8_STAGE(bufoff, gbase, voff) do { if constexpr (!pg8_noload<Epi>::value) { _Pragma("unroll") for (int _i = 0; _i < 2; ++_i) \
;         __builtin_amdgcn_global_load_lds((const unsigned*)((const char*)(gbase) + (size_t)_i * pstep + (voff)[0]), (PG8_LAS unsigned*)(lds + (bufoff) + ldsw + _i * 8192), 16, 0, 0); } } while (0)
; #define PG8_LDA(dst, b, h) do { _Pragma("unroll") for (int m = 0; m < 4; ++m) _Pragma("unroll") for (int k = 0; k < 2; ++k) dst[m][k] = *(const PG8_LAS bf16x8*)(lds + PG8_SA(b, h) + aoff + m * 2048 + k * 1024); } while (0)
; #define PG8_LDB(dst, b, h) do { _Pragma("unroll") for (int n = 0; n < 2; ++n) _Pragma("unroll") for (int k = 0; k < 2; ++k) dst[n][k] = *(const PG8_LAS bf16x8*)(lds + PG8_SB(b, h) + boff + n * 2048 + k * 1024); } while (0)
; #define PG8_MMA(ai, bj, At, Bt) do { __builtin_amdgcn_s_setprio(1); _Pragma("unroll") for (int m = 0; m < 4; ++m) _Pragma("unroll") for (int n = 0; n < 2; ++n) _Pragma("unroll") for (int k = 0; k < 2; ++k) \
;         acc[ai][bj][m][n] = __builtin_amdgcn_mfma_f32_16x16x32_bf16(Bt[n][k], At[m][k], acc[ai][bj][m][n], 0, 0, 0); __builtin_amdgcn_s_setprio(0); } while (0)
; #define PG8_WAIT_V(n) asm volatile("s_waitcnt vmcnt(" #n ")" ::: "memory")
; #define PG8_WAIT_L(n) asm volatile("s_waitcnt lgkmcnt(" #n ")" ::: "memory")
; #define PG8_BAR __builtin_amdgcn_s_barrier()
; template <class Epi, class Sched, bool ALIGN_EPI = false, bool SP2 = false, bool ABLK = false>
; __device__ __forceinline__ void gemm_phase(PG8_LAS unsigned char* lds, const Gemm g, const Sched& S, const Epi& E) {
;     ...
;             const bool last = (t == nt - 2);
;             const char* a1 = cA + (size_t)(t + 1) * kstep;
;             const char* a2 = last ? nA : cA + (size_t)(t + 2) * kstep; const char* b2 = last ? nB : cB + (size_t)(t + 2) * kstepB;
;             const char* a3 = a2 + kstep; const char* b3 = b2 + kstepB;
;             if (last && has_next) S.a_ready(nxt);
;             if constexpr (SP2) {
;             PG8_LDB(B0, 0, 0); PG8_LDB(B1, 0, 1); PG8_SCHED; PG8_LDA(At, 0, 0); PG8_STAGE(PG8_SA(1, 1), a1 + hstep, voffA);
;             PG8_WAIT_V(8); PG8_WAIT_L(0); PG8_BAR; PG8_MMA(0, 0, At, B0); PG8_MMA(0, 1, At, B1); PG8_BAR; PG8_SCHED;
;             PG8_LDA(At, 0, 1); PG8_STAGE(PG8_SB(0, 0), b2, voffB); PG8_STAGE(PG8_SB(0, 1), b2 + hstep, voffB); PG8_STAGE(PG8_SA(0, 0), a2, voffA);
.LBB0_2399:
	ds_read_b128 v[130:133], v175
	ds_read_b128 v[134:137], v175 offset:1024
	ds_read_b128 v[138:141], v175 offset:2048
	ds_read_b128 v[142:145], v175 offset:3072
	ds_read_b128 v[146:149], v176
	ds_read_b128 v[150:153], v176 offset:1024
	ds_read_b128 v[154:157], v176 offset:2048
	ds_read_b128 v[158:161], v176 offset:3072
	s_add_i32 s55, s53, 2
	s_add_u32 s64, s62, 0xfff00800
	s_addc_u32 s65, s63, -1
	s_cmp_eq_u32 s3, s53
	s_cselect_b32 s65, s57, s65
	s_cselect_b32 s64, s56, s64
	s_cselect_b32 s91, s59, s49
	s_cselect_b32 s90, s58, s11
	v_lshl_add_u64 v[170:171], s[62:63], 0, v[166:167]
	s_add_i32 m0, s61, 0xc000
	ds_read_b128 v[184:187], v177
	ds_read_b128 v[188:191], v177 offset:1024
	ds_read_b128 v[192:195], v177 offset:2048
	ds_read_b128 v[196:199], v177 offset:3072
	ds_read_b128 v[200:203], v177 offset:4096
	ds_read_b128 v[204:207], v177 offset:5120
	ds_read_b128 v[208:211], v177 offset:6144
	ds_read_b128 v[212:215], v177 offset:7168
	global_load_lds_dwordx4 v[170:171], off
	v_lshl_add_u64 v[170:171], v[170:171], 0, s[12:13]
	s_add_i32 m0, s61, 0xe000
	s_nop 0
	global_load_lds_dwordx4 v[170:171], off
	s_waitcnt vmcnt(8)
	s_waitcnt lgkmcnt(0)
	s_barrier
	s_setprio 1
	s_waitcnt lgkmcnt(0)
	v_mfma_f32_16x16x32_bf16 v[126:129], v[130:133], v[184:187], v[126:129]
	v_mfma_f32_16x16x32_bf16 v[126:129], v[134:137], v[188:191], v[126:129]
	v_mfma_f32_16x16x32_bf16 v[122:125], v[142:145], v[188:191], v[122:125]
	v_mfma_f32_16x16x32_bf16 v[122:125], v[138:141], v[184:187], v[122:125]
	v_mfma_f32_16x16x32_bf16 v[106:109], v[138:141], v[192:195], v[106:109]
	v_mfma_f32_16x16x32_bf16 v[106:109], v[142:145], v[196:199], v[106:109]
	v_mfma_f32_16x16x32_bf16 v[110:113], v[134:137], v[196:199], v[110:113]
	v_mfma_f32_16x16x32_bf16 v[110:113], v[130:133], v[192:195], v[110:113]
	v_mfma_f32_16x16x32_bf16 v[94:97], v[130:133], v[200:203], v[94:97]
	v_mfma_f32_16x16x32_bf16 v[94:97], v[134:137], v[204:207], v[94:97]
	v_mfma_f32_16x16x32_bf16 v[90:93], v[142:145], v[204:207], v[90:93]
	v_mfma_f32_16x16x32_bf16 v[90:93], v[138:141], v[200:203], v[90:93]
	v_mfma_f32_16x16x32_bf16 v[74:77], v[138:141], v[208:211], v[74:77]
	v_mfma_f32_16x16x32_bf16 v[74:77], v[142:145], v[212:215], v[74:77]
	v_mfma_f32_16x16x32_bf16 v[78:81], v[134:137], v[212:215], v[78:81]
	v_mfma_f32_16x16x32_bf16 v[78:81], v[130:133], v[208:211], v[78:81]
	v_mfma_f32_16x16x32_bf16 v[118:121], v[146:149], v[184:187], v[118:121]
	v_mfma_f32_16x16x32_bf16 v[118:121], v[150:153], v[188:191], v[118:121]
	v_mfma_f32_16x16x32_bf16 v[114:117], v[158:161], v[188:191], v[114:117]
	v_mfma_f32_16x16x32_bf16 v[114:117], v[154:157], v[184:187], v[114:117]
	v_mfma_f32_16x16x32_bf16 v[98:101], v[154:157], v[192:195], v[98:101]
	v_mfma_f32_16x16x32_bf16 v[98:101], v[158:161], v[196:199], v[98:101]
	v_mfma_f32_16x16x32_bf16 v[102:105], v[150:153], v[196:199], v[102:105]
	v_mfma_f32_16x16x32_bf16 v[102:105], v[146:149], v[192:195], v[102:105]
	v_mfma_f32_16x16x32_bf16 v[86:89], v[146:149], v[200:203], v[86:89]
	v_mfma_f32_16x16x32_bf16 v[86:89], v[150:153], v[204:207], v[86:89]
	v_mfma_f32_16x16x32_bf16 v[82:85], v[158:161], v[204:207], v[82:85]
	v_mfma_f32_16x16x32_bf16 v[82:85], v[154:157], v[200:203], v[82:85]
	s_barrier
	s_setprio 2
	v_mfma_f32_16x16x32_bf16 v[66:69], v[154:157], v[208:211], v[66:69]
	v_mfma_f32_16x16x32_bf16 v[66:69], v[158:161], v[212:215], v[66:69]
	v_mfma_f32_16x16x32_bf16 v[70:73], v[150:153], v[212:215], v[70:73]
	v_mfma_f32_16x16x32_bf16 v[70:73], v[146:149], v[208:211], v[70:73]
	s_setprio 0
	s_add_i32 s53, s80, s69
	v_lshl_add_u64 v[170:171], s[90:91], 0, v[162:163]
	s_mov_b32 m0, s53
	ds_read_b128 v[184:187], v177 offset:16384
	ds_read_b128 v[188:191], v177 offset:17408
	ds_read_b128 v[192:195], v177 offset:18432
	ds_read_b128 v[196:199], v177 offset:19456
	ds_read_b128 v[200:203], v177 offset:20480
	ds_read_b128 v[204:207], v177 offset:21504
	ds_read_b128 v[208:211], v177 offset:22528
	ds_read_b128 v[212:215], v177 offset:23552
	global_load_lds_dwordx4 v[170:171], off
	v_lshl_add_u64 v[216:217], v[170:171], 0, s[12:13]
	s_add_i32 m0, s53, 0x2000
	s_add_i32 s53, s81, s69
	global_load_lds_dwordx4 v[216:217], off
	v_lshl_add_u64 v[216:217], v[170:171], 0, s[14:15]
	s_mov_b32 m0, s53
	s_nop 0
	global_load_lds_dwordx4 v[216:217], off
	v_lshl_add_u64 v[216:217], v[170:171], 0, s[16:17]
	s_add_i32 m0, s53, 0x2000
	s_nop 0
	global_load_lds_dwordx4 v[216:217], off
	v_lshl_add_u64 v[216:217], s[64:65], 0, v[162:163]
	s_mov_b32 m0, s61
	v_lshl_add_u64 v[218:219], v[216:217], 0, s[12:13]
	global_load_lds_dwordx4 v[216:217], off
	s_mov_b32 m0, s70
	s_nop 0
	global_load_lds_dwordx4 v[218:219], off
	s_waitcnt vmcnt(8)
	s_waitcnt lgkmcnt(0)
	s_barrier
; #define PG8_STAGE(bufoff, gbase, voff) do { if constexpr (!pg8_noload<Epi>::value) { _Pragma("unroll") for (int _i = 0; _i < 2; ++_i) \
;         __builtin_amdgcn_global_load_lds((const unsigned*)((const char*)(gbase) + (size_t)_i * pstep + (voff)[0]), (PG8_LAS unsigned*)(lds + (bufoff) + ldsw + _i * 8192), 16, 0, 0); } } while (0)
; #define PG8_LDA(dst, b, h) do { _Pragma("unroll") for (int m = 0; m < 4; ++m) _Pragma("unroll") for (int k = 0; k < 2; ++k) dst[m][k] = *(const PG8_LAS bf16x8*)(lds + PG8_SA(b, h) + aoff + m * 2048 + k * 1024); } while (0)
; #define PG8_LDB(dst, b, h) do { _Pragma("unroll") for (int n = 0; n < 2; ++n) _Pragma("unroll") for (int k = 0; k < 2; ++k) dst[n][k] = *(const PG8_LAS bf16x8*)(lds + PG8_SB(b, h) + boff + n * 2048 + k * 1024); } while (0)
; #define PG8_MMA(ai, bj, At, Bt) do { __builtin_amdgcn_s_setprio(1); _Pragma("unroll") for (int m = 0; m < 4; ++m) _Pragma("unroll") for (int n = 0; n < 2; ++n) _Pragma("unroll") for (int k = 0; k < 2; ++k) \
;         acc[ai][bj][m][n] = __builtin_amdgcn_mfma_f32_16x16x32_bf16(Bt[n][k], At[m][k], acc[ai][bj][m][n], 0, 0, 0); __builtin_amdgcn_s_setprio(0); } while (0)
; #define PG8_WAIT_V(n) asm volatile("s_waitcnt vmcnt(" #n ")" ::: "memory")
; #define PG8_WAIT_L(n) asm volatile("s_waitcnt lgkmcnt(" #n ")" ::: "memory")
; #define PG8_BAR __builtin_amdgcn_s_barrier()
; #define PG8_SCHED __builtin_amdgcn_sched_barrier(0)
; template <class Epi, class Sched, bool ALIGN_EPI = false, bool SP2 = false, bool ABLK = false>
; __device__ __forceinline__ void gemm_phase(PG8_LAS unsigned char* lds, const Gemm g, const Sched& S, const Epi& E) {
;     ...
;             PG8_WAIT_V(8); PG8_WAIT_L(0); PG8_BAR; PG8_MMA(1, 0, At, B0); PG8_MMA(1, 1, At, B1); PG8_BAR; PG8_SCHED;
;             PG8_LDB(B0, 1, 0); PG8_LDB(B1, 1, 1); PG8_SCHED; PG8_LDA(At, 1, 0); PG8_STAGE(PG8_SA(0, 1), a2 + hstep, voffA);
;             PG8_WAIT_V(8); PG8_WAIT_L(0); PG8_BAR; PG8_MMA(0, 0, At, B0); PG8_MMA(0, 1, At, B1); PG8_BAR; PG8_SCHED;
	s_setprio 1
	s_waitcnt lgkmcnt(0)
	v_mfma_f32_16x16x32_bf16 v[62:65], v[130:133], v[184:187], v[62:65]
	v_mfma_f32_16x16x32_bf16 v[62:65], v[134:137], v[188:191], v[62:65]
	v_mfma_f32_16x16x32_bf16 v[58:61], v[142:145], v[188:191], v[58:61]
	v_mfma_f32_16x16x32_bf16 v[58:61], v[138:141], v[184:187], v[58:61]
	v_mfma_f32_16x16x32_bf16 v[42:45], v[138:141], v[192:195], v[42:45]
	v_mfma_f32_16x16x32_bf16 v[42:45], v[142:145], v[196:199], v[42:45]
	v_mfma_f32_16x16x32_bf16 v[46:49], v[134:137], v[196:199], v[46:49]
	v_mfma_f32_16x16x32_bf16 v[46:49], v[130:133], v[192:195], v[46:49]
	v_mfma_f32_16x16x32_bf16 v[30:33], v[130:133], v[200:203], v[30:33]
	v_mfma_f32_16x16x32_bf16 v[30:33], v[134:137], v[204:207], v[30:33]
	v_mfma_f32_16x16x32_bf16 v[26:29], v[142:145], v[204:207], v[26:29]
	v_mfma_f32_16x16x32_bf16 v[26:29], v[138:141], v[200:203], v[26:29]
	v_mfma_f32_16x16x32_bf16 v[10:13], v[138:141], v[208:211], v[10:13]
	v_mfma_f32_16x16x32_bf16 v[10:13], v[142:145], v[212:215], v[10:13]
	v_mfma_f32_16x16x32_bf16 v[14:17], v[134:137], v[212:215], v[14:17]
	v_mfma_f32_16x16x32_bf16 v[14:17], v[130:133], v[208:211], v[14:17]
	v_mfma_f32_16x16x32_bf16 v[54:57], v[146:149], v[184:187], v[54:57]
	v_mfma_f32_16x16x32_bf16 v[54:57], v[150:153], v[188:191], v[54:57]
	v_mfma_f32_16x16x32_bf16 v[50:53], v[158:161], v[188:191], v[50:53]
	v_mfma_f32_16x16x32_bf16 v[50:53], v[154:157], v[184:187], v[50:53]
	v_mfma_f32_16x16x32_bf16 v[34:37], v[154:157], v[192:195], v[34:37]
	v_mfma_f32_16x16x32_bf16 v[34:37], v[158:161], v[196:199], v[34:37]
	v_mfma_f32_16x16x32_bf16 v[38:41], v[150:153], v[196:199], v[38:41]
	v_mfma_f32_16x16x32_bf16 v[38:41], v[146:149], v[192:195], v[38:41]
	v_mfma_f32_16x16x32_bf16 v[22:25], v[146:149], v[200:203], v[22:25]
	v_mfma_f32_16x16x32_bf16 v[22:25], v[150:153], v[204:207], v[22:25]
	v_mfma_f32_16x16x32_bf16 v[18:21], v[158:161], v[204:207], v[18:21]
	v_mfma_f32_16x16x32_bf16 v[18:21], v[154:157], v[200:203], v[18:21]
	s_barrier
	s_setprio 2
	v_mfma_f32_16x16x32_bf16 v[2:5], v[154:157], v[208:211], v[2:5]
	v_mfma_f32_16x16x32_bf16 v[2:5], v[158:161], v[212:215], v[2:5]
	v_mfma_f32_16x16x32_bf16 v[6:9], v[150:153], v[212:215], v[6:9]
	v_mfma_f32_16x16x32_bf16 v[6:9], v[146:149], v[208:211], v[6:9]
	s_setprio 0
	s_add_i32 s53, 0, 0x18000
	s_add_i32 s64, 0, 0x1c000
	v_add_u32_e32 v142, s53, v1
	v_add_u32_e32 v158, s64, v1
	ds_read_b128 v[130:133], v142
	ds_read_b128 v[134:137], v142 offset:1024
	ds_read_b128 v[138:141], v142 offset:2048
	ds_read_b128 v[142:145], v142 offset:3072
	ds_read_b128 v[146:149], v158
	ds_read_b128 v[150:153], v158 offset:1024
	ds_read_b128 v[154:157], v158 offset:2048
	ds_read_b128 v[158:161], v158 offset:3072
	s_mov_b32 m0, s71
	v_lshl_add_u64 v[218:219], v[216:217], 0, s[14:15]
	ds_read_b128 v[184:187], v177 offset:32768
	ds_read_b128 v[188:191], v177 offset:33792
	ds_read_b128 v[192:195], v177 offset:34816
	ds_read_b128 v[196:199], v177 offset:35840
	ds_read_b128 v[200:203], v177 offset:36864
	ds_read_b128 v[204:207], v177 offset:37888
	ds_read_b128 v[208:211], v177 offset:38912
	ds_read_b128 v[212:215], v177 offset:39936
	global_load_lds_dwordx4 v[218:219], off
	v_lshl_add_u64 v[218:219], v[216:217], 0, s[16:17]
	s_mov_b32 m0, s72
	s_nop 0
	global_load_lds_dwordx4 v[218:219], off
	s_waitcnt vmcnt(8)
	s_waitcnt lgkmcnt(0)
	s_barrier
	s_setprio 1
	s_waitcnt lgkmcnt(0)
	v_mfma_f32_16x16x32_bf16 v[126:129], v[130:133], v[184:187], v[126:129]
	v_mfma_f32_16x16x32_bf16 v[126:129], v[134:137], v[188:191], v[126:129]
	v_mfma_f32_16x16x32_bf16 v[122:125], v[142:145], v[188:191], v[122:125]
	v_mfma_f32_16x16x32_bf16 v[122:125], v[138:141], v[184:187], v[122:125]
	v_mfma_f32_16x16x32_bf16 v[106:109], v[138:141], v[192:195], v[106:109]
	v_mfma_f32_16x16x32_bf16 v[106:109], v[142:145], v[196:199], v[106:109]
	v_mfma_f32_16x16x32_bf16 v[110:113], v[134:137], v[196:199], v[110:113]
	v_mfma_f32_16x16x32_bf16 v[110:113], v[130:133], v[192:195], v[110:113]
	v_mfma_f32_16x16x32_bf16 v[94:97], v[130:133], v[200:203], v[94:97]
	v_mfma_f32_16x16x32_bf16 v[94:97], v[134:137], v[204:207], v[94:97]
	v_mfma_f32_16x16x32_bf16 v[90:93], v[142:145], v[204:207], v[90:93]
	v_mfma_f32_16x16x32_bf16 v[90:93], v[138:141], v[200:203], v[90:93]
	v_mfma_f32_16x16x32_bf16 v[74:77], v[138:141], v[208:211], v[74:77]
	v_mfma_f32_16x16x32_bf16 v[74:77], v[142:145], v[212:215], v[74:77]
	v_mfma_f32_16x16x32_bf16 v[78:81], v[134:137], v[212:215], v[78:81]
	v_mfma_f32_16x16x32_bf16 v[78:81], v[130:133], v[208:211], v[78:81]
	v_mfma_f32_16x16x32_bf16 v[118:121], v[146:149], v[184:187], v[118:121]
	v_mfma_f32_16x16x32_bf16 v[118:121], v[150:153], v[188:191], v[118:121]
	v_mfma_f32_16x16x32_bf16 v[114:117], v[158:161], v[188:191], v[114:117]
	v_mfma_f32_16x16x32_bf16 v[114:117], v[154:157], v[184:187], v[114:117]
	v_mfma_f32_16x16x32_bf16 v[98:101], v[154:157], v[192:195], v[98:101]
	v_mfma_f32_16x16x32_bf16 v[98:101], v[158:161], v[196:199], v[98:101]
	v_mfma_f32_16x16x32_bf16 v[102:105], v[150:153], v[196:199], v[102:105]
	v_mfma_f32_16x16x32_bf16 v[102:105], v[146:149], v[192:195], v[102:105]
	v_mfma_f32_16x16x32_bf16 v[86:89], v[146:149], v[200:203], v[86:89]
	v_mfma_f32_16x16x32_bf16 v[86:89], v[150:153], v[204:207], v[86:89]
	v_mfma_f32_16x16x32_bf16 v[82:85], v[158:161], v[204:207], v[82:85]
	v_mfma_f32_16x16x32_bf16 v[82:85], v[154:157], v[200:203], v[82:85]
	s_barrier
; #define PG8_STAGE(bufoff, gbase, voff) do { if constexpr (!pg8_noload<Epi>::value) { _Pragma("unroll") for (int _i = 0; _i < 2; ++_i) \
;         __builtin_amdgcn_global_load_lds((const unsigned*)((const char*)(gbase) + (size_t)_i * pstep + (voff)[0]), (PG8_LAS unsigned*)(lds + (bufoff) + ldsw + _i * 8192), 16, 0, 0); } } while (0)
; #define PG8_LDA(dst, b, h) do { _Pragma("unroll") for (int m = 0; m < 4; ++m) _Pragma("unroll") for (int k = 0; k < 2; ++k) dst[m][k] = *(const PG8_LAS bf16x8*)(lds + PG8_SA(b, h) + aoff + m * 2048 + k * 1024); } while (0)
; #define PG8_MMA(ai, bj, At, Bt) do { __builtin_amdgcn_s_setprio(1); _Pragma("unroll") for (int m = 0; m < 4; ++m) _Pragma("unroll") for (int n = 0; n < 2; ++n) _Pragma("unroll") for (int k = 0; k < 2; ++k) \
;         acc[ai][bj][m][n] = __builtin_amdgcn_mfma_f32_16x16x32_bf16(Bt[n][k], At[m][k], acc[ai][bj][m][n], 0, 0, 0); __builtin_amdgcn_s_setprio(0); } while (0)
; #define PG8_WAIT_V(n) asm volatile("s_waitcnt vmcnt(" #n ")" ::: "memory")
; #define PG8_WAIT_L(n) asm volatile("s_waitcnt lgkmcnt(" #n ")" ::: "memory")
; #define PG8_BAR __builtin_amdgcn_s_barrier()
; #define PG8_SCHED __builtin_amdgcn_sched_barrier(0)
; template <class Epi, class Sched, bool ALIGN_EPI = false, bool SP2 = false, bool ABLK = false>
; __device__ __forceinline__ void gemm_phase(PG8_LAS unsigned char* lds, const Gemm g, const Sched& S, const Epi& E) {
;     ...
;             PG8_WAIT_V(8); PG8_WAIT_L(0); PG8_BAR; PG8_MMA(0, 0, At, B0); PG8_MMA(0, 1, At, B1); PG8_BAR; PG8_SCHED;
;             PG8_LDA(At, 1, 1); PG8_STAGE(PG8_SB(1, 0), b3, voffB); PG8_STAGE(PG8_SB(1, 1), b3 + hstep, voffB); PG8_STAGE(PG8_SA(1, 0), a3, voffA);
;             PG8_WAIT_V(8); PG8_WAIT_L(0); PG8_BAR; PG8_MMA(1, 0, At, B0); PG8_MMA(1, 1, At, B1); PG8_BAR; PG8_SCHED;
	s_setprio 2
	v_mfma_f32_16x16x32_bf16 v[66:69], v[154:157], v[208:211], v[66:69]
	v_mfma_f32_16x16x32_bf16 v[66:69], v[158:161], v[212:215], v[66:69]
	v_mfma_f32_16x16x32_bf16 v[70:73], v[150:153], v[212:215], v[70:73]
	v_mfma_f32_16x16x32_bf16 v[70:73], v[146:149], v[208:211], v[70:73]
	s_setprio 0
	s_add_i32 s53, s53, s69
	v_lshl_add_u64 v[218:219], v[170:171], 0, s[24:25]
	s_mov_b32 m0, s53
	ds_read_b128 v[184:187], v177 offset:49152
	ds_read_b128 v[188:191], v177 offset:50176
	ds_read_b128 v[192:195], v177 offset:51200
	ds_read_b128 v[196:199], v177 offset:52224
	ds_read_b128 v[200:203], v177 offset:53248
	ds_read_b128 v[204:207], v177 offset:54272
	ds_read_b128 v[208:211], v177 offset:55296
	ds_read_b128 v[212:215], v177 offset:56320
	global_load_lds_dwordx4 v[218:219], off
	v_lshl_add_u64 v[218:219], v[170:171], 0, s[26:27]
	s_add_i32 m0, s53, 0x2000
	s_add_i32 s53, s64, s69
	global_load_lds_dwordx4 v[218:219], off
	v_lshl_add_u64 v[218:219], v[170:171], 0, s[28:29]
	s_mov_b32 m0, s53
	v_lshl_add_u64 v[170:171], v[170:171], 0, s[30:31]
	global_load_lds_dwordx4 v[218:219], off
	s_add_i32 m0, s53, 0x2000
	s_nop 0
	global_load_lds_dwordx4 v[170:171], off
	v_lshl_add_u64 v[170:171], v[216:217], 0, s[24:25]
	s_mov_b32 m0, s75
	s_nop 0
	global_load_lds_dwordx4 v[170:171], off
	v_lshl_add_u64 v[170:171], v[216:217], 0, s[26:27]
	s_mov_b32 m0, s76
	s_nop 0
	global_load_lds_dwordx4 v[170:171], off
	s_waitcnt vmcnt(8)
	s_waitcnt lgkmcnt(0)
	s_barrier
	s_setprio 1
	s_waitcnt lgkmcnt(0)
	v_mfma_f32_16x16x32_bf16 v[62:65], v[130:133], v[184:187], v[62:65]
	v_mfma_f32_16x16x32_bf16 v[62:65], v[134:137], v[188:191], v[62:65]
	v_mfma_f32_16x16x32_bf16 v[58:61], v[142:145], v[188:191], v[58:61]
	v_mfma_f32_16x16x32_bf16 v[58:61], v[138:141], v[184:187], v[58:61]
	v_mfma_f32_16x16x32_bf16 v[42:45], v[138:141], v[192:195], v[42:45]
	v_mfma_f32_16x16x32_bf16 v[42:45], v[142:145], v[196:199], v[42:45]
	v_mfma_f32_16x16x32_bf16 v[46:49], v[134:137], v[196:199], v[46:49]
	v_mfma_f32_16x16x32_bf16 v[46:49], v[130:133], v[192:195], v[46:49]
	v_mfma_f32_16x16x32_bf16 v[30:33], v[130:133], v[200:203], v[30:33]
	v_mfma_f32_16x16x32_bf16 v[30:33], v[134:137], v[204:207], v[30:33]
	v_mfma_f32_16x16x32_bf16 v[26:29], v[142:145], v[204:207], v[26:29]
	v_mfma_f32_16x16x32_bf16 v[26:29], v[138:141], v[200:203], v[26:29]
	v_mfma_f32_16x16x32_bf16 v[10:13], v[138:141], v[208:211], v[10:13]
	v_mfma_f32_16x16x32_bf16 v[10:13], v[142:145], v[212:215], v[10:13]
	v_mfma_f32_16x16x32_bf16 v[14:17], v[134:137], v[212:215], v[14:17]
	v_mfma_f32_16x16x32_bf16 v[14:17], v[130:133], v[208:211], v[14:17]
	v_mfma_f32_16x16x32_bf16 v[54:57], v[146:149], v[184:187], v[54:57]
	v_mfma_f32_16x16x32_bf16 v[54:57], v[150:153], v[188:191], v[54:57]
	v_mfma_f32_16x16x32_bf16 v[50:53], v[158:161], v[188:191], v[50:53]
	v_mfma_f32_16x16x32_bf16 v[50:53], v[154:157], v[184:187], v[50:53]
	v_mfma_f32_16x16x32_bf16 v[34:37], v[154:157], v[192:195], v[34:37]
	v_mfma_f32_16x16x32_bf16 v[34:37], v[158:161], v[196:199], v[34:37]
	v_mfma_f32_16x16x32_bf16 v[38:41], v[150:153], v[196:199], v[38:41]
	v_mfma_f32_16x16x32_bf16 v[38:41], v[146:149], v[192:195], v[38:41]
	v_mfma_f32_16x16x32_bf16 v[22:25], v[146:149], v[200:203], v[22:25]
	v_mfma_f32_16x16x32_bf16 v[22:25], v[150:153], v[204:207], v[22:25]
	v_mfma_f32_16x16x32_bf16 v[18:21], v[158:161], v[204:207], v[18:21]
	v_mfma_f32_16x16x32_bf16 v[18:21], v[154:157], v[200:203], v[18:21]
	s_barrier
	s_setprio 2
	v_mfma_f32_16x16x32_bf16 v[2:5], v[154:157], v[208:211], v[2:5]
	v_mfma_f32_16x16x32_bf16 v[2:5], v[158:161], v[212:215], v[2:5]
	v_mfma_f32_16x16x32_bf16 v[6:9], v[150:153], v[212:215], v[6:9]
	v_mfma_f32_16x16x32_bf16 v[6:9], v[146:149], v[208:211], v[6:9]
	s_setprio 0
	s_add_u32 s62, s62, 0x1000
	s_addc_u32 s63, s63, 0
	s_add_u32 s11, s11, 0x1000
	s_addc_u32 s49, s49, 0
	s_cmp_ge_i32 s55, s89
	s_mov_b32 s53, s55
	s_cbranch_scc0 .LBB0_2399
	s_and_b64 vcc, exec, s[34:35]
	s_cbranch_vccnz .LBB0_2404
	s_lshl_b32 s11, s2, 8
	s_cmp_gt_i32 s2, 63
	s_mov_b64 s[62:63], -1
	s_cbranch_scc1 .LBB0_2405
